# all 7 GEMM loops: SGPR-base LDS-DMA loads and loop-invariant LDS read base (no per-phase VALU address adds except phase 1)
# speedup vs baseline: 1.0228x; 1.0034x over previous
.LBB0_241:
	v_bfe_u32 v1, v8, 4, 2
	v_and_b32_e32 v144, 15, v8
	v_lshlrev_b32_e32 v9, 4, v1
	v_lshlrev_b32_e32 v8, 2, v8
	s_sext_i32_i16 s46, s8
	v_lshl_or_b32 v9, v144, 6, v9
	s_lshl_b32 s8, s9, 13
	v_and_b32_e32 v8, 32, v8
	v_bitop3_b32 v22, v9, s8, v8 bitop3:0xde
	s_lshl_b32 s8, s12, 5
	v_mov_b32_e32 v133, v0
	s_and_b32 s34, s8, 0x60
	v_lshl_add_u64 v[10:11], s[4:5], 0, v[132:133]
	v_mov_b32_e32 v137, v0
	s_lshl_b32 s8, s34, 7
	v_lshl_add_u64 v[12:13], s[4:5], 0, v[136:137]
	v_mov_b32_e32 v131, v0
	v_bitop3_b32 v145, v9, s8, v8 bitop3:0xde
	s_add_i32 m0, s26, 0x18000
	v_lshl_add_u64 v[8:9], v[10:11], 0, s[6:7]
	v_lshl_add_u64 v[14:15], s[0:1], 0, v[130:131]
	v_mov_b32_e32 v135, v0
	s_waitcnt vmcnt(4)
	s_barrier
	global_load_lds_dwordx4 v[8:9], off
	v_lshl_add_u64 v[8:9], v[12:13], 0, s[6:7]
	s_add_i32 m0, s26, 0x1a000
	s_add_i32 s35, s26, 0x8000
	v_lshl_add_u64 v[16:17], s[0:1], 0, v[134:135]
	global_load_lds_dwordx4 v[8:9], off
	v_lshl_add_u64 v[8:9], v[14:15], 0, s[6:7]
	s_mov_b32 m0, s35
	s_add_i32 s40, s26, 0xa000
	v_lshl_add_u64 v[18:19], s[10:11], 0, v[132:133]
	global_load_lds_dwordx4 v[8:9], off
	v_lshl_add_u64 v[8:9], v[16:17], 0, s[6:7]
	s_mov_b32 m0, s40
	v_lshl_add_u64 v[20:21], s[10:11], 0, v[136:137]
	global_load_lds_dwordx4 v[8:9], off
	s_add_i32 m0, s26, 0x1c000
	v_lshl_add_u64 v[8:9], v[18:19], 0, s[6:7]
	global_load_lds_dwordx4 v[8:9], off
	v_lshl_add_u64 v[8:9], v[20:21], 0, s[6:7]
	s_add_i32 m0, s26, 0x1e000
	v_add_u32_e32 v2, v4, v2
	global_load_lds_dwordx4 v[8:9], off
	v_add_lshl_u32 v2, v2, v3, 1
	v_mov_b32_e32 v3, v0
	s_waitcnt vmcnt(6)
	v_lshl_add_u64 v[138:139], s[92:93], 0, v[2:3]
	v_add_u32_e32 v2, v7, v5
	s_lshr_b32 s30, s64, 6
	v_add_lshl_u32 v2, v2, v6, 1
	s_lshl_b32 s31, s9, 6
	s_add_i32 s41, s30, -2
	s_mov_b32 s39, s93
	v_lshl_add_u64 v[140:141], s[92:93], 0, v[2:3]
	s_mov_b32 s42, 0
	v_add_u32_e32 v146, 0, v22
	s_barrier
	v_add_u32_e32 v248, 0x10000, v145

.LBB0_252:
	s_add_u32 s0, s0, 0x80
	s_addc_u32 s1, s1, 0
	s_add_u32 s47, s4, 0x100
	s_addc_u32 s48, s5, 0
	s_mov_b32 s4, 0
	s_waitcnt lgkmcnt(0)
	s_waitcnt vmcnt(0)
	s_add_i32 s49, s4, 2
	s_add_u32 s16, s0, 0x80
	s_addc_u32 s5, s1, 0
	s_add_i32 s65, 0, 0x10000
	ds_read_b128 v[148:151], v248
	ds_read_b128 v[152:155], v248 offset:1024
	ds_read_b128 v[156:159], v248 offset:2048
	ds_read_b128 v[160:163], v248 offset:3072
	s_cmp_eq_u32 s41, s4
	s_cselect_b32 s4, s10, s16
	s_cselect_b32 s5, s11, s5
	s_cselect_b32 s17, s13, s48
	s_cselect_b32 s16, s12, s47
	v_lshl_add_u64 v[142:143], s[0:1], 0, v[138:139]
	s_add_i32 m0, s26, 0xc000
	ds_read_b128 v[164:167], v146
	ds_read_b128 v[168:171], v146 offset:1024
	ds_read_b128 v[172:175], v146 offset:2048
	ds_read_b128 v[176:179], v146 offset:3072
	ds_read_b128 v[180:183], v146 offset:4096
	ds_read_b128 v[204:207], v146 offset:5120
	ds_read_b128 v[208:211], v146 offset:6144
	ds_read_b128 v[212:215], v146 offset:7168
	global_load_lds_dwordx4 v[142:143], off
	v_lshl_add_u64 v[142:143], s[0:1], 0, v[140:141]
	s_add_i32 m0, s26, 0xe000
	s_nop 0
	global_load_lds_dwordx4 v[142:143], off
	s_waitcnt lgkmcnt(8)
	s_barrier
	s_waitcnt lgkmcnt(0)
	v_mfma_f32_16x16x32_bf16 v[126:129], v[148:151], v[164:167], 0
	v_mfma_f32_16x16x32_bf16 v[122:125], v[156:159], v[164:167], 0
	v_mfma_f32_16x16x32_bf16 v[110:113], v[148:151], v[172:175], 0
	v_mfma_f32_16x16x32_bf16 v[106:109], v[156:159], v[172:175], 0
	v_mfma_f32_16x16x32_bf16 v[94:97], v[148:151], v[180:183], 0
	v_mfma_f32_16x16x32_bf16 v[90:93], v[156:159], v[180:183], 0
	v_mfma_f32_16x16x32_bf16 v[78:81], v[148:151], v[208:211], 0
	v_mfma_f32_16x16x32_bf16 v[74:77], v[156:159], v[208:211], 0
	v_mfma_f32_16x16x32_bf16 v[126:129], v[152:155], v[168:171], v[126:129]
	v_mfma_f32_16x16x32_bf16 v[122:125], v[160:163], v[168:171], v[122:125]
	v_mfma_f32_16x16x32_bf16 v[110:113], v[152:155], v[176:179], v[110:113]
	v_mfma_f32_16x16x32_bf16 v[106:109], v[160:163], v[176:179], v[106:109]
	v_mfma_f32_16x16x32_bf16 v[94:97], v[152:155], v[204:207], v[94:97]
	v_mfma_f32_16x16x32_bf16 v[90:93], v[160:163], v[204:207], v[90:93]
	v_mfma_f32_16x16x32_bf16 v[78:81], v[152:155], v[212:215], v[78:81]
	v_mfma_f32_16x16x32_bf16 v[74:77], v[160:163], v[212:215], v[74:77]
	s_barrier
	s_add_i32 s66, 0, 0x14000
	s_add_i32 s65, s65, s24
	ds_read_b128 v[216:219], v248 offset:16384
	ds_read_b128 v[220:223], v248 offset:17408
	ds_read_b128 v[224:227], v248 offset:18432
	ds_read_b128 v[228:231], v248 offset:19456
	s_add_u32 s70, s16, s6
	s_addc_u32 s71, s17, s7
	s_mov_b32 m0, s65
	s_nop 0
	global_load_lds_dwordx4 v132, s[16:17]
	s_add_i32 m0, s65, 0x2000
	s_nop 0
	global_load_lds_dwordx4 v136, s[16:17]
	s_barrier
	s_waitcnt lgkmcnt(0)
	v_mfma_f32_16x16x32_bf16 v[114:117], v[216:219], v[164:167], 0
	v_mfma_f32_16x16x32_bf16 v[118:121], v[224:227], v[164:167], 0
	v_mfma_f32_16x16x32_bf16 v[98:101], v[216:219], v[172:175], 0
	v_mfma_f32_16x16x32_bf16 v[102:105], v[224:227], v[172:175], 0
	v_mfma_f32_16x16x32_bf16 v[82:85], v[216:219], v[180:183], 0
	v_mfma_f32_16x16x32_bf16 v[86:89], v[224:227], v[180:183], 0
	v_mfma_f32_16x16x32_bf16 v[66:69], v[216:219], v[208:211], 0
	v_mfma_f32_16x16x32_bf16 v[70:73], v[224:227], v[208:211], 0
	v_mfma_f32_16x16x32_bf16 v[114:117], v[220:223], v[168:171], v[114:117]
	v_mfma_f32_16x16x32_bf16 v[118:121], v[228:231], v[168:171], v[118:121]
	v_mfma_f32_16x16x32_bf16 v[98:101], v[220:223], v[176:179], v[98:101]
	v_mfma_f32_16x16x32_bf16 v[102:105], v[228:231], v[176:179], v[102:105]
	v_mfma_f32_16x16x32_bf16 v[82:85], v[220:223], v[204:207], v[82:85]
	v_mfma_f32_16x16x32_bf16 v[86:89], v[228:231], v[204:207], v[86:89]
	v_mfma_f32_16x16x32_bf16 v[66:69], v[220:223], v[212:215], v[66:69]
	v_mfma_f32_16x16x32_bf16 v[70:73], v[228:231], v[212:215], v[70:73]
	s_barrier
	s_mov_b32 m0, s26
	s_add_u32 s72, s4, s6
	s_addc_u32 s73, s5, s7
	ds_read_b128 v[164:167], v146 offset:16384
	ds_read_b128 v[168:171], v146 offset:17408
	ds_read_b128 v[172:175], v146 offset:18432
	ds_read_b128 v[176:179], v146 offset:19456
	ds_read_b128 v[180:183], v146 offset:20480
	ds_read_b128 v[204:207], v146 offset:21504
	ds_read_b128 v[208:211], v146 offset:22528
	ds_read_b128 v[212:215], v146 offset:23552
	global_load_lds_dwordx4 v130, s[4:5]
	s_mov_b32 m0, s27
	s_nop 0
	global_load_lds_dwordx4 v134, s[4:5]
	s_barrier
	s_waitcnt lgkmcnt(0)
	v_mfma_f32_16x16x32_bf16 v[62:65], v[148:151], v[164:167], 0
	v_mfma_f32_16x16x32_bf16 v[58:61], v[156:159], v[164:167], 0
	v_mfma_f32_16x16x32_bf16 v[46:49], v[148:151], v[172:175], 0
	v_mfma_f32_16x16x32_bf16 v[42:45], v[156:159], v[172:175], 0
	v_mfma_f32_16x16x32_bf16 v[30:33], v[148:151], v[180:183], 0
	v_mfma_f32_16x16x32_bf16 v[26:29], v[156:159], v[180:183], 0
	v_mfma_f32_16x16x32_bf16 v[14:17], v[148:151], v[208:211], 0
	v_mfma_f32_16x16x32_bf16 v[10:13], v[156:159], v[208:211], 0
	v_mfma_f32_16x16x32_bf16 v[62:65], v[152:155], v[168:171], v[62:65]
	v_mfma_f32_16x16x32_bf16 v[58:61], v[160:163], v[168:171], v[58:61]
	v_mfma_f32_16x16x32_bf16 v[46:49], v[152:155], v[176:179], v[46:49]
	v_mfma_f32_16x16x32_bf16 v[42:45], v[160:163], v[176:179], v[42:45]
	v_mfma_f32_16x16x32_bf16 v[30:33], v[152:155], v[204:207], v[30:33]
	v_mfma_f32_16x16x32_bf16 v[26:29], v[160:163], v[204:207], v[26:29]
	v_mfma_f32_16x16x32_bf16 v[14:17], v[152:155], v[212:215], v[14:17]
	v_mfma_f32_16x16x32_bf16 v[10:13], v[160:163], v[212:215], v[10:13]
	s_barrier
	s_add_u32 s16, s16, s92
	s_addc_u32 s17, s17, 0
	s_add_i32 s65, s66, s24
	s_add_u32 s76, s16, s6
	s_addc_u32 s77, s17, s7
	s_mov_b32 m0, s65
	s_nop 0
	global_load_lds_dwordx4 v132, s[16:17]
	s_add_i32 m0, s65, 0x2000
	s_nop 0
	global_load_lds_dwordx4 v136, s[16:17]
	s_waitcnt vmcnt(6)
	s_barrier
	v_mfma_f32_16x16x32_bf16 v[50:53], v[216:219], v[164:167], 0
	v_mfma_f32_16x16x32_bf16 v[54:57], v[224:227], v[164:167], 0
	v_mfma_f32_16x16x32_bf16 v[34:37], v[216:219], v[172:175], 0
	v_mfma_f32_16x16x32_bf16 v[38:41], v[224:227], v[172:175], 0
	v_mfma_f32_16x16x32_bf16 v[18:21], v[216:219], v[180:183], 0
	v_mfma_f32_16x16x32_bf16 v[22:25], v[224:227], v[180:183], 0
	v_mfma_f32_16x16x32_bf16 v[6:9], v[216:219], v[208:211], 0
	v_mfma_f32_16x16x32_bf16 v[2:5], v[224:227], v[208:211], 0
	v_mfma_f32_16x16x32_bf16 v[50:53], v[220:223], v[168:171], v[50:53]
	v_mfma_f32_16x16x32_bf16 v[54:57], v[228:231], v[168:171], v[54:57]
	v_mfma_f32_16x16x32_bf16 v[34:37], v[220:223], v[176:179], v[34:37]
	v_mfma_f32_16x16x32_bf16 v[38:41], v[228:231], v[176:179], v[38:41]
	v_mfma_f32_16x16x32_bf16 v[18:21], v[220:223], v[204:207], v[18:21]
	v_mfma_f32_16x16x32_bf16 v[22:25], v[228:231], v[204:207], v[22:25]
	v_mfma_f32_16x16x32_bf16 v[6:9], v[220:223], v[212:215], v[6:9]
	v_mfma_f32_16x16x32_bf16 v[2:5], v[228:231], v[212:215], v[2:5]
	s_barrier
	s_add_i32 s16, 0, 0x18000
	ds_read_b128 v[148:151], v248 offset:32768
	ds_read_b128 v[152:155], v248 offset:33792
	ds_read_b128 v[156:159], v248 offset:34816
	ds_read_b128 v[160:163], v248 offset:35840
	s_add_u32 s4, s4, s92
	s_addc_u32 s5, s5, 0
	s_mov_b32 m0, s28
	ds_read_b128 v[164:167], v146 offset:32768
	ds_read_b128 v[168:171], v146 offset:33792
	ds_read_b128 v[172:175], v146 offset:34816
	ds_read_b128 v[176:179], v146 offset:35840
	ds_read_b128 v[180:183], v146 offset:36864
	ds_read_b128 v[204:207], v146 offset:37888
	ds_read_b128 v[208:211], v146 offset:38912
	ds_read_b128 v[212:215], v146 offset:39936
	global_load_lds_dwordx4 v130, s[4:5]
	s_mov_b32 m0, s29
	s_nop 0
	global_load_lds_dwordx4 v134, s[4:5]
	s_waitcnt lgkmcnt(8)
	s_barrier
	s_waitcnt lgkmcnt(0)
	v_mfma_f32_16x16x32_bf16 v[126:129], v[148:151], v[164:167], v[126:129]
	v_mfma_f32_16x16x32_bf16 v[122:125], v[156:159], v[164:167], v[122:125]
	v_mfma_f32_16x16x32_bf16 v[110:113], v[148:151], v[172:175], v[110:113]
	v_mfma_f32_16x16x32_bf16 v[106:109], v[156:159], v[172:175], v[106:109]
	v_mfma_f32_16x16x32_bf16 v[94:97], v[148:151], v[180:183], v[94:97]
	v_mfma_f32_16x16x32_bf16 v[90:93], v[156:159], v[180:183], v[90:93]
	v_mfma_f32_16x16x32_bf16 v[78:81], v[148:151], v[208:211], v[78:81]
	v_mfma_f32_16x16x32_bf16 v[74:77], v[156:159], v[208:211], v[74:77]
	v_mfma_f32_16x16x32_bf16 v[126:129], v[152:155], v[168:171], v[126:129]
	v_mfma_f32_16x16x32_bf16 v[122:125], v[160:163], v[168:171], v[122:125]
	v_mfma_f32_16x16x32_bf16 v[110:113], v[152:155], v[176:179], v[110:113]
	v_mfma_f32_16x16x32_bf16 v[106:109], v[160:163], v[176:179], v[106:109]
	v_mfma_f32_16x16x32_bf16 v[94:97], v[152:155], v[204:207], v[94:97]
	v_mfma_f32_16x16x32_bf16 v[90:93], v[160:163], v[204:207], v[90:93]
	v_mfma_f32_16x16x32_bf16 v[78:81], v[152:155], v[212:215], v[78:81]
	v_mfma_f32_16x16x32_bf16 v[74:77], v[160:163], v[212:215], v[74:77]
	s_barrier
	s_add_i32 s4, 0, 0x1c000
	s_add_i32 s5, s16, s24
	s_mov_b32 m0, s5
	ds_read_b128 v[216:219], v248 offset:49152
	ds_read_b128 v[220:223], v248 offset:50176
	ds_read_b128 v[224:227], v248 offset:51200
	ds_read_b128 v[228:231], v248 offset:52224
	global_load_lds_dwordx4 v132, s[70:71]
	s_add_i32 m0, s5, 0x2000
	s_nop 0
	global_load_lds_dwordx4 v136, s[70:71]
	s_barrier
	s_waitcnt lgkmcnt(0)
	v_mfma_f32_16x16x32_bf16 v[114:117], v[216:219], v[164:167], v[114:117]
	v_mfma_f32_16x16x32_bf16 v[118:121], v[224:227], v[164:167], v[118:121]
	v_mfma_f32_16x16x32_bf16 v[98:101], v[216:219], v[172:175], v[98:101]
	v_mfma_f32_16x16x32_bf16 v[102:105], v[224:227], v[172:175], v[102:105]
	v_mfma_f32_16x16x32_bf16 v[82:85], v[216:219], v[180:183], v[82:85]
	v_mfma_f32_16x16x32_bf16 v[86:89], v[224:227], v[180:183], v[86:89]
	v_mfma_f32_16x16x32_bf16 v[66:69], v[216:219], v[208:211], v[66:69]
	v_mfma_f32_16x16x32_bf16 v[70:73], v[224:227], v[208:211], v[70:73]
	v_mfma_f32_16x16x32_bf16 v[114:117], v[220:223], v[168:171], v[114:117]
	v_mfma_f32_16x16x32_bf16 v[118:121], v[228:231], v[168:171], v[118:121]
	v_mfma_f32_16x16x32_bf16 v[98:101], v[220:223], v[176:179], v[98:101]
	v_mfma_f32_16x16x32_bf16 v[102:105], v[228:231], v[176:179], v[102:105]
	v_mfma_f32_16x16x32_bf16 v[82:85], v[220:223], v[204:207], v[82:85]
	v_mfma_f32_16x16x32_bf16 v[86:89], v[228:231], v[204:207], v[86:89]
	v_mfma_f32_16x16x32_bf16 v[66:69], v[220:223], v[212:215], v[66:69]
	v_mfma_f32_16x16x32_bf16 v[70:73], v[228:231], v[212:215], v[70:73]
	s_barrier
	s_mov_b32 m0, s35
	ds_read_b128 v[164:167], v146 offset:49152
	ds_read_b128 v[168:171], v146 offset:50176
	ds_read_b128 v[172:175], v146 offset:51200
	ds_read_b128 v[176:179], v146 offset:52224
	ds_read_b128 v[180:183], v146 offset:53248
	ds_read_b128 v[204:207], v146 offset:54272
	ds_read_b128 v[208:211], v146 offset:55296
	ds_read_b128 v[212:215], v146 offset:56320
	global_load_lds_dwordx4 v130, s[72:73]
	s_mov_b32 m0, s40
	s_nop 0
	global_load_lds_dwordx4 v134, s[72:73]
	s_barrier
	s_waitcnt lgkmcnt(0)
	v_mfma_f32_16x16x32_bf16 v[62:65], v[148:151], v[164:167], v[62:65]
	v_mfma_f32_16x16x32_bf16 v[58:61], v[156:159], v[164:167], v[58:61]
	v_mfma_f32_16x16x32_bf16 v[46:49], v[148:151], v[172:175], v[46:49]
	v_mfma_f32_16x16x32_bf16 v[42:45], v[156:159], v[172:175], v[42:45]
	v_mfma_f32_16x16x32_bf16 v[30:33], v[148:151], v[180:183], v[30:33]
	v_mfma_f32_16x16x32_bf16 v[26:29], v[156:159], v[180:183], v[26:29]
	v_mfma_f32_16x16x32_bf16 v[14:17], v[148:151], v[208:211], v[14:17]
	v_mfma_f32_16x16x32_bf16 v[10:13], v[156:159], v[208:211], v[10:13]
	v_mfma_f32_16x16x32_bf16 v[62:65], v[152:155], v[168:171], v[62:65]
	v_mfma_f32_16x16x32_bf16 v[58:61], v[160:163], v[168:171], v[58:61]
	v_mfma_f32_16x16x32_bf16 v[46:49], v[152:155], v[176:179], v[46:49]
	v_mfma_f32_16x16x32_bf16 v[42:45], v[160:163], v[176:179], v[42:45]
	v_mfma_f32_16x16x32_bf16 v[30:33], v[152:155], v[204:207], v[30:33]
	v_mfma_f32_16x16x32_bf16 v[26:29], v[160:163], v[204:207], v[26:29]
	v_mfma_f32_16x16x32_bf16 v[14:17], v[152:155], v[212:215], v[14:17]
	v_mfma_f32_16x16x32_bf16 v[10:13], v[160:163], v[212:215], v[10:13]
	s_barrier
	s_add_i32 s4, s4, s24
	s_mov_b32 m0, s4
	s_nop 0
	global_load_lds_dwordx4 v132, s[76:77]
	s_add_i32 m0, s4, 0x2000
	s_nop 0
	global_load_lds_dwordx4 v136, s[76:77]
	s_add_u32 s0, s0, 0x100
	s_addc_u32 s1, s1, 0
	s_add_u32 s47, s47, 0x100
	s_addc_u32 s48, s48, 0
	s_cmp_ge_u32 s49, s30
	s_mov_b32 s4, s49
	s_waitcnt vmcnt(6)
	s_barrier
	v_mfma_f32_16x16x32_bf16 v[50:53], v[216:219], v[164:167], v[50:53]
	v_mfma_f32_16x16x32_bf16 v[54:57], v[224:227], v[164:167], v[54:57]
	v_mfma_f32_16x16x32_bf16 v[34:37], v[216:219], v[172:175], v[34:37]
	v_mfma_f32_16x16x32_bf16 v[38:41], v[224:227], v[172:175], v[38:41]
	v_mfma_f32_16x16x32_bf16 v[18:21], v[216:219], v[180:183], v[18:21]
	v_mfma_f32_16x16x32_bf16 v[22:25], v[224:227], v[180:183], v[22:25]
	v_mfma_f32_16x16x32_bf16 v[6:9], v[216:219], v[208:211], v[6:9]
	v_mfma_f32_16x16x32_bf16 v[2:5], v[224:227], v[208:211], v[2:5]
	v_mfma_f32_16x16x32_bf16 v[50:53], v[220:223], v[168:171], v[50:53]
	v_mfma_f32_16x16x32_bf16 v[54:57], v[228:231], v[168:171], v[54:57]
	v_mfma_f32_16x16x32_bf16 v[34:37], v[220:223], v[176:179], v[34:37]
	v_mfma_f32_16x16x32_bf16 v[38:41], v[228:231], v[176:179], v[38:41]
	v_mfma_f32_16x16x32_bf16 v[18:21], v[220:223], v[204:207], v[18:21]
	v_mfma_f32_16x16x32_bf16 v[22:25], v[228:231], v[204:207], v[22:25]
	v_mfma_f32_16x16x32_bf16 v[6:9], v[220:223], v[212:215], v[6:9]
	v_mfma_f32_16x16x32_bf16 v[2:5], v[228:231], v[212:215], v[2:5]
	s_barrier
	s_cbranch_scc1 .Lkexit_253
.LBB0_253:
	s_add_i32 s49, s4, 2
	s_add_u32 s16, s0, 0x80
	s_addc_u32 s5, s1, 0
	s_add_i32 s65, 0, 0x10000
	ds_read_b128 v[148:151], v248
	ds_read_b128 v[152:155], v248 offset:1024
	ds_read_b128 v[156:159], v248 offset:2048
	ds_read_b128 v[160:163], v248 offset:3072
	s_cmp_eq_u32 s41, s4
	s_cselect_b32 s4, s10, s16
	s_cselect_b32 s5, s11, s5
	s_cselect_b32 s17, s13, s48
	s_cselect_b32 s16, s12, s47
	v_lshl_add_u64 v[142:143], s[0:1], 0, v[138:139]
	s_add_i32 m0, s26, 0xc000
	ds_read_b128 v[164:167], v146
	ds_read_b128 v[168:171], v146 offset:1024
	ds_read_b128 v[172:175], v146 offset:2048
	ds_read_b128 v[176:179], v146 offset:3072
	ds_read_b128 v[180:183], v146 offset:4096
	ds_read_b128 v[204:207], v146 offset:5120
	ds_read_b128 v[208:211], v146 offset:6144
	ds_read_b128 v[212:215], v146 offset:7168
	global_load_lds_dwordx4 v[142:143], off
	v_lshl_add_u64 v[142:143], s[0:1], 0, v[140:141]
	s_add_i32 m0, s26, 0xe000
	s_nop 0
	global_load_lds_dwordx4 v[142:143], off
	s_waitcnt lgkmcnt(8)
	s_barrier
	s_waitcnt lgkmcnt(0)
	v_mfma_f32_16x16x32_bf16 v[126:129], v[148:151], v[164:167], v[126:129]
	v_mfma_f32_16x16x32_bf16 v[122:125], v[156:159], v[164:167], v[122:125]
	v_mfma_f32_16x16x32_bf16 v[110:113], v[148:151], v[172:175], v[110:113]
	v_mfma_f32_16x16x32_bf16 v[106:109], v[156:159], v[172:175], v[106:109]
	v_mfma_f32_16x16x32_bf16 v[94:97], v[148:151], v[180:183], v[94:97]
	v_mfma_f32_16x16x32_bf16 v[90:93], v[156:159], v[180:183], v[90:93]
	v_mfma_f32_16x16x32_bf16 v[78:81], v[148:151], v[208:211], v[78:81]
	v_mfma_f32_16x16x32_bf16 v[74:77], v[156:159], v[208:211], v[74:77]
	v_mfma_f32_16x16x32_bf16 v[126:129], v[152:155], v[168:171], v[126:129]
	v_mfma_f32_16x16x32_bf16 v[122:125], v[160:163], v[168:171], v[122:125]
	v_mfma_f32_16x16x32_bf16 v[110:113], v[152:155], v[176:179], v[110:113]
	v_mfma_f32_16x16x32_bf16 v[106:109], v[160:163], v[176:179], v[106:109]
	v_mfma_f32_16x16x32_bf16 v[94:97], v[152:155], v[204:207], v[94:97]
	v_mfma_f32_16x16x32_bf16 v[90:93], v[160:163], v[204:207], v[90:93]
	v_mfma_f32_16x16x32_bf16 v[78:81], v[152:155], v[212:215], v[78:81]
	v_mfma_f32_16x16x32_bf16 v[74:77], v[160:163], v[212:215], v[74:77]
	s_barrier
	s_add_i32 s66, 0, 0x14000
	s_add_i32 s65, s65, s24
	ds_read_b128 v[216:219], v248 offset:16384
	ds_read_b128 v[220:223], v248 offset:17408
	ds_read_b128 v[224:227], v248 offset:18432
	ds_read_b128 v[228:231], v248 offset:19456
	s_add_u32 s70, s16, s6
	s_addc_u32 s71, s17, s7
	s_mov_b32 m0, s65
	s_nop 0
	global_load_lds_dwordx4 v132, s[16:17]
	s_add_i32 m0, s65, 0x2000
	s_nop 0
	global_load_lds_dwordx4 v136, s[16:17]
	s_barrier
	s_waitcnt lgkmcnt(0)
	v_mfma_f32_16x16x32_bf16 v[114:117], v[216:219], v[164:167], v[114:117]
	v_mfma_f32_16x16x32_bf16 v[118:121], v[224:227], v[164:167], v[118:121]
	v_mfma_f32_16x16x32_bf16 v[98:101], v[216:219], v[172:175], v[98:101]
	v_mfma_f32_16x16x32_bf16 v[102:105], v[224:227], v[172:175], v[102:105]
	v_mfma_f32_16x16x32_bf16 v[82:85], v[216:219], v[180:183], v[82:85]
	v_mfma_f32_16x16x32_bf16 v[86:89], v[224:227], v[180:183], v[86:89]
	v_mfma_f32_16x16x32_bf16 v[66:69], v[216:219], v[208:211], v[66:69]
	v_mfma_f32_16x16x32_bf16 v[70:73], v[224:227], v[208:211], v[70:73]
	v_mfma_f32_16x16x32_bf16 v[114:117], v[220:223], v[168:171], v[114:117]
	v_mfma_f32_16x16x32_bf16 v[118:121], v[228:231], v[168:171], v[118:121]
	v_mfma_f32_16x16x32_bf16 v[98:101], v[220:223], v[176:179], v[98:101]
	v_mfma_f32_16x16x32_bf16 v[102:105], v[228:231], v[176:179], v[102:105]
	v_mfma_f32_16x16x32_bf16 v[82:85], v[220:223], v[204:207], v[82:85]
	v_mfma_f32_16x16x32_bf16 v[86:89], v[228:231], v[204:207], v[86:89]
	v_mfma_f32_16x16x32_bf16 v[66:69], v[220:223], v[212:215], v[66:69]
	v_mfma_f32_16x16x32_bf16 v[70:73], v[228:231], v[212:215], v[70:73]
	s_barrier
	s_mov_b32 m0, s26
	s_add_u32 s72, s4, s6
	s_addc_u32 s73, s5, s7
	ds_read_b128 v[164:167], v146 offset:16384
	ds_read_b128 v[168:171], v146 offset:17408
	ds_read_b128 v[172:175], v146 offset:18432
	ds_read_b128 v[176:179], v146 offset:19456
	ds_read_b128 v[180:183], v146 offset:20480
	ds_read_b128 v[204:207], v146 offset:21504
	ds_read_b128 v[208:211], v146 offset:22528
	ds_read_b128 v[212:215], v146 offset:23552
	global_load_lds_dwordx4 v130, s[4:5]
	s_mov_b32 m0, s27
	s_nop 0
	global_load_lds_dwordx4 v134, s[4:5]
	s_barrier
	s_waitcnt lgkmcnt(0)
	v_mfma_f32_16x16x32_bf16 v[62:65], v[148:151], v[164:167], v[62:65]
	v_mfma_f32_16x16x32_bf16 v[58:61], v[156:159], v[164:167], v[58:61]
	v_mfma_f32_16x16x32_bf16 v[46:49], v[148:151], v[172:175], v[46:49]
	v_mfma_f32_16x16x32_bf16 v[42:45], v[156:159], v[172:175], v[42:45]
	v_mfma_f32_16x16x32_bf16 v[30:33], v[148:151], v[180:183], v[30:33]
	v_mfma_f32_16x16x32_bf16 v[26:29], v[156:159], v[180:183], v[26:29]
	v_mfma_f32_16x16x32_bf16 v[14:17], v[148:151], v[208:211], v[14:17]
	v_mfma_f32_16x16x32_bf16 v[10:13], v[156:159], v[208:211], v[10:13]
	v_mfma_f32_16x16x32_bf16 v[62:65], v[152:155], v[168:171], v[62:65]
	v_mfma_f32_16x16x32_bf16 v[58:61], v[160:163], v[168:171], v[58:61]
	v_mfma_f32_16x16x32_bf16 v[46:49], v[152:155], v[176:179], v[46:49]
	v_mfma_f32_16x16x32_bf16 v[42:45], v[160:163], v[176:179], v[42:45]
	v_mfma_f32_16x16x32_bf16 v[30:33], v[152:155], v[204:207], v[30:33]
	v_mfma_f32_16x16x32_bf16 v[26:29], v[160:163], v[204:207], v[26:29]
	v_mfma_f32_16x16x32_bf16 v[14:17], v[152:155], v[212:215], v[14:17]
	v_mfma_f32_16x16x32_bf16 v[10:13], v[160:163], v[212:215], v[10:13]
	s_barrier
	s_add_u32 s16, s16, s92
	s_addc_u32 s17, s17, 0
	s_add_i32 s65, s66, s24
	s_add_u32 s76, s16, s6
	s_addc_u32 s77, s17, s7
	s_mov_b32 m0, s65
	s_nop 0
	global_load_lds_dwordx4 v132, s[16:17]
	s_add_i32 m0, s65, 0x2000
	s_nop 0
	global_load_lds_dwordx4 v136, s[16:17]
	s_waitcnt vmcnt(6)
	s_barrier
	v_mfma_f32_16x16x32_bf16 v[50:53], v[216:219], v[164:167], v[50:53]
	v_mfma_f32_16x16x32_bf16 v[54:57], v[224:227], v[164:167], v[54:57]
	v_mfma_f32_16x16x32_bf16 v[34:37], v[216:219], v[172:175], v[34:37]
	v_mfma_f32_16x16x32_bf16 v[38:41], v[224:227], v[172:175], v[38:41]
	v_mfma_f32_16x16x32_bf16 v[18:21], v[216:219], v[180:183], v[18:21]
	v_mfma_f32_16x16x32_bf16 v[22:25], v[224:227], v[180:183], v[22:25]
	v_mfma_f32_16x16x32_bf16 v[6:9], v[216:219], v[208:211], v[6:9]
	v_mfma_f32_16x16x32_bf16 v[2:5], v[224:227], v[208:211], v[2:5]
	v_mfma_f32_16x16x32_bf16 v[50:53], v[220:223], v[168:171], v[50:53]
	v_mfma_f32_16x16x32_bf16 v[54:57], v[228:231], v[168:171], v[54:57]
	v_mfma_f32_16x16x32_bf16 v[34:37], v[220:223], v[176:179], v[34:37]
	v_mfma_f32_16x16x32_bf16 v[38:41], v[228:231], v[176:179], v[38:41]
	v_mfma_f32_16x16x32_bf16 v[18:21], v[220:223], v[204:207], v[18:21]
	v_mfma_f32_16x16x32_bf16 v[22:25], v[228:231], v[204:207], v[22:25]
	v_mfma_f32_16x16x32_bf16 v[6:9], v[220:223], v[212:215], v[6:9]
	v_mfma_f32_16x16x32_bf16 v[2:5], v[228:231], v[212:215], v[2:5]
	s_barrier
	s_add_i32 s16, 0, 0x18000
	ds_read_b128 v[148:151], v248 offset:32768
	ds_read_b128 v[152:155], v248 offset:33792
	ds_read_b128 v[156:159], v248 offset:34816
	ds_read_b128 v[160:163], v248 offset:35840
	s_add_u32 s4, s4, s92
	s_addc_u32 s5, s5, 0
	s_mov_b32 m0, s28
	ds_read_b128 v[164:167], v146 offset:32768
	ds_read_b128 v[168:171], v146 offset:33792
	ds_read_b128 v[172:175], v146 offset:34816
	ds_read_b128 v[176:179], v146 offset:35840
	ds_read_b128 v[180:183], v146 offset:36864
	ds_read_b128 v[204:207], v146 offset:37888
	ds_read_b128 v[208:211], v146 offset:38912
	ds_read_b128 v[212:215], v146 offset:39936
	global_load_lds_dwordx4 v130, s[4:5]
	s_mov_b32 m0, s29
	s_nop 0
	global_load_lds_dwordx4 v134, s[4:5]
	s_waitcnt lgkmcnt(8)
	s_barrier
	s_waitcnt lgkmcnt(0)
	v_mfma_f32_16x16x32_bf16 v[126:129], v[148:151], v[164:167], v[126:129]
	v_mfma_f32_16x16x32_bf16 v[122:125], v[156:159], v[164:167], v[122:125]
	v_mfma_f32_16x16x32_bf16 v[110:113], v[148:151], v[172:175], v[110:113]
	v_mfma_f32_16x16x32_bf16 v[106:109], v[156:159], v[172:175], v[106:109]
	v_mfma_f32_16x16x32_bf16 v[94:97], v[148:151], v[180:183], v[94:97]
	v_mfma_f32_16x16x32_bf16 v[90:93], v[156:159], v[180:183], v[90:93]
	v_mfma_f32_16x16x32_bf16 v[78:81], v[148:151], v[208:211], v[78:81]
	v_mfma_f32_16x16x32_bf16 v[74:77], v[156:159], v[208:211], v[74:77]
	v_mfma_f32_16x16x32_bf16 v[126:129], v[152:155], v[168:171], v[126:129]
	v_mfma_f32_16x16x32_bf16 v[122:125], v[160:163], v[168:171], v[122:125]
	v_mfma_f32_16x16x32_bf16 v[110:113], v[152:155], v[176:179], v[110:113]
	v_mfma_f32_16x16x32_bf16 v[106:109], v[160:163], v[176:179], v[106:109]
	v_mfma_f32_16x16x32_bf16 v[94:97], v[152:155], v[204:207], v[94:97]
	v_mfma_f32_16x16x32_bf16 v[90:93], v[160:163], v[204:207], v[90:93]
	v_mfma_f32_16x16x32_bf16 v[78:81], v[152:155], v[212:215], v[78:81]
	v_mfma_f32_16x16x32_bf16 v[74:77], v[160:163], v[212:215], v[74:77]
	s_barrier
	s_add_i32 s4, 0, 0x1c000
	s_add_i32 s5, s16, s24
	s_mov_b32 m0, s5
	ds_read_b128 v[216:219], v248 offset:49152
	ds_read_b128 v[220:223], v248 offset:50176
	ds_read_b128 v[224:227], v248 offset:51200
	ds_read_b128 v[228:231], v248 offset:52224
	global_load_lds_dwordx4 v132, s[70:71]
	s_add_i32 m0, s5, 0x2000
	s_nop 0
	global_load_lds_dwordx4 v136, s[70:71]
	s_barrier
	s_waitcnt lgkmcnt(0)
	v_mfma_f32_16x16x32_bf16 v[114:117], v[216:219], v[164:167], v[114:117]
	v_mfma_f32_16x16x32_bf16 v[118:121], v[224:227], v[164:167], v[118:121]
	v_mfma_f32_16x16x32_bf16 v[98:101], v[216:219], v[172:175], v[98:101]
	v_mfma_f32_16x16x32_bf16 v[102:105], v[224:227], v[172:175], v[102:105]
	v_mfma_f32_16x16x32_bf16 v[82:85], v[216:219], v[180:183], v[82:85]
	v_mfma_f32_16x16x32_bf16 v[86:89], v[224:227], v[180:183], v[86:89]
	v_mfma_f32_16x16x32_bf16 v[66:69], v[216:219], v[208:211], v[66:69]
	v_mfma_f32_16x16x32_bf16 v[70:73], v[224:227], v[208:211], v[70:73]
	v_mfma_f32_16x16x32_bf16 v[114:117], v[220:223], v[168:171], v[114:117]
	v_mfma_f32_16x16x32_bf16 v[118:121], v[228:231], v[168:171], v[118:121]
	v_mfma_f32_16x16x32_bf16 v[98:101], v[220:223], v[176:179], v[98:101]
	v_mfma_f32_16x16x32_bf16 v[102:105], v[228:231], v[176:179], v[102:105]
	v_mfma_f32_16x16x32_bf16 v[82:85], v[220:223], v[204:207], v[82:85]
	v_mfma_f32_16x16x32_bf16 v[86:89], v[228:231], v[204:207], v[86:89]
	v_mfma_f32_16x16x32_bf16 v[66:69], v[220:223], v[212:215], v[66:69]
	v_mfma_f32_16x16x32_bf16 v[70:73], v[228:231], v[212:215], v[70:73]
	s_barrier
	s_mov_b32 m0, s35
	ds_read_b128 v[164:167], v146 offset:49152
	ds_read_b128 v[168:171], v146 offset:50176
	ds_read_b128 v[172:175], v146 offset:51200
	ds_read_b128 v[176:179], v146 offset:52224
	ds_read_b128 v[180:183], v146 offset:53248
	ds_read_b128 v[204:207], v146 offset:54272
	ds_read_b128 v[208:211], v146 offset:55296
	ds_read_b128 v[212:215], v146 offset:56320
	global_load_lds_dwordx4 v130, s[72:73]
	s_mov_b32 m0, s40
	s_nop 0
	global_load_lds_dwordx4 v134, s[72:73]
	s_barrier
	s_waitcnt lgkmcnt(0)
	v_mfma_f32_16x16x32_bf16 v[62:65], v[148:151], v[164:167], v[62:65]
	v_mfma_f32_16x16x32_bf16 v[58:61], v[156:159], v[164:167], v[58:61]
	v_mfma_f32_16x16x32_bf16 v[46:49], v[148:151], v[172:175], v[46:49]
	v_mfma_f32_16x16x32_bf16 v[42:45], v[156:159], v[172:175], v[42:45]
	v_mfma_f32_16x16x32_bf16 v[30:33], v[148:151], v[180:183], v[30:33]
	v_mfma_f32_16x16x32_bf16 v[26:29], v[156:159], v[180:183], v[26:29]
	v_mfma_f32_16x16x32_bf16 v[14:17], v[148:151], v[208:211], v[14:17]
	v_mfma_f32_16x16x32_bf16 v[10:13], v[156:159], v[208:211], v[10:13]
	v_mfma_f32_16x16x32_bf16 v[62:65], v[152:155], v[168:171], v[62:65]
	v_mfma_f32_16x16x32_bf16 v[58:61], v[160:163], v[168:171], v[58:61]
	v_mfma_f32_16x16x32_bf16 v[46:49], v[152:155], v[176:179], v[46:49]
	v_mfma_f32_16x16x32_bf16 v[42:45], v[160:163], v[176:179], v[42:45]
	v_mfma_f32_16x16x32_bf16 v[30:33], v[152:155], v[204:207], v[30:33]
	v_mfma_f32_16x16x32_bf16 v[26:29], v[160:163], v[204:207], v[26:29]
	v_mfma_f32_16x16x32_bf16 v[14:17], v[152:155], v[212:215], v[14:17]
	v_mfma_f32_16x16x32_bf16 v[10:13], v[160:163], v[212:215], v[10:13]
	s_barrier
	s_add_i32 s4, s4, s24
	s_mov_b32 m0, s4
	s_nop 0
	global_load_lds_dwordx4 v132, s[76:77]
	s_add_i32 m0, s4, 0x2000
	s_nop 0
	global_load_lds_dwordx4 v136, s[76:77]
	s_add_u32 s0, s0, 0x100
	s_addc_u32 s1, s1, 0
	s_add_u32 s47, s47, 0x100
	s_addc_u32 s48, s48, 0
	s_cmp_ge_u32 s49, s30
	s_mov_b32 s4, s49
	s_waitcnt vmcnt(6)
	s_barrier
	v_mfma_f32_16x16x32_bf16 v[50:53], v[216:219], v[164:167], v[50:53]
	v_mfma_f32_16x16x32_bf16 v[54:57], v[224:227], v[164:167], v[54:57]
	v_mfma_f32_16x16x32_bf16 v[34:37], v[216:219], v[172:175], v[34:37]
	v_mfma_f32_16x16x32_bf16 v[38:41], v[224:227], v[172:175], v[38:41]
	v_mfma_f32_16x16x32_bf16 v[18:21], v[216:219], v[180:183], v[18:21]
	v_mfma_f32_16x16x32_bf16 v[22:25], v[224:227], v[180:183], v[22:25]
	v_mfma_f32_16x16x32_bf16 v[6:9], v[216:219], v[208:211], v[6:9]
	v_mfma_f32_16x16x32_bf16 v[2:5], v[224:227], v[208:211], v[2:5]
	v_mfma_f32_16x16x32_bf16 v[50:53], v[220:223], v[168:171], v[50:53]
	v_mfma_f32_16x16x32_bf16 v[54:57], v[228:231], v[168:171], v[54:57]
	v_mfma_f32_16x16x32_bf16 v[34:37], v[220:223], v[176:179], v[34:37]
	v_mfma_f32_16x16x32_bf16 v[38:41], v[228:231], v[176:179], v[38:41]
	v_mfma_f32_16x16x32_bf16 v[18:21], v[220:223], v[204:207], v[18:21]
	v_mfma_f32_16x16x32_bf16 v[22:25], v[228:231], v[204:207], v[22:25]
	v_mfma_f32_16x16x32_bf16 v[6:9], v[220:223], v[212:215], v[6:9]
	v_mfma_f32_16x16x32_bf16 v[2:5], v[228:231], v[212:215], v[2:5]
	s_barrier
	s_cbranch_scc0 .LBB0_253

.LBB0_269:
	s_add_i32 m0, s29, 0x18000
	v_lshl_add_u64 v[2:3], v[2:3], 0, s[6:7]
	s_waitcnt vmcnt(4)
	s_barrier
	global_load_lds_dwordx4 v[2:3], off
	v_lshl_add_u64 v[2:3], v[4:5], 0, s[6:7]
	s_add_i32 m0, s29, 0x1a000
	s_add_i32 s42, s29, 0x8000
	global_load_lds_dwordx4 v[2:3], off
	v_lshl_add_u64 v[2:3], v[6:7], 0, s[6:7]
	s_mov_b32 m0, s42
	s_add_i32 s43, s29, 0xa000
	global_load_lds_dwordx4 v[2:3], off
	v_lshl_add_u64 v[2:3], v[8:9], 0, s[6:7]
	s_mov_b32 m0, s43
	s_lshl_b32 s48, s57, 3
	global_load_lds_dwordx4 v[2:3], off
	s_add_i32 m0, s29, 0x1c000
	v_lshl_add_u64 v[2:3], v[10:11], 0, s[6:7]
	global_load_lds_dwordx4 v[2:3], off
	v_lshl_add_u64 v[2:3], v[12:13], 0, s[6:7]
	s_add_i32 m0, s29, 0x1e000
	v_bfe_u32 v1, v20, 4, 2
	global_load_lds_dwordx4 v[2:3], off
	v_cvt_f32_u32_e32 v2, s48
	s_waitcnt vmcnt(0)
	v_and_b32_e32 v164, 15, v20
	v_lshlrev_b32_e32 v21, 4, v1
	v_lshlrev_b32_e32 v20, 2, v20
	v_rcp_iflag_f32_e32 v2, v2
	s_and_b32 s9, s9, 3
	s_lshl_b32 s40, s8, 6
	v_lshl_or_b32 v21, v164, 6, v21
	v_mul_f32_e32 v2, 0x4f7ffffe, v2
	v_cvt_u32_f32_e32 v2, v2
	s_lshl_b32 s10, s8, 13
	v_and_b32_e32 v20, 32, v20
	s_lshl_b32 s8, s8, 11
	v_bitop3_b32 v22, v21, s10, v20 bitop3:0xde
	s_lshl_b32 s41, s9, 5
	s_lshl_b32 s10, s9, 12
	s_lshl_b32 s9, s9, 9
	s_add_i32 s8, s8, 0
	s_add_i32 s49, s8, s9
	v_readfirstlane_b32 s9, v2
	v_add_u32_e32 v2, v16, v14
	s_sub_i32 s8, 0, s48
	v_add_lshl_u32 v2, v2, v15, 1
	v_mov_b32_e32 v3, v0
	s_waitcnt vmcnt(6)
	s_mul_i32 s8, s8, s9
	v_lshl_add_u64 v[138:139], s[92:93], 0, v[2:3]
	v_add_u32_e32 v2, v19, v17
	s_lshr_b32 s35, s64, 6
	s_lshr_b32 s45, s38, 3
	s_mul_hi_u32 s8, s9, s8
	v_add_lshl_u32 v2, v2, v18, 1
	v_bitop3_b32 v165, v21, s10, v20 bitop3:0xde
	s_add_i32 s44, s35, -2
	s_mov_b32 s39, s93
	s_and_b32 s46, s38, 7
	s_add_i32 s47, s45, 1
	s_add_i32 s49, s49, 0x20000
	s_mov_b32 s65, 0
	s_add_i32 s66, s9, s8
	v_lshl_add_u64 v[140:141], s[92:93], 0, v[2:3]
	s_mov_b32 s19, -1
	v_add_u32_e32 v166, 0, v22
	s_barrier
	v_add_u32_e32 v248, 0x10000, v165
	s_branch .LBB0_271

.LBB0_281:
	s_add_u32 s0, s0, 0x80
	s_addc_u32 s1, s1, 0
	s_add_u32 s20, s4, 0x100
	s_addc_u32 s21, s5, 0
	s_mov_b32 s4, 0
	s_waitcnt lgkmcnt(0)
	s_add_i32 s22, s4, 2
	s_add_u32 s10, s0, 0x80
	s_addc_u32 s5, s1, 0
	s_add_i32 s23, 0, 0x10000
	ds_read_b128 v[142:145], v248
	ds_read_b128 v[146:149], v248 offset:1024
	ds_read_b128 v[150:153], v248 offset:2048
	ds_read_b128 v[154:157], v248 offset:3072
	s_cmp_eq_u32 s44, s4
	s_cselect_b32 s4, s16, s10
	s_cselect_b32 s5, s17, s5
	s_cselect_b32 s11, s13, s21
	s_cselect_b32 s10, s12, s20
	v_lshl_add_u64 v[162:163], s[0:1], 0, v[138:139]
	s_add_i32 m0, s29, 0xc000
	ds_read_b128 v[158:161], v166
	ds_read_b128 v[168:171], v166 offset:1024
	ds_read_b128 v[172:175], v166 offset:2048
	ds_read_b128 v[176:179], v166 offset:3072
	ds_read_b128 v[180:183], v166 offset:4096
	ds_read_b128 v[204:207], v166 offset:5120
	ds_read_b128 v[208:211], v166 offset:6144
	ds_read_b128 v[212:215], v166 offset:7168
	global_load_lds_dwordx4 v[162:163], off
	v_lshl_add_u64 v[162:163], s[0:1], 0, v[140:141]
	s_add_i32 m0, s29, 0xe000
	s_nop 0
	global_load_lds_dwordx4 v[162:163], off
	s_waitcnt lgkmcnt(8)
	s_barrier
	s_waitcnt lgkmcnt(0)
	v_mfma_f32_16x16x32_bf16 v[126:129], v[142:145], v[158:161], 0
	v_mfma_f32_16x16x32_bf16 v[122:125], v[150:153], v[158:161], 0
	v_mfma_f32_16x16x32_bf16 v[110:113], v[142:145], v[172:175], 0
	v_mfma_f32_16x16x32_bf16 v[106:109], v[150:153], v[172:175], 0
	v_mfma_f32_16x16x32_bf16 v[94:97], v[142:145], v[180:183], 0
	v_mfma_f32_16x16x32_bf16 v[90:93], v[150:153], v[180:183], 0
	v_mfma_f32_16x16x32_bf16 v[78:81], v[142:145], v[208:211], 0
	v_mfma_f32_16x16x32_bf16 v[74:77], v[150:153], v[208:211], 0
	v_mfma_f32_16x16x32_bf16 v[126:129], v[146:149], v[168:171], v[126:129]
	v_mfma_f32_16x16x32_bf16 v[122:125], v[154:157], v[168:171], v[122:125]
	v_mfma_f32_16x16x32_bf16 v[110:113], v[146:149], v[176:179], v[110:113]
	v_mfma_f32_16x16x32_bf16 v[106:109], v[154:157], v[176:179], v[106:109]
	v_mfma_f32_16x16x32_bf16 v[94:97], v[146:149], v[204:207], v[94:97]
	v_mfma_f32_16x16x32_bf16 v[90:93], v[154:157], v[204:207], v[90:93]
	v_mfma_f32_16x16x32_bf16 v[78:81], v[146:149], v[212:215], v[78:81]
	v_mfma_f32_16x16x32_bf16 v[74:77], v[154:157], v[212:215], v[74:77]
	s_barrier
	s_add_i32 s24, 0, 0x14000
	s_add_i32 s23, s23, s28
	ds_read_b128 v[216:219], v248 offset:16384
	ds_read_b128 v[220:223], v248 offset:17408
	ds_read_b128 v[224:227], v248 offset:18432
	ds_read_b128 v[228:231], v248 offset:19456
	s_add_u32 s70, s10, s6
	s_addc_u32 s71, s11, s7
	s_mov_b32 m0, s23
	s_nop 0
	global_load_lds_dwordx4 v132, s[10:11]
	s_add_i32 m0, s23, 0x2000
	s_nop 0
	global_load_lds_dwordx4 v136, s[10:11]
	s_barrier
	s_waitcnt lgkmcnt(0)
	v_mfma_f32_16x16x32_bf16 v[118:121], v[216:219], v[158:161], 0
	v_mfma_f32_16x16x32_bf16 v[114:117], v[224:227], v[158:161], 0
	v_mfma_f32_16x16x32_bf16 v[102:105], v[216:219], v[172:175], 0
	v_mfma_f32_16x16x32_bf16 v[98:101], v[224:227], v[172:175], 0
	v_mfma_f32_16x16x32_bf16 v[86:89], v[216:219], v[180:183], 0
	v_mfma_f32_16x16x32_bf16 v[82:85], v[224:227], v[180:183], 0
	v_mfma_f32_16x16x32_bf16 v[70:73], v[216:219], v[208:211], 0
	v_mfma_f32_16x16x32_bf16 v[66:69], v[224:227], v[208:211], 0
	v_mfma_f32_16x16x32_bf16 v[118:121], v[220:223], v[168:171], v[118:121]
	v_mfma_f32_16x16x32_bf16 v[114:117], v[228:231], v[168:171], v[114:117]
	v_mfma_f32_16x16x32_bf16 v[102:105], v[220:223], v[176:179], v[102:105]
	v_mfma_f32_16x16x32_bf16 v[98:101], v[228:231], v[176:179], v[98:101]
	v_mfma_f32_16x16x32_bf16 v[86:89], v[220:223], v[204:207], v[86:89]
	v_mfma_f32_16x16x32_bf16 v[82:85], v[228:231], v[204:207], v[82:85]
	v_mfma_f32_16x16x32_bf16 v[70:73], v[220:223], v[212:215], v[70:73]
	v_mfma_f32_16x16x32_bf16 v[66:69], v[228:231], v[212:215], v[66:69]
	s_barrier
	s_mov_b32 m0, s29
	s_add_u32 s72, s4, s6
	s_addc_u32 s73, s5, s7
	ds_read_b128 v[158:161], v166 offset:16384
	ds_read_b128 v[168:171], v166 offset:17408
	ds_read_b128 v[172:175], v166 offset:18432
	ds_read_b128 v[176:179], v166 offset:19456
	ds_read_b128 v[180:183], v166 offset:20480
	ds_read_b128 v[204:207], v166 offset:21504
	ds_read_b128 v[208:211], v166 offset:22528
	ds_read_b128 v[212:215], v166 offset:23552
	global_load_lds_dwordx4 v130, s[4:5]
	s_mov_b32 m0, s30
	s_nop 0
	global_load_lds_dwordx4 v134, s[4:5]
	s_barrier
	s_waitcnt lgkmcnt(0)
	v_mfma_f32_16x16x32_bf16 v[62:65], v[142:145], v[158:161], 0
	v_mfma_f32_16x16x32_bf16 v[58:61], v[150:153], v[158:161], 0
	v_mfma_f32_16x16x32_bf16 v[46:49], v[142:145], v[172:175], 0
	v_mfma_f32_16x16x32_bf16 v[42:45], v[150:153], v[172:175], 0
	v_mfma_f32_16x16x32_bf16 v[30:33], v[142:145], v[180:183], 0
	v_mfma_f32_16x16x32_bf16 v[26:29], v[150:153], v[180:183], 0
	v_mfma_f32_16x16x32_bf16 v[14:17], v[142:145], v[208:211], 0
	v_mfma_f32_16x16x32_bf16 v[10:13], v[150:153], v[208:211], 0
	v_mfma_f32_16x16x32_bf16 v[62:65], v[146:149], v[168:171], v[62:65]
	v_mfma_f32_16x16x32_bf16 v[58:61], v[154:157], v[168:171], v[58:61]
	v_mfma_f32_16x16x32_bf16 v[46:49], v[146:149], v[176:179], v[46:49]
	v_mfma_f32_16x16x32_bf16 v[42:45], v[154:157], v[176:179], v[42:45]
	v_mfma_f32_16x16x32_bf16 v[30:33], v[146:149], v[204:207], v[30:33]
	v_mfma_f32_16x16x32_bf16 v[26:29], v[154:157], v[204:207], v[26:29]
	v_mfma_f32_16x16x32_bf16 v[14:17], v[146:149], v[212:215], v[14:17]
	v_mfma_f32_16x16x32_bf16 v[10:13], v[154:157], v[212:215], v[10:13]
	s_barrier
	s_add_u32 s10, s10, s92
	s_addc_u32 s11, s11, 0
	s_add_i32 s23, s24, s28
	s_add_u32 s80, s10, s6
	s_addc_u32 s81, s11, s7
	s_mov_b32 m0, s23
	s_nop 0
	global_load_lds_dwordx4 v132, s[10:11]
	s_add_i32 m0, s23, 0x2000
	s_nop 0
	global_load_lds_dwordx4 v136, s[10:11]
	s_waitcnt vmcnt(6)
	s_barrier
	v_mfma_f32_16x16x32_bf16 v[54:57], v[216:219], v[158:161], 0
	v_mfma_f32_16x16x32_bf16 v[50:53], v[224:227], v[158:161], 0
	v_mfma_f32_16x16x32_bf16 v[38:41], v[216:219], v[172:175], 0
	v_mfma_f32_16x16x32_bf16 v[34:37], v[224:227], v[172:175], 0
	v_mfma_f32_16x16x32_bf16 v[22:25], v[216:219], v[180:183], 0
	v_mfma_f32_16x16x32_bf16 v[18:21], v[224:227], v[180:183], 0
	v_mfma_f32_16x16x32_bf16 v[6:9], v[216:219], v[208:211], 0
	v_mfma_f32_16x16x32_bf16 v[2:5], v[224:227], v[208:211], 0
	v_mfma_f32_16x16x32_bf16 v[54:57], v[220:223], v[168:171], v[54:57]
	v_mfma_f32_16x16x32_bf16 v[50:53], v[228:231], v[168:171], v[50:53]
	v_mfma_f32_16x16x32_bf16 v[38:41], v[220:223], v[176:179], v[38:41]
	v_mfma_f32_16x16x32_bf16 v[34:37], v[228:231], v[176:179], v[34:37]
	v_mfma_f32_16x16x32_bf16 v[22:25], v[220:223], v[204:207], v[22:25]
	v_mfma_f32_16x16x32_bf16 v[18:21], v[228:231], v[204:207], v[18:21]
	v_mfma_f32_16x16x32_bf16 v[6:9], v[220:223], v[212:215], v[6:9]
	v_mfma_f32_16x16x32_bf16 v[2:5], v[228:231], v[212:215], v[2:5]
	s_barrier
	s_add_i32 s10, 0, 0x18000
	ds_read_b128 v[142:145], v248 offset:32768
	ds_read_b128 v[146:149], v248 offset:33792
	ds_read_b128 v[150:153], v248 offset:34816
	ds_read_b128 v[154:157], v248 offset:35840
	s_add_u32 s4, s4, s92
	s_addc_u32 s5, s5, 0
	s_mov_b32 m0, s31
	ds_read_b128 v[158:161], v166 offset:32768
	ds_read_b128 v[168:171], v166 offset:33792
	ds_read_b128 v[172:175], v166 offset:34816
	ds_read_b128 v[176:179], v166 offset:35840
	ds_read_b128 v[180:183], v166 offset:36864
	ds_read_b128 v[204:207], v166 offset:37888
	ds_read_b128 v[208:211], v166 offset:38912
	ds_read_b128 v[212:215], v166 offset:39936
	global_load_lds_dwordx4 v130, s[4:5]
	s_mov_b32 m0, s34
	s_nop 0
	global_load_lds_dwordx4 v134, s[4:5]
	s_waitcnt lgkmcnt(8)
	s_barrier
	s_waitcnt lgkmcnt(0)
	v_mfma_f32_16x16x32_bf16 v[126:129], v[142:145], v[158:161], v[126:129]
	v_mfma_f32_16x16x32_bf16 v[122:125], v[150:153], v[158:161], v[122:125]
	v_mfma_f32_16x16x32_bf16 v[110:113], v[142:145], v[172:175], v[110:113]
	v_mfma_f32_16x16x32_bf16 v[106:109], v[150:153], v[172:175], v[106:109]
	v_mfma_f32_16x16x32_bf16 v[94:97], v[142:145], v[180:183], v[94:97]
	v_mfma_f32_16x16x32_bf16 v[90:93], v[150:153], v[180:183], v[90:93]
	v_mfma_f32_16x16x32_bf16 v[78:81], v[142:145], v[208:211], v[78:81]
	v_mfma_f32_16x16x32_bf16 v[74:77], v[150:153], v[208:211], v[74:77]
	v_mfma_f32_16x16x32_bf16 v[126:129], v[146:149], v[168:171], v[126:129]
	v_mfma_f32_16x16x32_bf16 v[122:125], v[154:157], v[168:171], v[122:125]
	v_mfma_f32_16x16x32_bf16 v[110:113], v[146:149], v[176:179], v[110:113]
	v_mfma_f32_16x16x32_bf16 v[106:109], v[154:157], v[176:179], v[106:109]
	v_mfma_f32_16x16x32_bf16 v[94:97], v[146:149], v[204:207], v[94:97]
	v_mfma_f32_16x16x32_bf16 v[90:93], v[154:157], v[204:207], v[90:93]
	v_mfma_f32_16x16x32_bf16 v[78:81], v[146:149], v[212:215], v[78:81]
	v_mfma_f32_16x16x32_bf16 v[74:77], v[154:157], v[212:215], v[74:77]
	s_barrier
	s_add_i32 s4, 0, 0x1c000
	s_add_i32 s5, s10, s28
	s_mov_b32 m0, s5
	ds_read_b128 v[216:219], v248 offset:49152
	ds_read_b128 v[220:223], v248 offset:50176
	ds_read_b128 v[224:227], v248 offset:51200
	ds_read_b128 v[228:231], v248 offset:52224
	global_load_lds_dwordx4 v132, s[70:71]
	s_add_i32 m0, s5, 0x2000
	s_nop 0
	global_load_lds_dwordx4 v136, s[70:71]
	s_barrier
	s_waitcnt lgkmcnt(0)
	v_mfma_f32_16x16x32_bf16 v[118:121], v[216:219], v[158:161], v[118:121]
	v_mfma_f32_16x16x32_bf16 v[114:117], v[224:227], v[158:161], v[114:117]
	v_mfma_f32_16x16x32_bf16 v[102:105], v[216:219], v[172:175], v[102:105]
	v_mfma_f32_16x16x32_bf16 v[98:101], v[224:227], v[172:175], v[98:101]
	v_mfma_f32_16x16x32_bf16 v[86:89], v[216:219], v[180:183], v[86:89]
	v_mfma_f32_16x16x32_bf16 v[82:85], v[224:227], v[180:183], v[82:85]
	v_mfma_f32_16x16x32_bf16 v[70:73], v[216:219], v[208:211], v[70:73]
	v_mfma_f32_16x16x32_bf16 v[66:69], v[224:227], v[208:211], v[66:69]
	v_mfma_f32_16x16x32_bf16 v[118:121], v[220:223], v[168:171], v[118:121]
	v_mfma_f32_16x16x32_bf16 v[114:117], v[228:231], v[168:171], v[114:117]
	v_mfma_f32_16x16x32_bf16 v[102:105], v[220:223], v[176:179], v[102:105]
	v_mfma_f32_16x16x32_bf16 v[98:101], v[228:231], v[176:179], v[98:101]
	v_mfma_f32_16x16x32_bf16 v[86:89], v[220:223], v[204:207], v[86:89]
	v_mfma_f32_16x16x32_bf16 v[82:85], v[228:231], v[204:207], v[82:85]
	v_mfma_f32_16x16x32_bf16 v[70:73], v[220:223], v[212:215], v[70:73]
	v_mfma_f32_16x16x32_bf16 v[66:69], v[228:231], v[212:215], v[66:69]
	s_barrier
	s_mov_b32 m0, s42
	ds_read_b128 v[158:161], v166 offset:49152
	ds_read_b128 v[168:171], v166 offset:50176
	ds_read_b128 v[172:175], v166 offset:51200
	ds_read_b128 v[176:179], v166 offset:52224
	ds_read_b128 v[180:183], v166 offset:53248
	ds_read_b128 v[204:207], v166 offset:54272
	ds_read_b128 v[208:211], v166 offset:55296
	ds_read_b128 v[212:215], v166 offset:56320
	global_load_lds_dwordx4 v130, s[72:73]
	s_mov_b32 m0, s43
	s_nop 0
	global_load_lds_dwordx4 v134, s[72:73]
	s_barrier
	s_waitcnt lgkmcnt(0)
	v_mfma_f32_16x16x32_bf16 v[62:65], v[142:145], v[158:161], v[62:65]
	v_mfma_f32_16x16x32_bf16 v[58:61], v[150:153], v[158:161], v[58:61]
	v_mfma_f32_16x16x32_bf16 v[46:49], v[142:145], v[172:175], v[46:49]
	v_mfma_f32_16x16x32_bf16 v[42:45], v[150:153], v[172:175], v[42:45]
	v_mfma_f32_16x16x32_bf16 v[30:33], v[142:145], v[180:183], v[30:33]
	v_mfma_f32_16x16x32_bf16 v[26:29], v[150:153], v[180:183], v[26:29]
	v_mfma_f32_16x16x32_bf16 v[14:17], v[142:145], v[208:211], v[14:17]
	v_mfma_f32_16x16x32_bf16 v[10:13], v[150:153], v[208:211], v[10:13]
	v_mfma_f32_16x16x32_bf16 v[62:65], v[146:149], v[168:171], v[62:65]
	v_mfma_f32_16x16x32_bf16 v[58:61], v[154:157], v[168:171], v[58:61]
	v_mfma_f32_16x16x32_bf16 v[46:49], v[146:149], v[176:179], v[46:49]
	v_mfma_f32_16x16x32_bf16 v[42:45], v[154:157], v[176:179], v[42:45]
	v_mfma_f32_16x16x32_bf16 v[30:33], v[146:149], v[204:207], v[30:33]
	v_mfma_f32_16x16x32_bf16 v[26:29], v[154:157], v[204:207], v[26:29]
	v_mfma_f32_16x16x32_bf16 v[14:17], v[146:149], v[212:215], v[14:17]
	v_mfma_f32_16x16x32_bf16 v[10:13], v[154:157], v[212:215], v[10:13]
	s_barrier
	s_add_i32 s4, s4, s28
	s_mov_b32 m0, s4
	s_nop 0
	global_load_lds_dwordx4 v132, s[80:81]
	s_add_i32 m0, s4, 0x2000
	s_nop 0
	global_load_lds_dwordx4 v136, s[80:81]
	s_add_u32 s0, s0, 0x100
	s_addc_u32 s1, s1, 0
	s_add_u32 s20, s20, 0x100
	s_addc_u32 s21, s21, 0
	s_cmp_ge_u32 s22, s35
	s_mov_b32 s4, s22
	s_waitcnt vmcnt(6)
	s_barrier
	v_mfma_f32_16x16x32_bf16 v[54:57], v[216:219], v[158:161], v[54:57]
	v_mfma_f32_16x16x32_bf16 v[50:53], v[224:227], v[158:161], v[50:53]
	v_mfma_f32_16x16x32_bf16 v[38:41], v[216:219], v[172:175], v[38:41]
	v_mfma_f32_16x16x32_bf16 v[34:37], v[224:227], v[172:175], v[34:37]
	v_mfma_f32_16x16x32_bf16 v[22:25], v[216:219], v[180:183], v[22:25]
	v_mfma_f32_16x16x32_bf16 v[18:21], v[224:227], v[180:183], v[18:21]
	v_mfma_f32_16x16x32_bf16 v[6:9], v[216:219], v[208:211], v[6:9]
	v_mfma_f32_16x16x32_bf16 v[2:5], v[224:227], v[208:211], v[2:5]
	v_mfma_f32_16x16x32_bf16 v[54:57], v[220:223], v[168:171], v[54:57]
	v_mfma_f32_16x16x32_bf16 v[50:53], v[228:231], v[168:171], v[50:53]
	v_mfma_f32_16x16x32_bf16 v[38:41], v[220:223], v[176:179], v[38:41]
	v_mfma_f32_16x16x32_bf16 v[34:37], v[228:231], v[176:179], v[34:37]
	v_mfma_f32_16x16x32_bf16 v[22:25], v[220:223], v[204:207], v[22:25]
	v_mfma_f32_16x16x32_bf16 v[18:21], v[228:231], v[204:207], v[18:21]
	v_mfma_f32_16x16x32_bf16 v[6:9], v[220:223], v[212:215], v[6:9]
	v_mfma_f32_16x16x32_bf16 v[2:5], v[228:231], v[212:215], v[2:5]
	s_barrier
	s_cbranch_scc1 .Lkexit_282
.LBB0_282:
	s_add_i32 s22, s4, 2
	s_add_u32 s10, s0, 0x80
	s_addc_u32 s5, s1, 0
	s_add_i32 s23, 0, 0x10000
	ds_read_b128 v[142:145], v248
	ds_read_b128 v[146:149], v248 offset:1024
	ds_read_b128 v[150:153], v248 offset:2048
	ds_read_b128 v[154:157], v248 offset:3072
	s_cmp_eq_u32 s44, s4
	s_cselect_b32 s4, s16, s10
	s_cselect_b32 s5, s17, s5
	s_cselect_b32 s11, s13, s21
	s_cselect_b32 s10, s12, s20
	v_lshl_add_u64 v[162:163], s[0:1], 0, v[138:139]
	s_add_i32 m0, s29, 0xc000
	ds_read_b128 v[158:161], v166
	ds_read_b128 v[168:171], v166 offset:1024
	ds_read_b128 v[172:175], v166 offset:2048
	ds_read_b128 v[176:179], v166 offset:3072
	ds_read_b128 v[180:183], v166 offset:4096
	ds_read_b128 v[204:207], v166 offset:5120
	ds_read_b128 v[208:211], v166 offset:6144
	ds_read_b128 v[212:215], v166 offset:7168
	global_load_lds_dwordx4 v[162:163], off
	v_lshl_add_u64 v[162:163], s[0:1], 0, v[140:141]
	s_add_i32 m0, s29, 0xe000
	s_nop 0
	global_load_lds_dwordx4 v[162:163], off
	s_waitcnt lgkmcnt(8)
	s_barrier
	s_waitcnt lgkmcnt(0)
	v_mfma_f32_16x16x32_bf16 v[126:129], v[142:145], v[158:161], v[126:129]
	v_mfma_f32_16x16x32_bf16 v[122:125], v[150:153], v[158:161], v[122:125]
	v_mfma_f32_16x16x32_bf16 v[110:113], v[142:145], v[172:175], v[110:113]
	v_mfma_f32_16x16x32_bf16 v[106:109], v[150:153], v[172:175], v[106:109]
	v_mfma_f32_16x16x32_bf16 v[94:97], v[142:145], v[180:183], v[94:97]
	v_mfma_f32_16x16x32_bf16 v[90:93], v[150:153], v[180:183], v[90:93]
	v_mfma_f32_16x16x32_bf16 v[78:81], v[142:145], v[208:211], v[78:81]
	v_mfma_f32_16x16x32_bf16 v[74:77], v[150:153], v[208:211], v[74:77]
	v_mfma_f32_16x16x32_bf16 v[126:129], v[146:149], v[168:171], v[126:129]
	v_mfma_f32_16x16x32_bf16 v[122:125], v[154:157], v[168:171], v[122:125]
	v_mfma_f32_16x16x32_bf16 v[110:113], v[146:149], v[176:179], v[110:113]
	v_mfma_f32_16x16x32_bf16 v[106:109], v[154:157], v[176:179], v[106:109]
	v_mfma_f32_16x16x32_bf16 v[94:97], v[146:149], v[204:207], v[94:97]
	v_mfma_f32_16x16x32_bf16 v[90:93], v[154:157], v[204:207], v[90:93]
	v_mfma_f32_16x16x32_bf16 v[78:81], v[146:149], v[212:215], v[78:81]
	v_mfma_f32_16x16x32_bf16 v[74:77], v[154:157], v[212:215], v[74:77]
	s_barrier
	s_add_i32 s24, 0, 0x14000
	s_add_i32 s23, s23, s28
	ds_read_b128 v[216:219], v248 offset:16384
	ds_read_b128 v[220:223], v248 offset:17408
	ds_read_b128 v[224:227], v248 offset:18432
	ds_read_b128 v[228:231], v248 offset:19456
	s_add_u32 s70, s10, s6
	s_addc_u32 s71, s11, s7
	s_mov_b32 m0, s23
	s_nop 0
	global_load_lds_dwordx4 v132, s[10:11]
	s_add_i32 m0, s23, 0x2000
	s_nop 0
	global_load_lds_dwordx4 v136, s[10:11]
	s_barrier
	s_waitcnt lgkmcnt(0)
	v_mfma_f32_16x16x32_bf16 v[118:121], v[216:219], v[158:161], v[118:121]
	v_mfma_f32_16x16x32_bf16 v[114:117], v[224:227], v[158:161], v[114:117]
	v_mfma_f32_16x16x32_bf16 v[102:105], v[216:219], v[172:175], v[102:105]
	v_mfma_f32_16x16x32_bf16 v[98:101], v[224:227], v[172:175], v[98:101]
	v_mfma_f32_16x16x32_bf16 v[86:89], v[216:219], v[180:183], v[86:89]
	v_mfma_f32_16x16x32_bf16 v[82:85], v[224:227], v[180:183], v[82:85]
	v_mfma_f32_16x16x32_bf16 v[70:73], v[216:219], v[208:211], v[70:73]
	v_mfma_f32_16x16x32_bf16 v[66:69], v[224:227], v[208:211], v[66:69]
	v_mfma_f32_16x16x32_bf16 v[118:121], v[220:223], v[168:171], v[118:121]
	v_mfma_f32_16x16x32_bf16 v[114:117], v[228:231], v[168:171], v[114:117]
	v_mfma_f32_16x16x32_bf16 v[102:105], v[220:223], v[176:179], v[102:105]
	v_mfma_f32_16x16x32_bf16 v[98:101], v[228:231], v[176:179], v[98:101]
	v_mfma_f32_16x16x32_bf16 v[86:89], v[220:223], v[204:207], v[86:89]
	v_mfma_f32_16x16x32_bf16 v[82:85], v[228:231], v[204:207], v[82:85]
	v_mfma_f32_16x16x32_bf16 v[70:73], v[220:223], v[212:215], v[70:73]
	v_mfma_f32_16x16x32_bf16 v[66:69], v[228:231], v[212:215], v[66:69]
	s_barrier
	s_mov_b32 m0, s29
	s_add_u32 s72, s4, s6
	s_addc_u32 s73, s5, s7
	ds_read_b128 v[158:161], v166 offset:16384
	ds_read_b128 v[168:171], v166 offset:17408
	ds_read_b128 v[172:175], v166 offset:18432
	ds_read_b128 v[176:179], v166 offset:19456
	ds_read_b128 v[180:183], v166 offset:20480
	ds_read_b128 v[204:207], v166 offset:21504
	ds_read_b128 v[208:211], v166 offset:22528
	ds_read_b128 v[212:215], v166 offset:23552
	global_load_lds_dwordx4 v130, s[4:5]
	s_mov_b32 m0, s30
	s_nop 0
	global_load_lds_dwordx4 v134, s[4:5]
	s_barrier
	s_waitcnt lgkmcnt(0)
	v_mfma_f32_16x16x32_bf16 v[62:65], v[142:145], v[158:161], v[62:65]
	v_mfma_f32_16x16x32_bf16 v[58:61], v[150:153], v[158:161], v[58:61]
	v_mfma_f32_16x16x32_bf16 v[46:49], v[142:145], v[172:175], v[46:49]
	v_mfma_f32_16x16x32_bf16 v[42:45], v[150:153], v[172:175], v[42:45]
	v_mfma_f32_16x16x32_bf16 v[30:33], v[142:145], v[180:183], v[30:33]
	v_mfma_f32_16x16x32_bf16 v[26:29], v[150:153], v[180:183], v[26:29]
	v_mfma_f32_16x16x32_bf16 v[14:17], v[142:145], v[208:211], v[14:17]
	v_mfma_f32_16x16x32_bf16 v[10:13], v[150:153], v[208:211], v[10:13]
	v_mfma_f32_16x16x32_bf16 v[62:65], v[146:149], v[168:171], v[62:65]
	v_mfma_f32_16x16x32_bf16 v[58:61], v[154:157], v[168:171], v[58:61]
	v_mfma_f32_16x16x32_bf16 v[46:49], v[146:149], v[176:179], v[46:49]
	v_mfma_f32_16x16x32_bf16 v[42:45], v[154:157], v[176:179], v[42:45]
	v_mfma_f32_16x16x32_bf16 v[30:33], v[146:149], v[204:207], v[30:33]
	v_mfma_f32_16x16x32_bf16 v[26:29], v[154:157], v[204:207], v[26:29]
	v_mfma_f32_16x16x32_bf16 v[14:17], v[146:149], v[212:215], v[14:17]
	v_mfma_f32_16x16x32_bf16 v[10:13], v[154:157], v[212:215], v[10:13]
	s_barrier
	s_add_u32 s10, s10, s92
	s_addc_u32 s11, s11, 0
	s_add_i32 s23, s24, s28
	s_add_u32 s80, s10, s6
	s_addc_u32 s81, s11, s7
	s_mov_b32 m0, s23
	s_nop 0
	global_load_lds_dwordx4 v132, s[10:11]
	s_add_i32 m0, s23, 0x2000
	s_nop 0
	global_load_lds_dwordx4 v136, s[10:11]
	s_waitcnt vmcnt(6)
	s_barrier
	v_mfma_f32_16x16x32_bf16 v[54:57], v[216:219], v[158:161], v[54:57]
	v_mfma_f32_16x16x32_bf16 v[50:53], v[224:227], v[158:161], v[50:53]
	v_mfma_f32_16x16x32_bf16 v[38:41], v[216:219], v[172:175], v[38:41]
	v_mfma_f32_16x16x32_bf16 v[34:37], v[224:227], v[172:175], v[34:37]
	v_mfma_f32_16x16x32_bf16 v[22:25], v[216:219], v[180:183], v[22:25]
	v_mfma_f32_16x16x32_bf16 v[18:21], v[224:227], v[180:183], v[18:21]
	v_mfma_f32_16x16x32_bf16 v[6:9], v[216:219], v[208:211], v[6:9]
	v_mfma_f32_16x16x32_bf16 v[2:5], v[224:227], v[208:211], v[2:5]
	v_mfma_f32_16x16x32_bf16 v[54:57], v[220:223], v[168:171], v[54:57]
	v_mfma_f32_16x16x32_bf16 v[50:53], v[228:231], v[168:171], v[50:53]
	v_mfma_f32_16x16x32_bf16 v[38:41], v[220:223], v[176:179], v[38:41]
	v_mfma_f32_16x16x32_bf16 v[34:37], v[228:231], v[176:179], v[34:37]
	v_mfma_f32_16x16x32_bf16 v[22:25], v[220:223], v[204:207], v[22:25]
	v_mfma_f32_16x16x32_bf16 v[18:21], v[228:231], v[204:207], v[18:21]
	v_mfma_f32_16x16x32_bf16 v[6:9], v[220:223], v[212:215], v[6:9]
	v_mfma_f32_16x16x32_bf16 v[2:5], v[228:231], v[212:215], v[2:5]
	s_barrier
	s_add_i32 s10, 0, 0x18000
	ds_read_b128 v[142:145], v248 offset:32768
	ds_read_b128 v[146:149], v248 offset:33792
	ds_read_b128 v[150:153], v248 offset:34816
	ds_read_b128 v[154:157], v248 offset:35840
	s_add_u32 s4, s4, s92
	s_addc_u32 s5, s5, 0
	s_mov_b32 m0, s31
	ds_read_b128 v[158:161], v166 offset:32768
	ds_read_b128 v[168:171], v166 offset:33792
	ds_read_b128 v[172:175], v166 offset:34816
	ds_read_b128 v[176:179], v166 offset:35840
	ds_read_b128 v[180:183], v166 offset:36864
	ds_read_b128 v[204:207], v166 offset:37888
	ds_read_b128 v[208:211], v166 offset:38912
	ds_read_b128 v[212:215], v166 offset:39936
	global_load_lds_dwordx4 v130, s[4:5]
	s_mov_b32 m0, s34
	s_nop 0
	global_load_lds_dwordx4 v134, s[4:5]
	s_waitcnt lgkmcnt(8)
	s_barrier
	s_waitcnt lgkmcnt(0)
	v_mfma_f32_16x16x32_bf16 v[126:129], v[142:145], v[158:161], v[126:129]
	v_mfma_f32_16x16x32_bf16 v[122:125], v[150:153], v[158:161], v[122:125]
	v_mfma_f32_16x16x32_bf16 v[110:113], v[142:145], v[172:175], v[110:113]
	v_mfma_f32_16x16x32_bf16 v[106:109], v[150:153], v[172:175], v[106:109]
	v_mfma_f32_16x16x32_bf16 v[94:97], v[142:145], v[180:183], v[94:97]
	v_mfma_f32_16x16x32_bf16 v[90:93], v[150:153], v[180:183], v[90:93]
	v_mfma_f32_16x16x32_bf16 v[78:81], v[142:145], v[208:211], v[78:81]
	v_mfma_f32_16x16x32_bf16 v[74:77], v[150:153], v[208:211], v[74:77]
	v_mfma_f32_16x16x32_bf16 v[126:129], v[146:149], v[168:171], v[126:129]
	v_mfma_f32_16x16x32_bf16 v[122:125], v[154:157], v[168:171], v[122:125]
	v_mfma_f32_16x16x32_bf16 v[110:113], v[146:149], v[176:179], v[110:113]
	v_mfma_f32_16x16x32_bf16 v[106:109], v[154:157], v[176:179], v[106:109]
	v_mfma_f32_16x16x32_bf16 v[94:97], v[146:149], v[204:207], v[94:97]
	v_mfma_f32_16x16x32_bf16 v[90:93], v[154:157], v[204:207], v[90:93]
	v_mfma_f32_16x16x32_bf16 v[78:81], v[146:149], v[212:215], v[78:81]
	v_mfma_f32_16x16x32_bf16 v[74:77], v[154:157], v[212:215], v[74:77]
	s_barrier
	s_add_i32 s4, 0, 0x1c000
	s_add_i32 s5, s10, s28
	s_mov_b32 m0, s5
	ds_read_b128 v[216:219], v248 offset:49152
	ds_read_b128 v[220:223], v248 offset:50176
	ds_read_b128 v[224:227], v248 offset:51200
	ds_read_b128 v[228:231], v248 offset:52224
	global_load_lds_dwordx4 v132, s[70:71]
	s_add_i32 m0, s5, 0x2000
	s_nop 0
	global_load_lds_dwordx4 v136, s[70:71]
	s_barrier
	s_waitcnt lgkmcnt(0)
	v_mfma_f32_16x16x32_bf16 v[118:121], v[216:219], v[158:161], v[118:121]
	v_mfma_f32_16x16x32_bf16 v[114:117], v[224:227], v[158:161], v[114:117]
	v_mfma_f32_16x16x32_bf16 v[102:105], v[216:219], v[172:175], v[102:105]
	v_mfma_f32_16x16x32_bf16 v[98:101], v[224:227], v[172:175], v[98:101]
	v_mfma_f32_16x16x32_bf16 v[86:89], v[216:219], v[180:183], v[86:89]
	v_mfma_f32_16x16x32_bf16 v[82:85], v[224:227], v[180:183], v[82:85]
	v_mfma_f32_16x16x32_bf16 v[70:73], v[216:219], v[208:211], v[70:73]
	v_mfma_f32_16x16x32_bf16 v[66:69], v[224:227], v[208:211], v[66:69]
	v_mfma_f32_16x16x32_bf16 v[118:121], v[220:223], v[168:171], v[118:121]
	v_mfma_f32_16x16x32_bf16 v[114:117], v[228:231], v[168:171], v[114:117]
	v_mfma_f32_16x16x32_bf16 v[102:105], v[220:223], v[176:179], v[102:105]
	v_mfma_f32_16x16x32_bf16 v[98:101], v[228:231], v[176:179], v[98:101]
	v_mfma_f32_16x16x32_bf16 v[86:89], v[220:223], v[204:207], v[86:89]
	v_mfma_f32_16x16x32_bf16 v[82:85], v[228:231], v[204:207], v[82:85]
	v_mfma_f32_16x16x32_bf16 v[70:73], v[220:223], v[212:215], v[70:73]
	v_mfma_f32_16x16x32_bf16 v[66:69], v[228:231], v[212:215], v[66:69]
	s_barrier
	s_mov_b32 m0, s42
	ds_read_b128 v[158:161], v166 offset:49152
	ds_read_b128 v[168:171], v166 offset:50176
	ds_read_b128 v[172:175], v166 offset:51200
	ds_read_b128 v[176:179], v166 offset:52224
	ds_read_b128 v[180:183], v166 offset:53248
	ds_read_b128 v[204:207], v166 offset:54272
	ds_read_b128 v[208:211], v166 offset:55296
	ds_read_b128 v[212:215], v166 offset:56320
	global_load_lds_dwordx4 v130, s[72:73]
	s_mov_b32 m0, s43
	s_nop 0
	global_load_lds_dwordx4 v134, s[72:73]
	s_barrier
	s_waitcnt lgkmcnt(0)
	v_mfma_f32_16x16x32_bf16 v[62:65], v[142:145], v[158:161], v[62:65]
	v_mfma_f32_16x16x32_bf16 v[58:61], v[150:153], v[158:161], v[58:61]
	v_mfma_f32_16x16x32_bf16 v[46:49], v[142:145], v[172:175], v[46:49]
	v_mfma_f32_16x16x32_bf16 v[42:45], v[150:153], v[172:175], v[42:45]
	v_mfma_f32_16x16x32_bf16 v[30:33], v[142:145], v[180:183], v[30:33]
	v_mfma_f32_16x16x32_bf16 v[26:29], v[150:153], v[180:183], v[26:29]
	v_mfma_f32_16x16x32_bf16 v[14:17], v[142:145], v[208:211], v[14:17]
	v_mfma_f32_16x16x32_bf16 v[10:13], v[150:153], v[208:211], v[10:13]
	v_mfma_f32_16x16x32_bf16 v[62:65], v[146:149], v[168:171], v[62:65]
	v_mfma_f32_16x16x32_bf16 v[58:61], v[154:157], v[168:171], v[58:61]
	v_mfma_f32_16x16x32_bf16 v[46:49], v[146:149], v[176:179], v[46:49]
	v_mfma_f32_16x16x32_bf16 v[42:45], v[154:157], v[176:179], v[42:45]
	v_mfma_f32_16x16x32_bf16 v[30:33], v[146:149], v[204:207], v[30:33]
	v_mfma_f32_16x16x32_bf16 v[26:29], v[154:157], v[204:207], v[26:29]
	v_mfma_f32_16x16x32_bf16 v[14:17], v[146:149], v[212:215], v[14:17]
	v_mfma_f32_16x16x32_bf16 v[10:13], v[154:157], v[212:215], v[10:13]
	s_barrier
	s_add_i32 s4, s4, s28
	s_mov_b32 m0, s4
	s_nop 0
	global_load_lds_dwordx4 v132, s[80:81]
	s_add_i32 m0, s4, 0x2000
	s_nop 0
	global_load_lds_dwordx4 v136, s[80:81]
	s_add_u32 s0, s0, 0x100
	s_addc_u32 s1, s1, 0
	s_add_u32 s20, s20, 0x100
	s_addc_u32 s21, s21, 0
	s_cmp_ge_u32 s22, s35
	s_mov_b32 s4, s22
	s_waitcnt vmcnt(6)
	s_barrier
	v_mfma_f32_16x16x32_bf16 v[54:57], v[216:219], v[158:161], v[54:57]
	v_mfma_f32_16x16x32_bf16 v[50:53], v[224:227], v[158:161], v[50:53]
	v_mfma_f32_16x16x32_bf16 v[38:41], v[216:219], v[172:175], v[38:41]
	v_mfma_f32_16x16x32_bf16 v[34:37], v[224:227], v[172:175], v[34:37]
	v_mfma_f32_16x16x32_bf16 v[22:25], v[216:219], v[180:183], v[22:25]
	v_mfma_f32_16x16x32_bf16 v[18:21], v[224:227], v[180:183], v[18:21]
	v_mfma_f32_16x16x32_bf16 v[6:9], v[216:219], v[208:211], v[6:9]
	v_mfma_f32_16x16x32_bf16 v[2:5], v[224:227], v[208:211], v[2:5]
	v_mfma_f32_16x16x32_bf16 v[54:57], v[220:223], v[168:171], v[54:57]
	v_mfma_f32_16x16x32_bf16 v[50:53], v[228:231], v[168:171], v[50:53]
	v_mfma_f32_16x16x32_bf16 v[38:41], v[220:223], v[176:179], v[38:41]
	v_mfma_f32_16x16x32_bf16 v[34:37], v[228:231], v[176:179], v[34:37]
	v_mfma_f32_16x16x32_bf16 v[22:25], v[220:223], v[204:207], v[22:25]
	v_mfma_f32_16x16x32_bf16 v[18:21], v[228:231], v[204:207], v[18:21]
	v_mfma_f32_16x16x32_bf16 v[6:9], v[220:223], v[212:215], v[6:9]
	v_mfma_f32_16x16x32_bf16 v[2:5], v[228:231], v[212:215], v[2:5]
	s_barrier
	s_cbranch_scc0 .LBB0_282

.LBB0_333:
	s_add_i32 m0, s71, 0x18000
	v_lshl_add_u64 v[2:3], v[2:3], 0, s[6:7]
	s_waitcnt vmcnt(4)
	s_barrier
	global_load_lds_dwordx4 v[2:3], off
	v_lshl_add_u64 v[2:3], v[4:5], 0, s[6:7]
	s_add_i32 m0, s71, 0x1a000
	s_add_i32 s77, s71, 0x8000
	global_load_lds_dwordx4 v[2:3], off
	v_lshl_add_u64 v[2:3], v[6:7], 0, s[6:7]
	s_mov_b32 m0, s77
	s_add_i32 s78, s71, 0xa000
	global_load_lds_dwordx4 v[2:3], off
	v_lshl_add_u64 v[2:3], v[8:9], 0, s[6:7]
	s_mov_b32 m0, s78
	v_bfe_u32 v1, v20, 4, 2
	global_load_lds_dwordx4 v[2:3], off
	s_add_i32 m0, s71, 0x1c000
	v_lshl_add_u64 v[2:3], v[10:11], 0, s[6:7]
	global_load_lds_dwordx4 v[2:3], off
	v_lshl_add_u64 v[2:3], v[12:13], 0, s[6:7]
	s_add_i32 m0, s71, 0x1e000
	s_and_b32 s9, s9, 3
	global_load_lds_dwordx4 v[2:3], off
	v_and_b32_e32 v204, 15, v20
	v_lshlrev_b32_e32 v21, 4, v1
	v_lshlrev_b32_e32 v20, 2, v20
	s_lshr_b32 s75, s64, 6
	v_lshl_or_b32 v21, v204, 6, v21
	s_lshl_b32 s10, s8, 13
	v_and_b32_e32 v20, 32, v20
	s_lshl_b32 s11, s9, 12
	s_lshl_b32 s76, s8, 6
	v_bitop3_b32 v22, v21, s10, v20 bitop3:0xde
	s_lshl_b32 s10, s9, 5
	v_bitop3_b32 v205, v21, s11, v20 bitop3:0xde
	s_add_i32 s79, s75, -2
	s_lshl_b32 s8, s8, 11
	s_lshl_b32 s11, s9, 9
	s_cmp_eq_u32 s9, 0
	s_cselect_b64 s[42:43], -1, 0
	s_lshl_b32 s96, s57, 3
	v_cvt_f32_u32_e32 v2, s96
	s_lshl_b32 s82, s9, 6
	s_lshr_b32 s9, s38, 3
	v_writelane_b32 v240, s9, 24
	v_rcp_iflag_f32_e32 v2, v2
	s_add_i32 s9, s9, 1
	v_writelane_b32 v240, s9, 15
	s_add_i32 s8, s8, 0
	v_mul_f32_e32 v2, 0x4f7ffffe, v2
	v_cvt_u32_f32_e32 v2, v2
	s_add_i32 s97, s8, s11
	s_sub_i32 s8, 0, s96
	v_mov_b32_e32 v3, v0
	v_readfirstlane_b32 s9, v2
	v_add_u32_e32 v2, v16, v14
	v_add_lshl_u32 v2, v2, v15, 1
	s_waitcnt vmcnt(6)
	s_mul_i32 s8, s8, s9
	v_lshl_add_u64 v[154:155], s[92:93], 0, v[2:3]
	v_add_u32_e32 v2, v19, v17
	s_mul_hi_u32 s8, s9, s8
	v_add_lshl_u32 v2, v2, v18, 1
	s_mov_b32 s80, 0
	s_or_b32 s81, s10, 0xfffffd00
	s_mov_b32 s39, s93
	s_and_b32 s90, s38, 7
	s_add_i32 s97, s97, 0x20000
	s_add_i32 s68, s9, s8
	v_lshl_add_u64 v[156:157], s[92:93], 0, v[2:3]
	s_mov_b32 s14, -1
	v_add_u32_e32 v206, 0, v22
	s_barrier
	v_writelane_b32 v240, s57, 22
	v_add_u32_e32 v248, 0x10000, v205
	s_branch .LBB0_336

.LBB0_346:
	s_add_u32 s0, s0, 0x80
	s_addc_u32 s1, s1, 0
	s_add_u32 s12, s4, 0x100
	s_addc_u32 s13, s5, 0
	s_mov_b32 s4, 0
	s_waitcnt lgkmcnt(0)
	s_waitcnt vmcnt(0)
	s_add_i32 s15, s4, 2
	s_add_u32 s10, s0, 0x80
	s_addc_u32 s5, s1, 0
	s_add_i32 s16, 0, 0x10000
	ds_read_b128 v[130:133], v248
	ds_read_b128 v[134:137], v248 offset:1024
	ds_read_b128 v[138:141], v248 offset:2048
	ds_read_b128 v[142:145], v248 offset:3072
	s_cmp_eq_u32 s79, s4
	s_cselect_b32 s4, s44, s10
	s_cselect_b32 s5, s45, s5
	s_cselect_b32 s11, s47, s13
	s_cselect_b32 s10, s46, s12
	v_lshl_add_u64 v[212:213], s[0:1], 0, v[154:155]
	s_add_i32 m0, s71, 0xc000
	ds_read_b128 v[158:161], v206
	ds_read_b128 v[162:165], v206 offset:1024
	ds_read_b128 v[166:169], v206 offset:2048
	ds_read_b128 v[170:173], v206 offset:3072
	ds_read_b128 v[174:177], v206 offset:4096
	ds_read_b128 v[178:181], v206 offset:5120
	ds_read_b128 v[182:185], v206 offset:6144
	ds_read_b128 v[208:211], v206 offset:7168
	global_load_lds_dwordx4 v[212:213], off
	v_lshl_add_u64 v[212:213], s[0:1], 0, v[156:157]
	s_add_i32 m0, s71, 0xe000
	s_nop 0
	global_load_lds_dwordx4 v[212:213], off
	s_waitcnt lgkmcnt(8)
	s_barrier
	s_waitcnt lgkmcnt(0)
	v_mfma_f32_16x16x32_bf16 v[126:129], v[130:133], v[158:161], 0
	v_mfma_f32_16x16x32_bf16 v[122:125], v[138:141], v[158:161], 0
	v_mfma_f32_16x16x32_bf16 v[110:113], v[130:133], v[166:169], 0
	v_mfma_f32_16x16x32_bf16 v[106:109], v[138:141], v[166:169], 0
	v_mfma_f32_16x16x32_bf16 v[94:97], v[130:133], v[174:177], 0
	v_mfma_f32_16x16x32_bf16 v[90:93], v[138:141], v[174:177], 0
	v_mfma_f32_16x16x32_bf16 v[78:81], v[130:133], v[182:185], 0
	v_mfma_f32_16x16x32_bf16 v[74:77], v[138:141], v[182:185], 0
	v_mfma_f32_16x16x32_bf16 v[126:129], v[134:137], v[162:165], v[126:129]
	v_mfma_f32_16x16x32_bf16 v[122:125], v[142:145], v[162:165], v[122:125]
	v_mfma_f32_16x16x32_bf16 v[110:113], v[134:137], v[170:173], v[110:113]
	v_mfma_f32_16x16x32_bf16 v[106:109], v[142:145], v[170:173], v[106:109]
	v_mfma_f32_16x16x32_bf16 v[94:97], v[134:137], v[178:181], v[94:97]
	v_mfma_f32_16x16x32_bf16 v[90:93], v[142:145], v[178:181], v[90:93]
	v_mfma_f32_16x16x32_bf16 v[78:81], v[134:137], v[208:211], v[78:81]
	v_mfma_f32_16x16x32_bf16 v[74:77], v[142:145], v[208:211], v[74:77]
	s_barrier
	s_add_i32 s17, 0, 0x14000
	s_add_i32 s16, s16, s70
	s_add_u32 s2, s10, s6
	s_addc_u32 s3, s11, s7
	s_mov_b32 m0, s16
	ds_read_b128 v[212:215], v248 offset:16384
	ds_read_b128 v[216:219], v248 offset:17408
	ds_read_b128 v[220:223], v248 offset:18432
	ds_read_b128 v[224:227], v248 offset:19456
	global_load_lds_dwordx4 v148, s[10:11]
	s_add_i32 m0, s16, 0x2000
	s_nop 0
	global_load_lds_dwordx4 v152, s[10:11]
	s_barrier
	s_waitcnt lgkmcnt(0)
	v_mfma_f32_16x16x32_bf16 v[118:121], v[212:215], v[158:161], 0
	v_mfma_f32_16x16x32_bf16 v[114:117], v[220:223], v[158:161], 0
	v_mfma_f32_16x16x32_bf16 v[102:105], v[212:215], v[166:169], 0
	v_mfma_f32_16x16x32_bf16 v[98:101], v[220:223], v[166:169], 0
	v_mfma_f32_16x16x32_bf16 v[86:89], v[212:215], v[174:177], 0
	v_mfma_f32_16x16x32_bf16 v[82:85], v[220:223], v[174:177], 0
	v_mfma_f32_16x16x32_bf16 v[70:73], v[212:215], v[182:185], 0
	v_mfma_f32_16x16x32_bf16 v[66:69], v[220:223], v[182:185], 0
	v_mfma_f32_16x16x32_bf16 v[118:121], v[216:219], v[162:165], v[118:121]
	v_mfma_f32_16x16x32_bf16 v[114:117], v[224:227], v[162:165], v[114:117]
	v_mfma_f32_16x16x32_bf16 v[102:105], v[216:219], v[170:173], v[102:105]
	v_mfma_f32_16x16x32_bf16 v[98:101], v[224:227], v[170:173], v[98:101]
	v_mfma_f32_16x16x32_bf16 v[86:89], v[216:219], v[178:181], v[86:89]
	v_mfma_f32_16x16x32_bf16 v[82:85], v[224:227], v[178:181], v[82:85]
	v_mfma_f32_16x16x32_bf16 v[70:73], v[216:219], v[208:211], v[70:73]
	v_mfma_f32_16x16x32_bf16 v[66:69], v[224:227], v[208:211], v[66:69]
	s_barrier
	s_mov_b32 m0, s71
	s_add_u32 s98, s4, s6
	s_addc_u32 s99, s5, s7
	ds_read_b128 v[158:161], v206 offset:16384
	ds_read_b128 v[162:165], v206 offset:17408
	ds_read_b128 v[166:169], v206 offset:18432
	ds_read_b128 v[170:173], v206 offset:19456
	ds_read_b128 v[174:177], v206 offset:20480
	ds_read_b128 v[178:181], v206 offset:21504
	ds_read_b128 v[182:185], v206 offset:22528
	ds_read_b128 v[208:211], v206 offset:23552
	global_load_lds_dwordx4 v146, s[4:5]
	s_mov_b32 m0, s72
	s_nop 0
	global_load_lds_dwordx4 v150, s[4:5]
	s_barrier
	s_waitcnt lgkmcnt(0)
	v_mfma_f32_16x16x32_bf16 v[62:65], v[130:133], v[158:161], 0
	v_mfma_f32_16x16x32_bf16 v[58:61], v[138:141], v[158:161], 0
	v_mfma_f32_16x16x32_bf16 v[46:49], v[130:133], v[166:169], 0
	v_mfma_f32_16x16x32_bf16 v[42:45], v[138:141], v[166:169], 0
	v_mfma_f32_16x16x32_bf16 v[30:33], v[130:133], v[174:177], 0
	v_mfma_f32_16x16x32_bf16 v[26:29], v[138:141], v[174:177], 0
	v_mfma_f32_16x16x32_bf16 v[14:17], v[130:133], v[182:185], 0
	v_mfma_f32_16x16x32_bf16 v[10:13], v[138:141], v[182:185], 0
	v_mfma_f32_16x16x32_bf16 v[62:65], v[134:137], v[162:165], v[62:65]
	v_mfma_f32_16x16x32_bf16 v[58:61], v[142:145], v[162:165], v[58:61]
	v_mfma_f32_16x16x32_bf16 v[46:49], v[134:137], v[170:173], v[46:49]
	v_mfma_f32_16x16x32_bf16 v[42:45], v[142:145], v[170:173], v[42:45]
	v_mfma_f32_16x16x32_bf16 v[30:33], v[134:137], v[178:181], v[30:33]
	v_mfma_f32_16x16x32_bf16 v[26:29], v[142:145], v[178:181], v[26:29]
	v_mfma_f32_16x16x32_bf16 v[14:17], v[134:137], v[208:211], v[14:17]
	v_mfma_f32_16x16x32_bf16 v[10:13], v[142:145], v[208:211], v[10:13]
	s_barrier
	s_add_u32 s10, s10, s92
	s_addc_u32 s11, s11, 0
	s_add_i32 s16, s17, s70
	v_lshl_add_u64 v[236:237], s[10:11], 0, v[148:149]
	s_mov_b32 m0, s16
	v_lshl_add_u64 v[238:239], s[10:11], 0, v[152:153]
	global_load_lds_dwordx4 v[236:237], off
	s_add_i32 m0, s16, 0x2000
	s_nop 0
	global_load_lds_dwordx4 v[238:239], off
	s_waitcnt vmcnt(6)
	s_barrier
	v_mfma_f32_16x16x32_bf16 v[54:57], v[212:215], v[158:161], 0
	v_mfma_f32_16x16x32_bf16 v[50:53], v[220:223], v[158:161], 0
	v_mfma_f32_16x16x32_bf16 v[38:41], v[212:215], v[166:169], 0
	v_mfma_f32_16x16x32_bf16 v[34:37], v[220:223], v[166:169], 0
	v_mfma_f32_16x16x32_bf16 v[22:25], v[212:215], v[174:177], 0
	v_mfma_f32_16x16x32_bf16 v[18:21], v[220:223], v[174:177], 0
	v_mfma_f32_16x16x32_bf16 v[6:9], v[212:215], v[182:185], 0
	v_mfma_f32_16x16x32_bf16 v[2:5], v[220:223], v[182:185], 0
	v_mfma_f32_16x16x32_bf16 v[54:57], v[216:219], v[162:165], v[54:57]
	v_mfma_f32_16x16x32_bf16 v[50:53], v[224:227], v[162:165], v[50:53]
	v_mfma_f32_16x16x32_bf16 v[38:41], v[216:219], v[170:173], v[38:41]
	v_mfma_f32_16x16x32_bf16 v[34:37], v[224:227], v[170:173], v[34:37]
	v_mfma_f32_16x16x32_bf16 v[22:25], v[216:219], v[178:181], v[22:25]
	v_mfma_f32_16x16x32_bf16 v[18:21], v[224:227], v[178:181], v[18:21]
	v_mfma_f32_16x16x32_bf16 v[6:9], v[216:219], v[208:211], v[6:9]
	v_mfma_f32_16x16x32_bf16 v[2:5], v[224:227], v[208:211], v[2:5]
	s_barrier
	s_add_i32 s10, 0, 0x18000
	ds_read_b128 v[130:133], v248 offset:32768
	ds_read_b128 v[134:137], v248 offset:33792
	ds_read_b128 v[138:141], v248 offset:34816
	ds_read_b128 v[142:145], v248 offset:35840
	s_add_u32 s4, s4, s92
	s_addc_u32 s5, s5, 0
	s_mov_b32 m0, s73
	ds_read_b128 v[158:161], v206 offset:32768
	ds_read_b128 v[162:165], v206 offset:33792
	ds_read_b128 v[166:169], v206 offset:34816
	ds_read_b128 v[170:173], v206 offset:35840
	ds_read_b128 v[174:177], v206 offset:36864
	ds_read_b128 v[178:181], v206 offset:37888
	ds_read_b128 v[182:185], v206 offset:38912
	ds_read_b128 v[208:211], v206 offset:39936
	global_load_lds_dwordx4 v146, s[4:5]
	s_mov_b32 m0, s74
	s_nop 0
	global_load_lds_dwordx4 v150, s[4:5]
	s_waitcnt lgkmcnt(8)
	s_barrier
	s_waitcnt lgkmcnt(0)
	v_mfma_f32_16x16x32_bf16 v[126:129], v[130:133], v[158:161], v[126:129]
	v_mfma_f32_16x16x32_bf16 v[122:125], v[138:141], v[158:161], v[122:125]
	v_mfma_f32_16x16x32_bf16 v[110:113], v[130:133], v[166:169], v[110:113]
	v_mfma_f32_16x16x32_bf16 v[106:109], v[138:141], v[166:169], v[106:109]
	v_mfma_f32_16x16x32_bf16 v[94:97], v[130:133], v[174:177], v[94:97]
	v_mfma_f32_16x16x32_bf16 v[90:93], v[138:141], v[174:177], v[90:93]
	v_mfma_f32_16x16x32_bf16 v[78:81], v[130:133], v[182:185], v[78:81]
	v_mfma_f32_16x16x32_bf16 v[74:77], v[138:141], v[182:185], v[74:77]
	v_mfma_f32_16x16x32_bf16 v[126:129], v[134:137], v[162:165], v[126:129]
	v_mfma_f32_16x16x32_bf16 v[122:125], v[142:145], v[162:165], v[122:125]
	v_mfma_f32_16x16x32_bf16 v[110:113], v[134:137], v[170:173], v[110:113]
	v_mfma_f32_16x16x32_bf16 v[106:109], v[142:145], v[170:173], v[106:109]
	v_mfma_f32_16x16x32_bf16 v[94:97], v[134:137], v[178:181], v[94:97]
	v_mfma_f32_16x16x32_bf16 v[90:93], v[142:145], v[178:181], v[90:93]
	v_mfma_f32_16x16x32_bf16 v[78:81], v[134:137], v[208:211], v[78:81]
	v_mfma_f32_16x16x32_bf16 v[74:77], v[142:145], v[208:211], v[74:77]
	s_barrier
	s_add_i32 s4, 0, 0x1c000
	s_add_i32 s5, s10, s70
	s_mov_b32 m0, s5
	ds_read_b128 v[212:215], v248 offset:49152
	ds_read_b128 v[216:219], v248 offset:50176
	ds_read_b128 v[220:223], v248 offset:51200
	ds_read_b128 v[224:227], v248 offset:52224
	global_load_lds_dwordx4 v148, s[2:3]
	s_add_i32 m0, s5, 0x2000
	s_nop 0
	global_load_lds_dwordx4 v152, s[2:3]
	s_barrier
	s_waitcnt lgkmcnt(0)
	v_mfma_f32_16x16x32_bf16 v[118:121], v[212:215], v[158:161], v[118:121]
	v_mfma_f32_16x16x32_bf16 v[114:117], v[220:223], v[158:161], v[114:117]
	v_mfma_f32_16x16x32_bf16 v[102:105], v[212:215], v[166:169], v[102:105]
	v_mfma_f32_16x16x32_bf16 v[98:101], v[220:223], v[166:169], v[98:101]
	v_mfma_f32_16x16x32_bf16 v[86:89], v[212:215], v[174:177], v[86:89]
	v_mfma_f32_16x16x32_bf16 v[82:85], v[220:223], v[174:177], v[82:85]
	v_mfma_f32_16x16x32_bf16 v[70:73], v[212:215], v[182:185], v[70:73]
	v_mfma_f32_16x16x32_bf16 v[66:69], v[220:223], v[182:185], v[66:69]
	v_mfma_f32_16x16x32_bf16 v[118:121], v[216:219], v[162:165], v[118:121]
	v_mfma_f32_16x16x32_bf16 v[114:117], v[224:227], v[162:165], v[114:117]
	v_mfma_f32_16x16x32_bf16 v[102:105], v[216:219], v[170:173], v[102:105]
	v_mfma_f32_16x16x32_bf16 v[98:101], v[224:227], v[170:173], v[98:101]
	v_mfma_f32_16x16x32_bf16 v[86:89], v[216:219], v[178:181], v[86:89]
	v_mfma_f32_16x16x32_bf16 v[82:85], v[224:227], v[178:181], v[82:85]
	v_mfma_f32_16x16x32_bf16 v[70:73], v[216:219], v[208:211], v[70:73]
	v_mfma_f32_16x16x32_bf16 v[66:69], v[224:227], v[208:211], v[66:69]
	s_barrier
	s_mov_b32 m0, s77
	ds_read_b128 v[158:161], v206 offset:49152
	ds_read_b128 v[162:165], v206 offset:50176
	ds_read_b128 v[166:169], v206 offset:51200
	ds_read_b128 v[170:173], v206 offset:52224
	ds_read_b128 v[174:177], v206 offset:53248
	ds_read_b128 v[178:181], v206 offset:54272
	ds_read_b128 v[182:185], v206 offset:55296
	ds_read_b128 v[208:211], v206 offset:56320
	global_load_lds_dwordx4 v146, s[98:99]
	s_mov_b32 m0, s78
	s_nop 0
	global_load_lds_dwordx4 v150, s[98:99]
	s_barrier
	s_waitcnt lgkmcnt(0)
	v_mfma_f32_16x16x32_bf16 v[62:65], v[130:133], v[158:161], v[62:65]
	v_mfma_f32_16x16x32_bf16 v[58:61], v[138:141], v[158:161], v[58:61]
	v_mfma_f32_16x16x32_bf16 v[46:49], v[130:133], v[166:169], v[46:49]
	v_mfma_f32_16x16x32_bf16 v[42:45], v[138:141], v[166:169], v[42:45]
	v_mfma_f32_16x16x32_bf16 v[30:33], v[130:133], v[174:177], v[30:33]
	v_mfma_f32_16x16x32_bf16 v[26:29], v[138:141], v[174:177], v[26:29]
	v_mfma_f32_16x16x32_bf16 v[14:17], v[130:133], v[182:185], v[14:17]
	v_mfma_f32_16x16x32_bf16 v[10:13], v[138:141], v[182:185], v[10:13]
	v_mfma_f32_16x16x32_bf16 v[62:65], v[134:137], v[162:165], v[62:65]
	v_mfma_f32_16x16x32_bf16 v[58:61], v[142:145], v[162:165], v[58:61]
	v_mfma_f32_16x16x32_bf16 v[46:49], v[134:137], v[170:173], v[46:49]
	v_mfma_f32_16x16x32_bf16 v[42:45], v[142:145], v[170:173], v[42:45]
	v_mfma_f32_16x16x32_bf16 v[30:33], v[134:137], v[178:181], v[30:33]
	v_mfma_f32_16x16x32_bf16 v[26:29], v[142:145], v[178:181], v[26:29]
	v_mfma_f32_16x16x32_bf16 v[14:17], v[134:137], v[208:211], v[14:17]
	v_mfma_f32_16x16x32_bf16 v[10:13], v[142:145], v[208:211], v[10:13]
	s_barrier
	s_add_i32 s4, s4, s70
	v_lshl_add_u64 v[130:131], v[236:237], 0, s[6:7]
	s_mov_b32 m0, s4
	s_nop 0
	global_load_lds_dwordx4 v[130:131], off
	v_lshl_add_u64 v[130:131], v[238:239], 0, s[6:7]
	s_add_i32 m0, s4, 0x2000
	s_nop 0
	global_load_lds_dwordx4 v[130:131], off
	s_add_u32 s0, s0, 0x100
	s_addc_u32 s1, s1, 0
	s_add_u32 s12, s12, 0x100
	s_addc_u32 s13, s13, 0
	s_cmp_ge_u32 s15, s75
	s_mov_b32 s4, s15
	s_waitcnt vmcnt(6)
	s_barrier
	v_mfma_f32_16x16x32_bf16 v[54:57], v[212:215], v[158:161], v[54:57]
	v_mfma_f32_16x16x32_bf16 v[50:53], v[220:223], v[158:161], v[50:53]
	v_mfma_f32_16x16x32_bf16 v[38:41], v[212:215], v[166:169], v[38:41]
	v_mfma_f32_16x16x32_bf16 v[34:37], v[220:223], v[166:169], v[34:37]
	v_mfma_f32_16x16x32_bf16 v[22:25], v[212:215], v[174:177], v[22:25]
	v_mfma_f32_16x16x32_bf16 v[18:21], v[220:223], v[174:177], v[18:21]
	v_mfma_f32_16x16x32_bf16 v[6:9], v[212:215], v[182:185], v[6:9]
	v_mfma_f32_16x16x32_bf16 v[2:5], v[220:223], v[182:185], v[2:5]
	v_mfma_f32_16x16x32_bf16 v[54:57], v[216:219], v[162:165], v[54:57]
	v_mfma_f32_16x16x32_bf16 v[50:53], v[224:227], v[162:165], v[50:53]
	v_mfma_f32_16x16x32_bf16 v[38:41], v[216:219], v[170:173], v[38:41]
	v_mfma_f32_16x16x32_bf16 v[34:37], v[224:227], v[170:173], v[34:37]
	v_mfma_f32_16x16x32_bf16 v[22:25], v[216:219], v[178:181], v[22:25]
	v_mfma_f32_16x16x32_bf16 v[18:21], v[224:227], v[178:181], v[18:21]
	v_mfma_f32_16x16x32_bf16 v[6:9], v[216:219], v[208:211], v[6:9]
	v_mfma_f32_16x16x32_bf16 v[2:5], v[224:227], v[208:211], v[2:5]
	s_barrier
	s_cbranch_scc1 .Lkexit_347
.LBB0_347:
	s_add_i32 s15, s4, 2
	s_add_u32 s10, s0, 0x80
	s_addc_u32 s5, s1, 0
	s_add_i32 s16, 0, 0x10000
	ds_read_b128 v[130:133], v248
	ds_read_b128 v[134:137], v248 offset:1024
	ds_read_b128 v[138:141], v248 offset:2048
	ds_read_b128 v[142:145], v248 offset:3072
	s_cmp_eq_u32 s79, s4
	s_cselect_b32 s4, s44, s10
	s_cselect_b32 s5, s45, s5
	s_cselect_b32 s11, s47, s13
	s_cselect_b32 s10, s46, s12
	v_lshl_add_u64 v[212:213], s[0:1], 0, v[154:155]
	s_add_i32 m0, s71, 0xc000
	ds_read_b128 v[158:161], v206
	ds_read_b128 v[162:165], v206 offset:1024
	ds_read_b128 v[166:169], v206 offset:2048
	ds_read_b128 v[170:173], v206 offset:3072
	ds_read_b128 v[174:177], v206 offset:4096
	ds_read_b128 v[178:181], v206 offset:5120
	ds_read_b128 v[182:185], v206 offset:6144
	ds_read_b128 v[208:211], v206 offset:7168
	global_load_lds_dwordx4 v[212:213], off
	v_lshl_add_u64 v[212:213], s[0:1], 0, v[156:157]
	s_add_i32 m0, s71, 0xe000
	s_nop 0
	global_load_lds_dwordx4 v[212:213], off
	s_waitcnt lgkmcnt(8)
	s_barrier
	s_waitcnt lgkmcnt(0)
	v_mfma_f32_16x16x32_bf16 v[126:129], v[130:133], v[158:161], v[126:129]
	v_mfma_f32_16x16x32_bf16 v[122:125], v[138:141], v[158:161], v[122:125]
	v_mfma_f32_16x16x32_bf16 v[110:113], v[130:133], v[166:169], v[110:113]
	v_mfma_f32_16x16x32_bf16 v[106:109], v[138:141], v[166:169], v[106:109]
	v_mfma_f32_16x16x32_bf16 v[94:97], v[130:133], v[174:177], v[94:97]
	v_mfma_f32_16x16x32_bf16 v[90:93], v[138:141], v[174:177], v[90:93]
	v_mfma_f32_16x16x32_bf16 v[78:81], v[130:133], v[182:185], v[78:81]
	v_mfma_f32_16x16x32_bf16 v[74:77], v[138:141], v[182:185], v[74:77]
	v_mfma_f32_16x16x32_bf16 v[126:129], v[134:137], v[162:165], v[126:129]
	v_mfma_f32_16x16x32_bf16 v[122:125], v[142:145], v[162:165], v[122:125]
	v_mfma_f32_16x16x32_bf16 v[110:113], v[134:137], v[170:173], v[110:113]
	v_mfma_f32_16x16x32_bf16 v[106:109], v[142:145], v[170:173], v[106:109]
	v_mfma_f32_16x16x32_bf16 v[94:97], v[134:137], v[178:181], v[94:97]
	v_mfma_f32_16x16x32_bf16 v[90:93], v[142:145], v[178:181], v[90:93]
	v_mfma_f32_16x16x32_bf16 v[78:81], v[134:137], v[208:211], v[78:81]
	v_mfma_f32_16x16x32_bf16 v[74:77], v[142:145], v[208:211], v[74:77]
	s_barrier
	s_add_i32 s17, 0, 0x14000
	s_add_i32 s16, s16, s70
	s_add_u32 s2, s10, s6
	s_addc_u32 s3, s11, s7
	s_mov_b32 m0, s16
	ds_read_b128 v[212:215], v248 offset:16384
	ds_read_b128 v[216:219], v248 offset:17408
	ds_read_b128 v[220:223], v248 offset:18432
	ds_read_b128 v[224:227], v248 offset:19456
	global_load_lds_dwordx4 v148, s[10:11]
	s_add_i32 m0, s16, 0x2000
	s_nop 0
	global_load_lds_dwordx4 v152, s[10:11]
	s_barrier
	s_waitcnt lgkmcnt(0)
	v_mfma_f32_16x16x32_bf16 v[118:121], v[212:215], v[158:161], v[118:121]
	v_mfma_f32_16x16x32_bf16 v[114:117], v[220:223], v[158:161], v[114:117]
	v_mfma_f32_16x16x32_bf16 v[102:105], v[212:215], v[166:169], v[102:105]
	v_mfma_f32_16x16x32_bf16 v[98:101], v[220:223], v[166:169], v[98:101]
	v_mfma_f32_16x16x32_bf16 v[86:89], v[212:215], v[174:177], v[86:89]
	v_mfma_f32_16x16x32_bf16 v[82:85], v[220:223], v[174:177], v[82:85]
	v_mfma_f32_16x16x32_bf16 v[70:73], v[212:215], v[182:185], v[70:73]
	v_mfma_f32_16x16x32_bf16 v[66:69], v[220:223], v[182:185], v[66:69]
	v_mfma_f32_16x16x32_bf16 v[118:121], v[216:219], v[162:165], v[118:121]
	v_mfma_f32_16x16x32_bf16 v[114:117], v[224:227], v[162:165], v[114:117]
	v_mfma_f32_16x16x32_bf16 v[102:105], v[216:219], v[170:173], v[102:105]
	v_mfma_f32_16x16x32_bf16 v[98:101], v[224:227], v[170:173], v[98:101]
	v_mfma_f32_16x16x32_bf16 v[86:89], v[216:219], v[178:181], v[86:89]
	v_mfma_f32_16x16x32_bf16 v[82:85], v[224:227], v[178:181], v[82:85]
	v_mfma_f32_16x16x32_bf16 v[70:73], v[216:219], v[208:211], v[70:73]
	v_mfma_f32_16x16x32_bf16 v[66:69], v[224:227], v[208:211], v[66:69]
	s_barrier
	s_mov_b32 m0, s71
	s_add_u32 s98, s4, s6
	s_addc_u32 s99, s5, s7
	ds_read_b128 v[158:161], v206 offset:16384
	ds_read_b128 v[162:165], v206 offset:17408
	ds_read_b128 v[166:169], v206 offset:18432
	ds_read_b128 v[170:173], v206 offset:19456
	ds_read_b128 v[174:177], v206 offset:20480
	ds_read_b128 v[178:181], v206 offset:21504
	ds_read_b128 v[182:185], v206 offset:22528
	ds_read_b128 v[208:211], v206 offset:23552
	global_load_lds_dwordx4 v146, s[4:5]
	s_mov_b32 m0, s72
	s_nop 0
	global_load_lds_dwordx4 v150, s[4:5]
	s_barrier
	s_waitcnt lgkmcnt(0)
	v_mfma_f32_16x16x32_bf16 v[62:65], v[130:133], v[158:161], v[62:65]
	v_mfma_f32_16x16x32_bf16 v[58:61], v[138:141], v[158:161], v[58:61]
	v_mfma_f32_16x16x32_bf16 v[46:49], v[130:133], v[166:169], v[46:49]
	v_mfma_f32_16x16x32_bf16 v[42:45], v[138:141], v[166:169], v[42:45]
	v_mfma_f32_16x16x32_bf16 v[30:33], v[130:133], v[174:177], v[30:33]
	v_mfma_f32_16x16x32_bf16 v[26:29], v[138:141], v[174:177], v[26:29]
	v_mfma_f32_16x16x32_bf16 v[14:17], v[130:133], v[182:185], v[14:17]
	v_mfma_f32_16x16x32_bf16 v[10:13], v[138:141], v[182:185], v[10:13]
	v_mfma_f32_16x16x32_bf16 v[62:65], v[134:137], v[162:165], v[62:65]
	v_mfma_f32_16x16x32_bf16 v[58:61], v[142:145], v[162:165], v[58:61]
	v_mfma_f32_16x16x32_bf16 v[46:49], v[134:137], v[170:173], v[46:49]
	v_mfma_f32_16x16x32_bf16 v[42:45], v[142:145], v[170:173], v[42:45]
	v_mfma_f32_16x16x32_bf16 v[30:33], v[134:137], v[178:181], v[30:33]
	v_mfma_f32_16x16x32_bf16 v[26:29], v[142:145], v[178:181], v[26:29]
	v_mfma_f32_16x16x32_bf16 v[14:17], v[134:137], v[208:211], v[14:17]
	v_mfma_f32_16x16x32_bf16 v[10:13], v[142:145], v[208:211], v[10:13]
	s_barrier
	s_add_u32 s10, s10, s92
	s_addc_u32 s11, s11, 0
	s_add_i32 s16, s17, s70
	v_lshl_add_u64 v[236:237], s[10:11], 0, v[148:149]
	s_mov_b32 m0, s16
	v_lshl_add_u64 v[238:239], s[10:11], 0, v[152:153]
	global_load_lds_dwordx4 v[236:237], off
	s_add_i32 m0, s16, 0x2000
	s_nop 0
	global_load_lds_dwordx4 v[238:239], off
	s_waitcnt vmcnt(6)
	s_barrier
	v_mfma_f32_16x16x32_bf16 v[54:57], v[212:215], v[158:161], v[54:57]
	v_mfma_f32_16x16x32_bf16 v[50:53], v[220:223], v[158:161], v[50:53]
	v_mfma_f32_16x16x32_bf16 v[38:41], v[212:215], v[166:169], v[38:41]
	v_mfma_f32_16x16x32_bf16 v[34:37], v[220:223], v[166:169], v[34:37]
	v_mfma_f32_16x16x32_bf16 v[22:25], v[212:215], v[174:177], v[22:25]
	v_mfma_f32_16x16x32_bf16 v[18:21], v[220:223], v[174:177], v[18:21]
	v_mfma_f32_16x16x32_bf16 v[6:9], v[212:215], v[182:185], v[6:9]
	v_mfma_f32_16x16x32_bf16 v[2:5], v[220:223], v[182:185], v[2:5]
	v_mfma_f32_16x16x32_bf16 v[54:57], v[216:219], v[162:165], v[54:57]
	v_mfma_f32_16x16x32_bf16 v[50:53], v[224:227], v[162:165], v[50:53]
	v_mfma_f32_16x16x32_bf16 v[38:41], v[216:219], v[170:173], v[38:41]
	v_mfma_f32_16x16x32_bf16 v[34:37], v[224:227], v[170:173], v[34:37]
	v_mfma_f32_16x16x32_bf16 v[22:25], v[216:219], v[178:181], v[22:25]
	v_mfma_f32_16x16x32_bf16 v[18:21], v[224:227], v[178:181], v[18:21]
	v_mfma_f32_16x16x32_bf16 v[6:9], v[216:219], v[208:211], v[6:9]
	v_mfma_f32_16x16x32_bf16 v[2:5], v[224:227], v[208:211], v[2:5]
	s_barrier
	s_add_i32 s10, 0, 0x18000
	ds_read_b128 v[130:133], v248 offset:32768
	ds_read_b128 v[134:137], v248 offset:33792
	ds_read_b128 v[138:141], v248 offset:34816
	ds_read_b128 v[142:145], v248 offset:35840
	s_add_u32 s4, s4, s92
	s_addc_u32 s5, s5, 0
	s_mov_b32 m0, s73
	ds_read_b128 v[158:161], v206 offset:32768
	ds_read_b128 v[162:165], v206 offset:33792
	ds_read_b128 v[166:169], v206 offset:34816
	ds_read_b128 v[170:173], v206 offset:35840
	ds_read_b128 v[174:177], v206 offset:36864
	ds_read_b128 v[178:181], v206 offset:37888
	ds_read_b128 v[182:185], v206 offset:38912
	ds_read_b128 v[208:211], v206 offset:39936
	global_load_lds_dwordx4 v146, s[4:5]
	s_mov_b32 m0, s74
	s_nop 0
	global_load_lds_dwordx4 v150, s[4:5]
	s_waitcnt lgkmcnt(8)
	s_barrier
	s_waitcnt lgkmcnt(0)
	v_mfma_f32_16x16x32_bf16 v[126:129], v[130:133], v[158:161], v[126:129]
	v_mfma_f32_16x16x32_bf16 v[122:125], v[138:141], v[158:161], v[122:125]
	v_mfma_f32_16x16x32_bf16 v[110:113], v[130:133], v[166:169], v[110:113]
	v_mfma_f32_16x16x32_bf16 v[106:109], v[138:141], v[166:169], v[106:109]
	v_mfma_f32_16x16x32_bf16 v[94:97], v[130:133], v[174:177], v[94:97]
	v_mfma_f32_16x16x32_bf16 v[90:93], v[138:141], v[174:177], v[90:93]
	v_mfma_f32_16x16x32_bf16 v[78:81], v[130:133], v[182:185], v[78:81]
	v_mfma_f32_16x16x32_bf16 v[74:77], v[138:141], v[182:185], v[74:77]
	v_mfma_f32_16x16x32_bf16 v[126:129], v[134:137], v[162:165], v[126:129]
	v_mfma_f32_16x16x32_bf16 v[122:125], v[142:145], v[162:165], v[122:125]
	v_mfma_f32_16x16x32_bf16 v[110:113], v[134:137], v[170:173], v[110:113]
	v_mfma_f32_16x16x32_bf16 v[106:109], v[142:145], v[170:173], v[106:109]
	v_mfma_f32_16x16x32_bf16 v[94:97], v[134:137], v[178:181], v[94:97]
	v_mfma_f32_16x16x32_bf16 v[90:93], v[142:145], v[178:181], v[90:93]
	v_mfma_f32_16x16x32_bf16 v[78:81], v[134:137], v[208:211], v[78:81]
	v_mfma_f32_16x16x32_bf16 v[74:77], v[142:145], v[208:211], v[74:77]
	s_barrier
	s_add_i32 s4, 0, 0x1c000
	s_add_i32 s5, s10, s70
	s_mov_b32 m0, s5
	ds_read_b128 v[212:215], v248 offset:49152
	ds_read_b128 v[216:219], v248 offset:50176
	ds_read_b128 v[220:223], v248 offset:51200
	ds_read_b128 v[224:227], v248 offset:52224
	global_load_lds_dwordx4 v148, s[2:3]
	s_add_i32 m0, s5, 0x2000
	s_nop 0
	global_load_lds_dwordx4 v152, s[2:3]
	s_barrier
	s_waitcnt lgkmcnt(0)
	v_mfma_f32_16x16x32_bf16 v[118:121], v[212:215], v[158:161], v[118:121]
	v_mfma_f32_16x16x32_bf16 v[114:117], v[220:223], v[158:161], v[114:117]
	v_mfma_f32_16x16x32_bf16 v[102:105], v[212:215], v[166:169], v[102:105]
	v_mfma_f32_16x16x32_bf16 v[98:101], v[220:223], v[166:169], v[98:101]
	v_mfma_f32_16x16x32_bf16 v[86:89], v[212:215], v[174:177], v[86:89]
	v_mfma_f32_16x16x32_bf16 v[82:85], v[220:223], v[174:177], v[82:85]
	v_mfma_f32_16x16x32_bf16 v[70:73], v[212:215], v[182:185], v[70:73]
	v_mfma_f32_16x16x32_bf16 v[66:69], v[220:223], v[182:185], v[66:69]
	v_mfma_f32_16x16x32_bf16 v[118:121], v[216:219], v[162:165], v[118:121]
	v_mfma_f32_16x16x32_bf16 v[114:117], v[224:227], v[162:165], v[114:117]
	v_mfma_f32_16x16x32_bf16 v[102:105], v[216:219], v[170:173], v[102:105]
	v_mfma_f32_16x16x32_bf16 v[98:101], v[224:227], v[170:173], v[98:101]
	v_mfma_f32_16x16x32_bf16 v[86:89], v[216:219], v[178:181], v[86:89]
	v_mfma_f32_16x16x32_bf16 v[82:85], v[224:227], v[178:181], v[82:85]
	v_mfma_f32_16x16x32_bf16 v[70:73], v[216:219], v[208:211], v[70:73]
	v_mfma_f32_16x16x32_bf16 v[66:69], v[224:227], v[208:211], v[66:69]
	s_barrier
	s_mov_b32 m0, s77
	ds_read_b128 v[158:161], v206 offset:49152
	ds_read_b128 v[162:165], v206 offset:50176
	ds_read_b128 v[166:169], v206 offset:51200
	ds_read_b128 v[170:173], v206 offset:52224
	ds_read_b128 v[174:177], v206 offset:53248
	ds_read_b128 v[178:181], v206 offset:54272
	ds_read_b128 v[182:185], v206 offset:55296
	ds_read_b128 v[208:211], v206 offset:56320
	global_load_lds_dwordx4 v146, s[98:99]
	s_mov_b32 m0, s78
	s_nop 0
	global_load_lds_dwordx4 v150, s[98:99]
	s_barrier
	s_waitcnt lgkmcnt(0)
	v_mfma_f32_16x16x32_bf16 v[62:65], v[130:133], v[158:161], v[62:65]
	v_mfma_f32_16x16x32_bf16 v[58:61], v[138:141], v[158:161], v[58:61]
	v_mfma_f32_16x16x32_bf16 v[46:49], v[130:133], v[166:169], v[46:49]
	v_mfma_f32_16x16x32_bf16 v[42:45], v[138:141], v[166:169], v[42:45]
	v_mfma_f32_16x16x32_bf16 v[30:33], v[130:133], v[174:177], v[30:33]
	v_mfma_f32_16x16x32_bf16 v[26:29], v[138:141], v[174:177], v[26:29]
	v_mfma_f32_16x16x32_bf16 v[14:17], v[130:133], v[182:185], v[14:17]
	v_mfma_f32_16x16x32_bf16 v[10:13], v[138:141], v[182:185], v[10:13]
	v_mfma_f32_16x16x32_bf16 v[62:65], v[134:137], v[162:165], v[62:65]
	v_mfma_f32_16x16x32_bf16 v[58:61], v[142:145], v[162:165], v[58:61]
	v_mfma_f32_16x16x32_bf16 v[46:49], v[134:137], v[170:173], v[46:49]
	v_mfma_f32_16x16x32_bf16 v[42:45], v[142:145], v[170:173], v[42:45]
	v_mfma_f32_16x16x32_bf16 v[30:33], v[134:137], v[178:181], v[30:33]
	v_mfma_f32_16x16x32_bf16 v[26:29], v[142:145], v[178:181], v[26:29]
	v_mfma_f32_16x16x32_bf16 v[14:17], v[134:137], v[208:211], v[14:17]
	v_mfma_f32_16x16x32_bf16 v[10:13], v[142:145], v[208:211], v[10:13]
	s_barrier
	s_add_i32 s4, s4, s70
	v_lshl_add_u64 v[130:131], v[236:237], 0, s[6:7]
	s_mov_b32 m0, s4
	s_nop 0
	global_load_lds_dwordx4 v[130:131], off
	v_lshl_add_u64 v[130:131], v[238:239], 0, s[6:7]
	s_add_i32 m0, s4, 0x2000
	s_nop 0
	global_load_lds_dwordx4 v[130:131], off
	s_add_u32 s0, s0, 0x100
	s_addc_u32 s1, s1, 0
	s_add_u32 s12, s12, 0x100
	s_addc_u32 s13, s13, 0
	s_cmp_ge_u32 s15, s75
	s_mov_b32 s4, s15
	s_waitcnt vmcnt(6)
	s_barrier
	v_mfma_f32_16x16x32_bf16 v[54:57], v[212:215], v[158:161], v[54:57]
	v_mfma_f32_16x16x32_bf16 v[50:53], v[220:223], v[158:161], v[50:53]
	v_mfma_f32_16x16x32_bf16 v[38:41], v[212:215], v[166:169], v[38:41]
	v_mfma_f32_16x16x32_bf16 v[34:37], v[220:223], v[166:169], v[34:37]
	v_mfma_f32_16x16x32_bf16 v[22:25], v[212:215], v[174:177], v[22:25]
	v_mfma_f32_16x16x32_bf16 v[18:21], v[220:223], v[174:177], v[18:21]
	v_mfma_f32_16x16x32_bf16 v[6:9], v[212:215], v[182:185], v[6:9]
	v_mfma_f32_16x16x32_bf16 v[2:5], v[220:223], v[182:185], v[2:5]
	v_mfma_f32_16x16x32_bf16 v[54:57], v[216:219], v[162:165], v[54:57]
	v_mfma_f32_16x16x32_bf16 v[50:53], v[224:227], v[162:165], v[50:53]
	v_mfma_f32_16x16x32_bf16 v[38:41], v[216:219], v[170:173], v[38:41]
	v_mfma_f32_16x16x32_bf16 v[34:37], v[224:227], v[170:173], v[34:37]
	v_mfma_f32_16x16x32_bf16 v[22:25], v[216:219], v[178:181], v[22:25]
	v_mfma_f32_16x16x32_bf16 v[18:21], v[224:227], v[178:181], v[18:21]
	v_mfma_f32_16x16x32_bf16 v[6:9], v[216:219], v[208:211], v[6:9]
	v_mfma_f32_16x16x32_bf16 v[2:5], v[224:227], v[208:211], v[2:5]
	s_barrier
	s_cbranch_scc0 .LBB0_347

.LBB0_651:
	s_add_i32 m0, s28, 0x18000
	v_lshl_add_u64 v[2:3], v[2:3], 0, s[6:7]
	s_waitcnt vmcnt(4)
	s_barrier
	global_load_lds_dwordx4 v[2:3], off
	v_lshl_add_u64 v[2:3], v[4:5], 0, s[6:7]
	s_add_i32 m0, s28, 0x1a000
	s_add_i32 s41, s28, 0x8000
	global_load_lds_dwordx4 v[2:3], off
	v_lshl_add_u64 v[2:3], v[6:7], 0, s[6:7]
	s_mov_b32 m0, s41
	s_add_i32 s42, s28, 0xa000
	global_load_lds_dwordx4 v[2:3], off
	v_lshl_add_u64 v[2:3], v[8:9], 0, s[6:7]
	s_mov_b32 m0, s42
	v_bfe_u32 v1, v20, 4, 2
	global_load_lds_dwordx4 v[2:3], off
	s_add_i32 m0, s28, 0x1c000
	v_lshl_add_u64 v[2:3], v[10:11], 0, s[6:7]
	global_load_lds_dwordx4 v[2:3], off
	v_lshl_add_u64 v[2:3], v[12:13], 0, s[6:7]
	s_add_i32 m0, s28, 0x1e000
	v_and_b32_e32 v152, 15, v20
	global_load_lds_dwordx4 v[2:3], off
	v_lshlrev_b32_e32 v21, 4, v1
	v_lshlrev_b32_e32 v20, 2, v20
	v_add_u32_e32 v2, v16, v14
	s_sext_i32_i16 s47, s8
	s_and_b32 s8, s10, 3
	s_lshl_b32 s40, s9, 6
	v_lshl_or_b32 v21, v152, 6, v21
	s_lshl_b32 s10, s9, 13
	v_and_b32_e32 v20, 32, v20
	s_lshl_b32 s9, s9, 11
	v_add_lshl_u32 v2, v2, v15, 1
	v_mov_b32_e32 v3, v0
	v_bitop3_b32 v22, v21, s10, v20 bitop3:0xde
	s_lshl_b32 s10, s8, 5
	s_lshl_b32 s11, s8, 12
	s_waitcnt vmcnt(6)
	s_lshl_b32 s8, s8, 9
	s_add_i32 s9, s9, 0
	v_lshl_add_u64 v[138:139], s[14:15], 0, v[2:3]
	v_add_u32_e32 v2, v19, v17
	s_lshr_b32 s35, s64, 6
	s_add_i32 s44, s9, s8
	v_add_lshl_u32 v2, v2, v18, 1
	v_bitop3_b32 v153, v21, s11, v20 bitop3:0xde
	s_add_i32 s43, s35, -2
	s_mov_b32 s39, s93
	s_add_i32 s44, s44, 0x20000
	v_lshl_add_u64 v[140:141], s[14:15], 0, v[2:3]
	s_mov_b32 s15, 0
	s_mov_b32 s48, -1
	v_add_u32_e32 v154, 0, v22
	s_lshl_b32 s92, s10, 1
	s_barrier
	v_add_u32_e32 v248, 0x10000, v153
	s_branch .LBB0_653

.LBB0_663:
	s_add_u32 s0, s0, 0x80
	s_addc_u32 s1, s1, 0
	s_add_u32 s49, s4, 0x100
	s_addc_u32 s65, s5, 0
	s_mov_b32 s4, 0
	s_waitcnt lgkmcnt(0)
	s_waitcnt vmcnt(0)
	s_add_i32 s66, s4, 2
	s_add_u32 s18, s0, 0x80
	s_addc_u32 s5, s1, 0
	s_add_i32 s68, 0, 0x10000
	ds_read_b128 v[142:145], v248
	ds_read_b128 v[146:149], v248 offset:1024
	ds_read_b128 v[156:159], v248 offset:2048
	ds_read_b128 v[160:163], v248 offset:3072
	s_cmp_eq_u32 s43, s4
	s_cselect_b32 s4, s10, s18
	s_cselect_b32 s5, s11, s5
	s_cselect_b32 s19, s13, s65
	s_cselect_b32 s18, s12, s49
	v_lshl_add_u64 v[150:151], s[0:1], 0, v[138:139]
	s_add_i32 m0, s28, 0xc000
	ds_read_b128 v[164:167], v154
	ds_read_b128 v[168:171], v154 offset:1024
	ds_read_b128 v[172:175], v154 offset:2048
	ds_read_b128 v[176:179], v154 offset:3072
	ds_read_b128 v[180:183], v154 offset:4096
	ds_read_b128 v[204:207], v154 offset:5120
	ds_read_b128 v[208:211], v154 offset:6144
	ds_read_b128 v[212:215], v154 offset:7168
	global_load_lds_dwordx4 v[150:151], off
	v_lshl_add_u64 v[150:151], s[0:1], 0, v[140:141]
	s_add_i32 m0, s28, 0xe000
	s_nop 0
	global_load_lds_dwordx4 v[150:151], off
	s_waitcnt lgkmcnt(8)
	s_barrier
	s_waitcnt lgkmcnt(0)
	v_mfma_f32_16x16x32_bf16 v[126:129], v[142:145], v[164:167], 0
	v_mfma_f32_16x16x32_bf16 v[122:125], v[156:159], v[164:167], 0
	v_mfma_f32_16x16x32_bf16 v[110:113], v[142:145], v[172:175], 0
	v_mfma_f32_16x16x32_bf16 v[106:109], v[156:159], v[172:175], 0
	v_mfma_f32_16x16x32_bf16 v[94:97], v[142:145], v[180:183], 0
	v_mfma_f32_16x16x32_bf16 v[90:93], v[156:159], v[180:183], 0
	v_mfma_f32_16x16x32_bf16 v[78:81], v[142:145], v[208:211], 0
	v_mfma_f32_16x16x32_bf16 v[74:77], v[156:159], v[208:211], 0
	v_mfma_f32_16x16x32_bf16 v[126:129], v[146:149], v[168:171], v[126:129]
	v_mfma_f32_16x16x32_bf16 v[122:125], v[160:163], v[168:171], v[122:125]
	v_mfma_f32_16x16x32_bf16 v[110:113], v[146:149], v[176:179], v[110:113]
	v_mfma_f32_16x16x32_bf16 v[106:109], v[160:163], v[176:179], v[106:109]
	v_mfma_f32_16x16x32_bf16 v[94:97], v[146:149], v[204:207], v[94:97]
	v_mfma_f32_16x16x32_bf16 v[90:93], v[160:163], v[204:207], v[90:93]
	v_mfma_f32_16x16x32_bf16 v[78:81], v[146:149], v[212:215], v[78:81]
	v_mfma_f32_16x16x32_bf16 v[74:77], v[160:163], v[212:215], v[74:77]
	s_barrier
	s_add_i32 s69, 0, 0x14000
	s_add_i32 s68, s68, s25
	ds_read_b128 v[216:219], v248 offset:16384
	ds_read_b128 v[220:223], v248 offset:17408
	ds_read_b128 v[224:227], v248 offset:18432
	ds_read_b128 v[228:231], v248 offset:19456
	s_add_u32 s70, s18, s6
	s_addc_u32 s71, s19, s7
	s_mov_b32 m0, s68
	s_nop 0
	global_load_lds_dwordx4 v132, s[18:19]
	s_add_i32 m0, s68, 0x2000
	s_nop 0
	global_load_lds_dwordx4 v136, s[18:19]
	s_barrier
	s_waitcnt lgkmcnt(0)
	v_mfma_f32_16x16x32_bf16 v[118:121], v[216:219], v[164:167], 0
	v_mfma_f32_16x16x32_bf16 v[114:117], v[224:227], v[164:167], 0
	v_mfma_f32_16x16x32_bf16 v[102:105], v[216:219], v[172:175], 0
	v_mfma_f32_16x16x32_bf16 v[98:101], v[224:227], v[172:175], 0
	v_mfma_f32_16x16x32_bf16 v[86:89], v[216:219], v[180:183], 0
	v_mfma_f32_16x16x32_bf16 v[82:85], v[224:227], v[180:183], 0
	v_mfma_f32_16x16x32_bf16 v[70:73], v[216:219], v[208:211], 0
	v_mfma_f32_16x16x32_bf16 v[66:69], v[224:227], v[208:211], 0
	v_mfma_f32_16x16x32_bf16 v[118:121], v[220:223], v[168:171], v[118:121]
	v_mfma_f32_16x16x32_bf16 v[114:117], v[228:231], v[168:171], v[114:117]
	v_mfma_f32_16x16x32_bf16 v[102:105], v[220:223], v[176:179], v[102:105]
	v_mfma_f32_16x16x32_bf16 v[98:101], v[228:231], v[176:179], v[98:101]
	v_mfma_f32_16x16x32_bf16 v[86:89], v[220:223], v[204:207], v[86:89]
	v_mfma_f32_16x16x32_bf16 v[82:85], v[228:231], v[204:207], v[82:85]
	v_mfma_f32_16x16x32_bf16 v[70:73], v[220:223], v[212:215], v[70:73]
	v_mfma_f32_16x16x32_bf16 v[66:69], v[228:231], v[212:215], v[66:69]
	s_barrier
	s_mov_b32 m0, s28
	s_add_u32 s72, s4, s6
	s_addc_u32 s73, s5, s7
	ds_read_b128 v[164:167], v154 offset:16384
	ds_read_b128 v[168:171], v154 offset:17408
	ds_read_b128 v[172:175], v154 offset:18432
	ds_read_b128 v[176:179], v154 offset:19456
	ds_read_b128 v[180:183], v154 offset:20480
	ds_read_b128 v[204:207], v154 offset:21504
	ds_read_b128 v[208:211], v154 offset:22528
	ds_read_b128 v[212:215], v154 offset:23552
	global_load_lds_dwordx4 v130, s[4:5]
	s_mov_b32 m0, s29
	s_nop 0
	global_load_lds_dwordx4 v134, s[4:5]
	s_barrier
	s_waitcnt lgkmcnt(0)
	v_mfma_f32_16x16x32_bf16 v[62:65], v[142:145], v[164:167], 0
	v_mfma_f32_16x16x32_bf16 v[58:61], v[156:159], v[164:167], 0
	v_mfma_f32_16x16x32_bf16 v[46:49], v[142:145], v[172:175], 0
	v_mfma_f32_16x16x32_bf16 v[42:45], v[156:159], v[172:175], 0
	v_mfma_f32_16x16x32_bf16 v[30:33], v[142:145], v[180:183], 0
	v_mfma_f32_16x16x32_bf16 v[26:29], v[156:159], v[180:183], 0
	v_mfma_f32_16x16x32_bf16 v[14:17], v[142:145], v[208:211], 0
	v_mfma_f32_16x16x32_bf16 v[10:13], v[156:159], v[208:211], 0
	v_mfma_f32_16x16x32_bf16 v[62:65], v[146:149], v[168:171], v[62:65]
	v_mfma_f32_16x16x32_bf16 v[58:61], v[160:163], v[168:171], v[58:61]
	v_mfma_f32_16x16x32_bf16 v[46:49], v[146:149], v[176:179], v[46:49]
	v_mfma_f32_16x16x32_bf16 v[42:45], v[160:163], v[176:179], v[42:45]
	v_mfma_f32_16x16x32_bf16 v[30:33], v[146:149], v[204:207], v[30:33]
	v_mfma_f32_16x16x32_bf16 v[26:29], v[160:163], v[204:207], v[26:29]
	v_mfma_f32_16x16x32_bf16 v[14:17], v[146:149], v[212:215], v[14:17]
	v_mfma_f32_16x16x32_bf16 v[10:13], v[160:163], v[212:215], v[10:13]
	s_barrier
	s_add_u32 s18, s18, s14
	s_addc_u32 s19, s19, 0
	s_add_i32 s68, s69, s25
	s_add_u32 s76, s18, s6
	s_addc_u32 s77, s19, s7
	s_mov_b32 m0, s68
	s_nop 0
	global_load_lds_dwordx4 v132, s[18:19]
	s_add_i32 m0, s68, 0x2000
	s_nop 0
	global_load_lds_dwordx4 v136, s[18:19]
	s_waitcnt vmcnt(6)
	s_barrier
	v_mfma_f32_16x16x32_bf16 v[54:57], v[216:219], v[164:167], 0
	v_mfma_f32_16x16x32_bf16 v[50:53], v[224:227], v[164:167], 0
	v_mfma_f32_16x16x32_bf16 v[38:41], v[216:219], v[172:175], 0
	v_mfma_f32_16x16x32_bf16 v[34:37], v[224:227], v[172:175], 0
	v_mfma_f32_16x16x32_bf16 v[22:25], v[216:219], v[180:183], 0
	v_mfma_f32_16x16x32_bf16 v[18:21], v[224:227], v[180:183], 0
	v_mfma_f32_16x16x32_bf16 v[6:9], v[216:219], v[208:211], 0
	v_mfma_f32_16x16x32_bf16 v[2:5], v[224:227], v[208:211], 0
	v_mfma_f32_16x16x32_bf16 v[54:57], v[220:223], v[168:171], v[54:57]
	v_mfma_f32_16x16x32_bf16 v[50:53], v[228:231], v[168:171], v[50:53]
	v_mfma_f32_16x16x32_bf16 v[38:41], v[220:223], v[176:179], v[38:41]
	v_mfma_f32_16x16x32_bf16 v[34:37], v[228:231], v[176:179], v[34:37]
	v_mfma_f32_16x16x32_bf16 v[22:25], v[220:223], v[204:207], v[22:25]
	v_mfma_f32_16x16x32_bf16 v[18:21], v[228:231], v[204:207], v[18:21]
	v_mfma_f32_16x16x32_bf16 v[6:9], v[220:223], v[212:215], v[6:9]
	v_mfma_f32_16x16x32_bf16 v[2:5], v[228:231], v[212:215], v[2:5]
	s_barrier
	s_add_i32 s18, 0, 0x18000
	ds_read_b128 v[142:145], v248 offset:32768
	ds_read_b128 v[146:149], v248 offset:33792
	ds_read_b128 v[156:159], v248 offset:34816
	ds_read_b128 v[160:163], v248 offset:35840
	s_add_u32 s4, s4, s14
	s_addc_u32 s5, s5, 0
	s_mov_b32 m0, s31
	ds_read_b128 v[164:167], v154 offset:32768
	ds_read_b128 v[168:171], v154 offset:33792
	ds_read_b128 v[172:175], v154 offset:34816
	ds_read_b128 v[176:179], v154 offset:35840
	ds_read_b128 v[180:183], v154 offset:36864
	ds_read_b128 v[204:207], v154 offset:37888
	ds_read_b128 v[208:211], v154 offset:38912
	ds_read_b128 v[212:215], v154 offset:39936
	global_load_lds_dwordx4 v130, s[4:5]
	s_mov_b32 m0, s34
	s_nop 0
	global_load_lds_dwordx4 v134, s[4:5]
	s_waitcnt lgkmcnt(8)
	s_barrier
	s_waitcnt lgkmcnt(0)
	v_mfma_f32_16x16x32_bf16 v[126:129], v[142:145], v[164:167], v[126:129]
	v_mfma_f32_16x16x32_bf16 v[122:125], v[156:159], v[164:167], v[122:125]
	v_mfma_f32_16x16x32_bf16 v[110:113], v[142:145], v[172:175], v[110:113]
	v_mfma_f32_16x16x32_bf16 v[106:109], v[156:159], v[172:175], v[106:109]
	v_mfma_f32_16x16x32_bf16 v[94:97], v[142:145], v[180:183], v[94:97]
	v_mfma_f32_16x16x32_bf16 v[90:93], v[156:159], v[180:183], v[90:93]
	v_mfma_f32_16x16x32_bf16 v[78:81], v[142:145], v[208:211], v[78:81]
	v_mfma_f32_16x16x32_bf16 v[74:77], v[156:159], v[208:211], v[74:77]
	v_mfma_f32_16x16x32_bf16 v[126:129], v[146:149], v[168:171], v[126:129]
	v_mfma_f32_16x16x32_bf16 v[122:125], v[160:163], v[168:171], v[122:125]
	v_mfma_f32_16x16x32_bf16 v[110:113], v[146:149], v[176:179], v[110:113]
	v_mfma_f32_16x16x32_bf16 v[106:109], v[160:163], v[176:179], v[106:109]
	v_mfma_f32_16x16x32_bf16 v[94:97], v[146:149], v[204:207], v[94:97]
	v_mfma_f32_16x16x32_bf16 v[90:93], v[160:163], v[204:207], v[90:93]
	v_mfma_f32_16x16x32_bf16 v[78:81], v[146:149], v[212:215], v[78:81]
	v_mfma_f32_16x16x32_bf16 v[74:77], v[160:163], v[212:215], v[74:77]
	s_barrier
	s_add_i32 s4, 0, 0x1c000
	s_add_i32 s5, s18, s25
	s_mov_b32 m0, s5
	ds_read_b128 v[216:219], v248 offset:49152
	ds_read_b128 v[220:223], v248 offset:50176
	ds_read_b128 v[224:227], v248 offset:51200
	ds_read_b128 v[228:231], v248 offset:52224
	global_load_lds_dwordx4 v132, s[70:71]
	s_add_i32 m0, s5, 0x2000
	s_nop 0
	global_load_lds_dwordx4 v136, s[70:71]
	s_barrier
	s_waitcnt lgkmcnt(0)
	v_mfma_f32_16x16x32_bf16 v[118:121], v[216:219], v[164:167], v[118:121]
	v_mfma_f32_16x16x32_bf16 v[114:117], v[224:227], v[164:167], v[114:117]
	v_mfma_f32_16x16x32_bf16 v[102:105], v[216:219], v[172:175], v[102:105]
	v_mfma_f32_16x16x32_bf16 v[98:101], v[224:227], v[172:175], v[98:101]
	v_mfma_f32_16x16x32_bf16 v[86:89], v[216:219], v[180:183], v[86:89]
	v_mfma_f32_16x16x32_bf16 v[82:85], v[224:227], v[180:183], v[82:85]
	v_mfma_f32_16x16x32_bf16 v[70:73], v[216:219], v[208:211], v[70:73]
	v_mfma_f32_16x16x32_bf16 v[66:69], v[224:227], v[208:211], v[66:69]
	v_mfma_f32_16x16x32_bf16 v[118:121], v[220:223], v[168:171], v[118:121]
	v_mfma_f32_16x16x32_bf16 v[114:117], v[228:231], v[168:171], v[114:117]
	v_mfma_f32_16x16x32_bf16 v[102:105], v[220:223], v[176:179], v[102:105]
	v_mfma_f32_16x16x32_bf16 v[98:101], v[228:231], v[176:179], v[98:101]
	v_mfma_f32_16x16x32_bf16 v[86:89], v[220:223], v[204:207], v[86:89]
	v_mfma_f32_16x16x32_bf16 v[82:85], v[228:231], v[204:207], v[82:85]
	v_mfma_f32_16x16x32_bf16 v[70:73], v[220:223], v[212:215], v[70:73]
	v_mfma_f32_16x16x32_bf16 v[66:69], v[228:231], v[212:215], v[66:69]
	s_barrier
	s_mov_b32 m0, s41
	ds_read_b128 v[164:167], v154 offset:49152
	ds_read_b128 v[168:171], v154 offset:50176
	ds_read_b128 v[172:175], v154 offset:51200
	ds_read_b128 v[176:179], v154 offset:52224
	ds_read_b128 v[180:183], v154 offset:53248
	ds_read_b128 v[204:207], v154 offset:54272
	ds_read_b128 v[208:211], v154 offset:55296
	ds_read_b128 v[212:215], v154 offset:56320
	global_load_lds_dwordx4 v130, s[72:73]
	s_mov_b32 m0, s42
	s_nop 0
	global_load_lds_dwordx4 v134, s[72:73]
	s_barrier
	s_waitcnt lgkmcnt(0)
	v_mfma_f32_16x16x32_bf16 v[62:65], v[142:145], v[164:167], v[62:65]
	v_mfma_f32_16x16x32_bf16 v[58:61], v[156:159], v[164:167], v[58:61]
	v_mfma_f32_16x16x32_bf16 v[46:49], v[142:145], v[172:175], v[46:49]
	v_mfma_f32_16x16x32_bf16 v[42:45], v[156:159], v[172:175], v[42:45]
	v_mfma_f32_16x16x32_bf16 v[30:33], v[142:145], v[180:183], v[30:33]
	v_mfma_f32_16x16x32_bf16 v[26:29], v[156:159], v[180:183], v[26:29]
	v_mfma_f32_16x16x32_bf16 v[14:17], v[142:145], v[208:211], v[14:17]
	v_mfma_f32_16x16x32_bf16 v[10:13], v[156:159], v[208:211], v[10:13]
	v_mfma_f32_16x16x32_bf16 v[62:65], v[146:149], v[168:171], v[62:65]
	v_mfma_f32_16x16x32_bf16 v[58:61], v[160:163], v[168:171], v[58:61]
	v_mfma_f32_16x16x32_bf16 v[46:49], v[146:149], v[176:179], v[46:49]
	v_mfma_f32_16x16x32_bf16 v[42:45], v[160:163], v[176:179], v[42:45]
	v_mfma_f32_16x16x32_bf16 v[30:33], v[146:149], v[204:207], v[30:33]
	v_mfma_f32_16x16x32_bf16 v[26:29], v[160:163], v[204:207], v[26:29]
	v_mfma_f32_16x16x32_bf16 v[14:17], v[146:149], v[212:215], v[14:17]
	v_mfma_f32_16x16x32_bf16 v[10:13], v[160:163], v[212:215], v[10:13]
	s_barrier
	s_add_i32 s4, s4, s25
	s_mov_b32 m0, s4
	s_nop 0
	global_load_lds_dwordx4 v132, s[76:77]
	s_add_i32 m0, s4, 0x2000
	s_nop 0
	global_load_lds_dwordx4 v136, s[76:77]
	s_add_u32 s0, s0, 0x100
	s_addc_u32 s1, s1, 0
	s_add_u32 s49, s49, 0x100
	s_addc_u32 s65, s65, 0
	s_cmp_ge_u32 s66, s35
	s_mov_b32 s4, s66
	s_waitcnt vmcnt(6)
	s_barrier
	v_mfma_f32_16x16x32_bf16 v[54:57], v[216:219], v[164:167], v[54:57]
	v_mfma_f32_16x16x32_bf16 v[50:53], v[224:227], v[164:167], v[50:53]
	v_mfma_f32_16x16x32_bf16 v[38:41], v[216:219], v[172:175], v[38:41]
	v_mfma_f32_16x16x32_bf16 v[34:37], v[224:227], v[172:175], v[34:37]
	v_mfma_f32_16x16x32_bf16 v[22:25], v[216:219], v[180:183], v[22:25]
	v_mfma_f32_16x16x32_bf16 v[18:21], v[224:227], v[180:183], v[18:21]
	v_mfma_f32_16x16x32_bf16 v[6:9], v[216:219], v[208:211], v[6:9]
	v_mfma_f32_16x16x32_bf16 v[2:5], v[224:227], v[208:211], v[2:5]
	v_mfma_f32_16x16x32_bf16 v[54:57], v[220:223], v[168:171], v[54:57]
	v_mfma_f32_16x16x32_bf16 v[50:53], v[228:231], v[168:171], v[50:53]
	v_mfma_f32_16x16x32_bf16 v[38:41], v[220:223], v[176:179], v[38:41]
	v_mfma_f32_16x16x32_bf16 v[34:37], v[228:231], v[176:179], v[34:37]
	v_mfma_f32_16x16x32_bf16 v[22:25], v[220:223], v[204:207], v[22:25]
	v_mfma_f32_16x16x32_bf16 v[18:21], v[228:231], v[204:207], v[18:21]
	v_mfma_f32_16x16x32_bf16 v[6:9], v[220:223], v[212:215], v[6:9]
	v_mfma_f32_16x16x32_bf16 v[2:5], v[228:231], v[212:215], v[2:5]
	s_barrier
	s_cbranch_scc1 .Lkexit_664
.LBB0_664:
	s_add_i32 s66, s4, 2
	s_add_u32 s18, s0, 0x80
	s_addc_u32 s5, s1, 0
	s_add_i32 s68, 0, 0x10000
	ds_read_b128 v[142:145], v248
	ds_read_b128 v[146:149], v248 offset:1024
	ds_read_b128 v[156:159], v248 offset:2048
	ds_read_b128 v[160:163], v248 offset:3072
	s_cmp_eq_u32 s43, s4
	s_cselect_b32 s4, s10, s18
	s_cselect_b32 s5, s11, s5
	s_cselect_b32 s19, s13, s65
	s_cselect_b32 s18, s12, s49
	v_lshl_add_u64 v[150:151], s[0:1], 0, v[138:139]
	s_add_i32 m0, s28, 0xc000
	ds_read_b128 v[164:167], v154
	ds_read_b128 v[168:171], v154 offset:1024
	ds_read_b128 v[172:175], v154 offset:2048
	ds_read_b128 v[176:179], v154 offset:3072
	ds_read_b128 v[180:183], v154 offset:4096
	ds_read_b128 v[204:207], v154 offset:5120
	ds_read_b128 v[208:211], v154 offset:6144
	ds_read_b128 v[212:215], v154 offset:7168
	global_load_lds_dwordx4 v[150:151], off
	v_lshl_add_u64 v[150:151], s[0:1], 0, v[140:141]
	s_add_i32 m0, s28, 0xe000
	s_nop 0
	global_load_lds_dwordx4 v[150:151], off
	s_waitcnt lgkmcnt(8)
	s_barrier
	s_waitcnt lgkmcnt(0)
	v_mfma_f32_16x16x32_bf16 v[126:129], v[142:145], v[164:167], v[126:129]
	v_mfma_f32_16x16x32_bf16 v[122:125], v[156:159], v[164:167], v[122:125]
	v_mfma_f32_16x16x32_bf16 v[110:113], v[142:145], v[172:175], v[110:113]
	v_mfma_f32_16x16x32_bf16 v[106:109], v[156:159], v[172:175], v[106:109]
	v_mfma_f32_16x16x32_bf16 v[94:97], v[142:145], v[180:183], v[94:97]
	v_mfma_f32_16x16x32_bf16 v[90:93], v[156:159], v[180:183], v[90:93]
	v_mfma_f32_16x16x32_bf16 v[78:81], v[142:145], v[208:211], v[78:81]
	v_mfma_f32_16x16x32_bf16 v[74:77], v[156:159], v[208:211], v[74:77]
	v_mfma_f32_16x16x32_bf16 v[126:129], v[146:149], v[168:171], v[126:129]
	v_mfma_f32_16x16x32_bf16 v[122:125], v[160:163], v[168:171], v[122:125]
	v_mfma_f32_16x16x32_bf16 v[110:113], v[146:149], v[176:179], v[110:113]
	v_mfma_f32_16x16x32_bf16 v[106:109], v[160:163], v[176:179], v[106:109]
	v_mfma_f32_16x16x32_bf16 v[94:97], v[146:149], v[204:207], v[94:97]
	v_mfma_f32_16x16x32_bf16 v[90:93], v[160:163], v[204:207], v[90:93]
	v_mfma_f32_16x16x32_bf16 v[78:81], v[146:149], v[212:215], v[78:81]
	v_mfma_f32_16x16x32_bf16 v[74:77], v[160:163], v[212:215], v[74:77]
	s_barrier
	s_add_i32 s69, 0, 0x14000
	s_add_i32 s68, s68, s25
	ds_read_b128 v[216:219], v248 offset:16384
	ds_read_b128 v[220:223], v248 offset:17408
	ds_read_b128 v[224:227], v248 offset:18432
	ds_read_b128 v[228:231], v248 offset:19456
	s_add_u32 s70, s18, s6
	s_addc_u32 s71, s19, s7
	s_mov_b32 m0, s68
	s_nop 0
	global_load_lds_dwordx4 v132, s[18:19]
	s_add_i32 m0, s68, 0x2000
	s_nop 0
	global_load_lds_dwordx4 v136, s[18:19]
	s_barrier
	s_waitcnt lgkmcnt(0)
	v_mfma_f32_16x16x32_bf16 v[118:121], v[216:219], v[164:167], v[118:121]
	v_mfma_f32_16x16x32_bf16 v[114:117], v[224:227], v[164:167], v[114:117]
	v_mfma_f32_16x16x32_bf16 v[102:105], v[216:219], v[172:175], v[102:105]
	v_mfma_f32_16x16x32_bf16 v[98:101], v[224:227], v[172:175], v[98:101]
	v_mfma_f32_16x16x32_bf16 v[86:89], v[216:219], v[180:183], v[86:89]
	v_mfma_f32_16x16x32_bf16 v[82:85], v[224:227], v[180:183], v[82:85]
	v_mfma_f32_16x16x32_bf16 v[70:73], v[216:219], v[208:211], v[70:73]
	v_mfma_f32_16x16x32_bf16 v[66:69], v[224:227], v[208:211], v[66:69]
	v_mfma_f32_16x16x32_bf16 v[118:121], v[220:223], v[168:171], v[118:121]
	v_mfma_f32_16x16x32_bf16 v[114:117], v[228:231], v[168:171], v[114:117]
	v_mfma_f32_16x16x32_bf16 v[102:105], v[220:223], v[176:179], v[102:105]
	v_mfma_f32_16x16x32_bf16 v[98:101], v[228:231], v[176:179], v[98:101]
	v_mfma_f32_16x16x32_bf16 v[86:89], v[220:223], v[204:207], v[86:89]
	v_mfma_f32_16x16x32_bf16 v[82:85], v[228:231], v[204:207], v[82:85]
	v_mfma_f32_16x16x32_bf16 v[70:73], v[220:223], v[212:215], v[70:73]
	v_mfma_f32_16x16x32_bf16 v[66:69], v[228:231], v[212:215], v[66:69]
	s_barrier
	s_mov_b32 m0, s28
	s_add_u32 s72, s4, s6
	s_addc_u32 s73, s5, s7
	ds_read_b128 v[164:167], v154 offset:16384
	ds_read_b128 v[168:171], v154 offset:17408
	ds_read_b128 v[172:175], v154 offset:18432
	ds_read_b128 v[176:179], v154 offset:19456
	ds_read_b128 v[180:183], v154 offset:20480
	ds_read_b128 v[204:207], v154 offset:21504
	ds_read_b128 v[208:211], v154 offset:22528
	ds_read_b128 v[212:215], v154 offset:23552
	global_load_lds_dwordx4 v130, s[4:5]
	s_mov_b32 m0, s29
	s_nop 0
	global_load_lds_dwordx4 v134, s[4:5]
	s_barrier
	s_waitcnt lgkmcnt(0)
	v_mfma_f32_16x16x32_bf16 v[62:65], v[142:145], v[164:167], v[62:65]
	v_mfma_f32_16x16x32_bf16 v[58:61], v[156:159], v[164:167], v[58:61]
	v_mfma_f32_16x16x32_bf16 v[46:49], v[142:145], v[172:175], v[46:49]
	v_mfma_f32_16x16x32_bf16 v[42:45], v[156:159], v[172:175], v[42:45]
	v_mfma_f32_16x16x32_bf16 v[30:33], v[142:145], v[180:183], v[30:33]
	v_mfma_f32_16x16x32_bf16 v[26:29], v[156:159], v[180:183], v[26:29]
	v_mfma_f32_16x16x32_bf16 v[14:17], v[142:145], v[208:211], v[14:17]
	v_mfma_f32_16x16x32_bf16 v[10:13], v[156:159], v[208:211], v[10:13]
	v_mfma_f32_16x16x32_bf16 v[62:65], v[146:149], v[168:171], v[62:65]
	v_mfma_f32_16x16x32_bf16 v[58:61], v[160:163], v[168:171], v[58:61]
	v_mfma_f32_16x16x32_bf16 v[46:49], v[146:149], v[176:179], v[46:49]
	v_mfma_f32_16x16x32_bf16 v[42:45], v[160:163], v[176:179], v[42:45]
	v_mfma_f32_16x16x32_bf16 v[30:33], v[146:149], v[204:207], v[30:33]
	v_mfma_f32_16x16x32_bf16 v[26:29], v[160:163], v[204:207], v[26:29]
	v_mfma_f32_16x16x32_bf16 v[14:17], v[146:149], v[212:215], v[14:17]
	v_mfma_f32_16x16x32_bf16 v[10:13], v[160:163], v[212:215], v[10:13]
	s_barrier
	s_add_u32 s18, s18, s14
	s_addc_u32 s19, s19, 0
	s_add_i32 s68, s69, s25
	s_add_u32 s76, s18, s6
	s_addc_u32 s77, s19, s7
	s_mov_b32 m0, s68
	s_nop 0
	global_load_lds_dwordx4 v132, s[18:19]
	s_add_i32 m0, s68, 0x2000
	s_nop 0
	global_load_lds_dwordx4 v136, s[18:19]
	s_waitcnt vmcnt(6)
	s_barrier
	v_mfma_f32_16x16x32_bf16 v[54:57], v[216:219], v[164:167], v[54:57]
	v_mfma_f32_16x16x32_bf16 v[50:53], v[224:227], v[164:167], v[50:53]
	v_mfma_f32_16x16x32_bf16 v[38:41], v[216:219], v[172:175], v[38:41]
	v_mfma_f32_16x16x32_bf16 v[34:37], v[224:227], v[172:175], v[34:37]
	v_mfma_f32_16x16x32_bf16 v[22:25], v[216:219], v[180:183], v[22:25]
	v_mfma_f32_16x16x32_bf16 v[18:21], v[224:227], v[180:183], v[18:21]
	v_mfma_f32_16x16x32_bf16 v[6:9], v[216:219], v[208:211], v[6:9]
	v_mfma_f32_16x16x32_bf16 v[2:5], v[224:227], v[208:211], v[2:5]
	v_mfma_f32_16x16x32_bf16 v[54:57], v[220:223], v[168:171], v[54:57]
	v_mfma_f32_16x16x32_bf16 v[50:53], v[228:231], v[168:171], v[50:53]
	v_mfma_f32_16x16x32_bf16 v[38:41], v[220:223], v[176:179], v[38:41]
	v_mfma_f32_16x16x32_bf16 v[34:37], v[228:231], v[176:179], v[34:37]
	v_mfma_f32_16x16x32_bf16 v[22:25], v[220:223], v[204:207], v[22:25]
	v_mfma_f32_16x16x32_bf16 v[18:21], v[228:231], v[204:207], v[18:21]
	v_mfma_f32_16x16x32_bf16 v[6:9], v[220:223], v[212:215], v[6:9]
	v_mfma_f32_16x16x32_bf16 v[2:5], v[228:231], v[212:215], v[2:5]
	s_barrier
	s_add_i32 s18, 0, 0x18000
	ds_read_b128 v[142:145], v248 offset:32768
	ds_read_b128 v[146:149], v248 offset:33792
	ds_read_b128 v[156:159], v248 offset:34816
	ds_read_b128 v[160:163], v248 offset:35840
	s_add_u32 s4, s4, s14
	s_addc_u32 s5, s5, 0
	s_mov_b32 m0, s31
	ds_read_b128 v[164:167], v154 offset:32768
	ds_read_b128 v[168:171], v154 offset:33792
	ds_read_b128 v[172:175], v154 offset:34816
	ds_read_b128 v[176:179], v154 offset:35840
	ds_read_b128 v[180:183], v154 offset:36864
	ds_read_b128 v[204:207], v154 offset:37888
	ds_read_b128 v[208:211], v154 offset:38912
	ds_read_b128 v[212:215], v154 offset:39936
	global_load_lds_dwordx4 v130, s[4:5]
	s_mov_b32 m0, s34
	s_nop 0
	global_load_lds_dwordx4 v134, s[4:5]
	s_waitcnt lgkmcnt(8)
	s_barrier
	s_waitcnt lgkmcnt(0)
	v_mfma_f32_16x16x32_bf16 v[126:129], v[142:145], v[164:167], v[126:129]
	v_mfma_f32_16x16x32_bf16 v[122:125], v[156:159], v[164:167], v[122:125]
	v_mfma_f32_16x16x32_bf16 v[110:113], v[142:145], v[172:175], v[110:113]
	v_mfma_f32_16x16x32_bf16 v[106:109], v[156:159], v[172:175], v[106:109]
	v_mfma_f32_16x16x32_bf16 v[94:97], v[142:145], v[180:183], v[94:97]
	v_mfma_f32_16x16x32_bf16 v[90:93], v[156:159], v[180:183], v[90:93]
	v_mfma_f32_16x16x32_bf16 v[78:81], v[142:145], v[208:211], v[78:81]
	v_mfma_f32_16x16x32_bf16 v[74:77], v[156:159], v[208:211], v[74:77]
	v_mfma_f32_16x16x32_bf16 v[126:129], v[146:149], v[168:171], v[126:129]
	v_mfma_f32_16x16x32_bf16 v[122:125], v[160:163], v[168:171], v[122:125]
	v_mfma_f32_16x16x32_bf16 v[110:113], v[146:149], v[176:179], v[110:113]
	v_mfma_f32_16x16x32_bf16 v[106:109], v[160:163], v[176:179], v[106:109]
	v_mfma_f32_16x16x32_bf16 v[94:97], v[146:149], v[204:207], v[94:97]
	v_mfma_f32_16x16x32_bf16 v[90:93], v[160:163], v[204:207], v[90:93]
	v_mfma_f32_16x16x32_bf16 v[78:81], v[146:149], v[212:215], v[78:81]
	v_mfma_f32_16x16x32_bf16 v[74:77], v[160:163], v[212:215], v[74:77]
	s_barrier
	s_add_i32 s4, 0, 0x1c000
	s_add_i32 s5, s18, s25
	s_mov_b32 m0, s5
	ds_read_b128 v[216:219], v248 offset:49152
	ds_read_b128 v[220:223], v248 offset:50176
	ds_read_b128 v[224:227], v248 offset:51200
	ds_read_b128 v[228:231], v248 offset:52224
	global_load_lds_dwordx4 v132, s[70:71]
	s_add_i32 m0, s5, 0x2000
	s_nop 0
	global_load_lds_dwordx4 v136, s[70:71]
	s_barrier
	s_waitcnt lgkmcnt(0)
	v_mfma_f32_16x16x32_bf16 v[118:121], v[216:219], v[164:167], v[118:121]
	v_mfma_f32_16x16x32_bf16 v[114:117], v[224:227], v[164:167], v[114:117]
	v_mfma_f32_16x16x32_bf16 v[102:105], v[216:219], v[172:175], v[102:105]
	v_mfma_f32_16x16x32_bf16 v[98:101], v[224:227], v[172:175], v[98:101]
	v_mfma_f32_16x16x32_bf16 v[86:89], v[216:219], v[180:183], v[86:89]
	v_mfma_f32_16x16x32_bf16 v[82:85], v[224:227], v[180:183], v[82:85]
	v_mfma_f32_16x16x32_bf16 v[70:73], v[216:219], v[208:211], v[70:73]
	v_mfma_f32_16x16x32_bf16 v[66:69], v[224:227], v[208:211], v[66:69]
	v_mfma_f32_16x16x32_bf16 v[118:121], v[220:223], v[168:171], v[118:121]
	v_mfma_f32_16x16x32_bf16 v[114:117], v[228:231], v[168:171], v[114:117]
	v_mfma_f32_16x16x32_bf16 v[102:105], v[220:223], v[176:179], v[102:105]
	v_mfma_f32_16x16x32_bf16 v[98:101], v[228:231], v[176:179], v[98:101]
	v_mfma_f32_16x16x32_bf16 v[86:89], v[220:223], v[204:207], v[86:89]
	v_mfma_f32_16x16x32_bf16 v[82:85], v[228:231], v[204:207], v[82:85]
	v_mfma_f32_16x16x32_bf16 v[70:73], v[220:223], v[212:215], v[70:73]
	v_mfma_f32_16x16x32_bf16 v[66:69], v[228:231], v[212:215], v[66:69]
	s_barrier
	s_mov_b32 m0, s41
	ds_read_b128 v[164:167], v154 offset:49152
	ds_read_b128 v[168:171], v154 offset:50176
	ds_read_b128 v[172:175], v154 offset:51200
	ds_read_b128 v[176:179], v154 offset:52224
	ds_read_b128 v[180:183], v154 offset:53248
	ds_read_b128 v[204:207], v154 offset:54272
	ds_read_b128 v[208:211], v154 offset:55296
	ds_read_b128 v[212:215], v154 offset:56320
	global_load_lds_dwordx4 v130, s[72:73]
	s_mov_b32 m0, s42
	s_nop 0
	global_load_lds_dwordx4 v134, s[72:73]
	s_barrier
	s_waitcnt lgkmcnt(0)
	v_mfma_f32_16x16x32_bf16 v[62:65], v[142:145], v[164:167], v[62:65]
	v_mfma_f32_16x16x32_bf16 v[58:61], v[156:159], v[164:167], v[58:61]
	v_mfma_f32_16x16x32_bf16 v[46:49], v[142:145], v[172:175], v[46:49]
	v_mfma_f32_16x16x32_bf16 v[42:45], v[156:159], v[172:175], v[42:45]
	v_mfma_f32_16x16x32_bf16 v[30:33], v[142:145], v[180:183], v[30:33]
	v_mfma_f32_16x16x32_bf16 v[26:29], v[156:159], v[180:183], v[26:29]
	v_mfma_f32_16x16x32_bf16 v[14:17], v[142:145], v[208:211], v[14:17]
	v_mfma_f32_16x16x32_bf16 v[10:13], v[156:159], v[208:211], v[10:13]
	v_mfma_f32_16x16x32_bf16 v[62:65], v[146:149], v[168:171], v[62:65]
	v_mfma_f32_16x16x32_bf16 v[58:61], v[160:163], v[168:171], v[58:61]
	v_mfma_f32_16x16x32_bf16 v[46:49], v[146:149], v[176:179], v[46:49]
	v_mfma_f32_16x16x32_bf16 v[42:45], v[160:163], v[176:179], v[42:45]
	v_mfma_f32_16x16x32_bf16 v[30:33], v[146:149], v[204:207], v[30:33]
	v_mfma_f32_16x16x32_bf16 v[26:29], v[160:163], v[204:207], v[26:29]
	v_mfma_f32_16x16x32_bf16 v[14:17], v[146:149], v[212:215], v[14:17]
	v_mfma_f32_16x16x32_bf16 v[10:13], v[160:163], v[212:215], v[10:13]
	s_barrier
	s_add_i32 s4, s4, s25
	s_mov_b32 m0, s4
	s_nop 0
	global_load_lds_dwordx4 v132, s[76:77]
	s_add_i32 m0, s4, 0x2000
	s_nop 0
	global_load_lds_dwordx4 v136, s[76:77]
	s_add_u32 s0, s0, 0x100
	s_addc_u32 s1, s1, 0
	s_add_u32 s49, s49, 0x100
	s_addc_u32 s65, s65, 0
	s_cmp_ge_u32 s66, s35
	s_mov_b32 s4, s66
	s_waitcnt vmcnt(6)
	s_barrier
	v_mfma_f32_16x16x32_bf16 v[54:57], v[216:219], v[164:167], v[54:57]
	v_mfma_f32_16x16x32_bf16 v[50:53], v[224:227], v[164:167], v[50:53]
	v_mfma_f32_16x16x32_bf16 v[38:41], v[216:219], v[172:175], v[38:41]
	v_mfma_f32_16x16x32_bf16 v[34:37], v[224:227], v[172:175], v[34:37]
	v_mfma_f32_16x16x32_bf16 v[22:25], v[216:219], v[180:183], v[22:25]
	v_mfma_f32_16x16x32_bf16 v[18:21], v[224:227], v[180:183], v[18:21]
	v_mfma_f32_16x16x32_bf16 v[6:9], v[216:219], v[208:211], v[6:9]
	v_mfma_f32_16x16x32_bf16 v[2:5], v[224:227], v[208:211], v[2:5]
	v_mfma_f32_16x16x32_bf16 v[54:57], v[220:223], v[168:171], v[54:57]
	v_mfma_f32_16x16x32_bf16 v[50:53], v[228:231], v[168:171], v[50:53]
	v_mfma_f32_16x16x32_bf16 v[38:41], v[220:223], v[176:179], v[38:41]
	v_mfma_f32_16x16x32_bf16 v[34:37], v[228:231], v[176:179], v[34:37]
	v_mfma_f32_16x16x32_bf16 v[22:25], v[220:223], v[204:207], v[22:25]
	v_mfma_f32_16x16x32_bf16 v[18:21], v[228:231], v[204:207], v[18:21]
	v_mfma_f32_16x16x32_bf16 v[6:9], v[220:223], v[212:215], v[6:9]
	v_mfma_f32_16x16x32_bf16 v[2:5], v[228:231], v[212:215], v[2:5]
	s_barrier
	s_cbranch_scc0 .LBB0_664

.LBB0_685:
	v_bfe_u32 v1, v8, 4, 2
	v_mov_b32_e32 v133, v0
	v_mov_b32_e32 v137, v0
	v_and_b32_e32 v148, 15, v8
	v_lshlrev_b32_e32 v9, 4, v1
	v_lshlrev_b32_e32 v8, 2, v8
	v_lshl_add_u64 v[18:19], s[8:9], 0, v[132:133]
	v_lshl_add_u64 v[20:21], s[8:9], 0, v[136:137]
	s_and_b32 s26, s10, 3
	v_lshl_or_b32 v9, v148, 6, v9
	s_lshl_b32 s8, s11, 13
	v_and_b32_e32 v8, 32, v8
	v_lshl_add_u64 v[10:11], s[4:5], 0, v[132:133]
	v_bitop3_b32 v22, v9, s8, v8 bitop3:0xde
	s_lshl_b32 s8, s26, 12
	v_lshl_add_u64 v[12:13], s[4:5], 0, v[136:137]
	v_mov_b32_e32 v131, v0
	v_bitop3_b32 v149, v9, s8, v8 bitop3:0xde
	s_add_i32 m0, s22, 0x18000
	v_lshl_add_u64 v[8:9], v[10:11], 0, s[6:7]
	v_lshl_add_u64 v[14:15], s[0:1], 0, v[130:131]
	v_mov_b32_e32 v135, v0
	s_waitcnt vmcnt(4)
	s_barrier
	global_load_lds_dwordx4 v[8:9], off
	v_lshl_add_u64 v[8:9], v[12:13], 0, s[6:7]
	s_add_i32 m0, s22, 0x1a000
	s_add_i32 s30, s22, 0x8000
	v_lshl_add_u64 v[16:17], s[0:1], 0, v[134:135]
	global_load_lds_dwordx4 v[8:9], off
	v_lshl_add_u64 v[8:9], v[14:15], 0, s[6:7]
	s_mov_b32 m0, s30
	s_add_i32 s31, s22, 0xa000
	global_load_lds_dwordx4 v[8:9], off
	v_lshl_add_u64 v[8:9], v[16:17], 0, s[6:7]
	s_mov_b32 m0, s31
	s_lshl_b32 s42, s57, 3
	global_load_lds_dwordx4 v[8:9], off
	s_add_i32 m0, s22, 0x1c000
	v_lshl_add_u64 v[8:9], v[18:19], 0, s[6:7]
	global_load_lds_dwordx4 v[8:9], off
	v_lshl_add_u64 v[8:9], v[20:21], 0, s[6:7]
	s_add_i32 m0, s22, 0x1e000
	v_add_u32_e32 v2, v4, v2
	global_load_lds_dwordx4 v[8:9], off
	v_cvt_f32_u32_e32 v8, s42
	s_sub_i32 s8, 0, s42
	v_add_lshl_u32 v2, v2, v3, 1
	v_mov_b32_e32 v3, v0
	v_rcp_iflag_f32_e32 v8, v8
	s_waitcnt vmcnt(6)
	v_lshl_add_u64 v[138:139], s[2:3], 0, v[2:3]
	v_add_u32_e32 v2, v7, v5
	v_mul_f32_e32 v8, 0x4f7ffffe, v8
	v_cvt_u32_f32_e32 v8, v8
	s_lshr_b32 s27, s64, 6
	s_lshr_b32 s35, s38, 3
	v_add_lshl_u32 v2, v2, v6, 1
	v_readfirstlane_b32 s9, v8
	s_mul_i32 s8, s8, s9
	s_mul_hi_u32 s8, s9, s8
	s_lshl_b32 s28, s11, 6
	s_lshl_b32 s29, s26, 5
	s_add_i32 s34, s27, -2
	s_mov_b32 s39, s93
	s_and_b32 s40, s38, 7
	s_add_i32 s41, s35, 1
	s_mov_b32 s43, 0
	s_add_i32 s44, s9, s8
	v_lshl_add_u64 v[140:141], s[2:3], 0, v[2:3]
	v_add_u32_e32 v150, 0, v22
	s_barrier
	v_add_u32_e32 v248, 0x10000, v149
	s_branch .LBB0_687

.LBB0_697:
	s_add_u32 s0, s0, 0x80
	s_addc_u32 s1, s1, 0
	s_add_u32 s48, s4, 0x100
	s_addc_u32 s49, s5, 0
	s_mov_b32 s4, 0
	s_waitcnt lgkmcnt(0)
	s_waitcnt vmcnt(0)
	s_add_i32 s65, s4, 2
	s_add_u32 s18, s0, 0x80
	s_addc_u32 s5, s1, 0
	s_add_i32 s66, 0, 0x10000
	ds_read_b128 v[142:145], v248
	ds_read_b128 v[152:155], v248 offset:1024
	ds_read_b128 v[156:159], v248 offset:2048
	ds_read_b128 v[160:163], v248 offset:3072
	s_cmp_eq_u32 s34, s4
	s_cselect_b32 s4, s10, s18
	s_cselect_b32 s5, s11, s5
	s_cselect_b32 s19, s13, s49
	s_cselect_b32 s18, s12, s48
	v_lshl_add_u64 v[146:147], s[0:1], 0, v[138:139]
	s_add_i32 m0, s22, 0xc000
	ds_read_b128 v[164:167], v150
	ds_read_b128 v[168:171], v150 offset:1024
	ds_read_b128 v[172:175], v150 offset:2048
	ds_read_b128 v[176:179], v150 offset:3072
	ds_read_b128 v[180:183], v150 offset:4096
	ds_read_b128 v[204:207], v150 offset:5120
	ds_read_b128 v[208:211], v150 offset:6144
	ds_read_b128 v[212:215], v150 offset:7168
	global_load_lds_dwordx4 v[146:147], off
	v_lshl_add_u64 v[146:147], s[0:1], 0, v[140:141]
	s_add_i32 m0, s22, 0xe000
	s_nop 0
	global_load_lds_dwordx4 v[146:147], off
	s_waitcnt lgkmcnt(8)
	s_barrier
	s_waitcnt lgkmcnt(0)
	v_mfma_f32_16x16x32_bf16 v[126:129], v[142:145], v[164:167], 0
	v_mfma_f32_16x16x32_bf16 v[122:125], v[156:159], v[164:167], 0
	v_mfma_f32_16x16x32_bf16 v[110:113], v[142:145], v[172:175], 0
	v_mfma_f32_16x16x32_bf16 v[106:109], v[156:159], v[172:175], 0
	v_mfma_f32_16x16x32_bf16 v[94:97], v[142:145], v[180:183], 0
	v_mfma_f32_16x16x32_bf16 v[90:93], v[156:159], v[180:183], 0
	v_mfma_f32_16x16x32_bf16 v[78:81], v[142:145], v[208:211], 0
	v_mfma_f32_16x16x32_bf16 v[74:77], v[156:159], v[208:211], 0
	v_mfma_f32_16x16x32_bf16 v[126:129], v[152:155], v[168:171], v[126:129]
	v_mfma_f32_16x16x32_bf16 v[122:125], v[160:163], v[168:171], v[122:125]
	v_mfma_f32_16x16x32_bf16 v[110:113], v[152:155], v[176:179], v[110:113]
	v_mfma_f32_16x16x32_bf16 v[106:109], v[160:163], v[176:179], v[106:109]
	v_mfma_f32_16x16x32_bf16 v[94:97], v[152:155], v[204:207], v[94:97]
	v_mfma_f32_16x16x32_bf16 v[90:93], v[160:163], v[204:207], v[90:93]
	v_mfma_f32_16x16x32_bf16 v[78:81], v[152:155], v[212:215], v[78:81]
	v_mfma_f32_16x16x32_bf16 v[74:77], v[160:163], v[212:215], v[74:77]
	s_barrier
	s_add_i32 s67, 0, 0x14000
	s_add_i32 s66, s66, s21
	ds_read_b128 v[216:219], v248 offset:16384
	ds_read_b128 v[220:223], v248 offset:17408
	ds_read_b128 v[224:227], v248 offset:18432
	ds_read_b128 v[228:231], v248 offset:19456
	s_add_u32 s70, s18, s6
	s_addc_u32 s71, s19, s7
	s_mov_b32 m0, s66
	s_nop 0
	global_load_lds_dwordx4 v132, s[18:19]
	s_add_i32 m0, s66, 0x2000
	s_nop 0
	global_load_lds_dwordx4 v136, s[18:19]
	s_barrier
	s_waitcnt lgkmcnt(0)
	v_mfma_f32_16x16x32_bf16 v[118:121], v[216:219], v[164:167], 0
	v_mfma_f32_16x16x32_bf16 v[114:117], v[224:227], v[164:167], 0
	v_mfma_f32_16x16x32_bf16 v[102:105], v[216:219], v[172:175], 0
	v_mfma_f32_16x16x32_bf16 v[98:101], v[224:227], v[172:175], 0
	v_mfma_f32_16x16x32_bf16 v[86:89], v[216:219], v[180:183], 0
	v_mfma_f32_16x16x32_bf16 v[82:85], v[224:227], v[180:183], 0
	v_mfma_f32_16x16x32_bf16 v[70:73], v[216:219], v[208:211], 0
	v_mfma_f32_16x16x32_bf16 v[66:69], v[224:227], v[208:211], 0
	v_mfma_f32_16x16x32_bf16 v[118:121], v[220:223], v[168:171], v[118:121]
	v_mfma_f32_16x16x32_bf16 v[114:117], v[228:231], v[168:171], v[114:117]
	v_mfma_f32_16x16x32_bf16 v[102:105], v[220:223], v[176:179], v[102:105]
	v_mfma_f32_16x16x32_bf16 v[98:101], v[228:231], v[176:179], v[98:101]
	v_mfma_f32_16x16x32_bf16 v[86:89], v[220:223], v[204:207], v[86:89]
	v_mfma_f32_16x16x32_bf16 v[82:85], v[228:231], v[204:207], v[82:85]
	v_mfma_f32_16x16x32_bf16 v[70:73], v[220:223], v[212:215], v[70:73]
	v_mfma_f32_16x16x32_bf16 v[66:69], v[228:231], v[212:215], v[66:69]
	s_barrier
	s_mov_b32 m0, s22
	s_add_u32 s72, s4, s6
	s_addc_u32 s73, s5, s7
	ds_read_b128 v[164:167], v150 offset:16384
	ds_read_b128 v[168:171], v150 offset:17408
	ds_read_b128 v[172:175], v150 offset:18432
	ds_read_b128 v[176:179], v150 offset:19456
	ds_read_b128 v[180:183], v150 offset:20480
	ds_read_b128 v[204:207], v150 offset:21504
	ds_read_b128 v[208:211], v150 offset:22528
	ds_read_b128 v[212:215], v150 offset:23552
	global_load_lds_dwordx4 v130, s[4:5]
	s_mov_b32 m0, s23
	s_nop 0
	global_load_lds_dwordx4 v134, s[4:5]
	s_barrier
	s_waitcnt lgkmcnt(0)
	v_mfma_f32_16x16x32_bf16 v[62:65], v[142:145], v[164:167], 0
	v_mfma_f32_16x16x32_bf16 v[58:61], v[156:159], v[164:167], 0
	v_mfma_f32_16x16x32_bf16 v[46:49], v[142:145], v[172:175], 0
	v_mfma_f32_16x16x32_bf16 v[42:45], v[156:159], v[172:175], 0
	v_mfma_f32_16x16x32_bf16 v[30:33], v[142:145], v[180:183], 0
	v_mfma_f32_16x16x32_bf16 v[26:29], v[156:159], v[180:183], 0
	v_mfma_f32_16x16x32_bf16 v[14:17], v[142:145], v[208:211], 0
	v_mfma_f32_16x16x32_bf16 v[10:13], v[156:159], v[208:211], 0
	v_mfma_f32_16x16x32_bf16 v[62:65], v[152:155], v[168:171], v[62:65]
	v_mfma_f32_16x16x32_bf16 v[58:61], v[160:163], v[168:171], v[58:61]
	v_mfma_f32_16x16x32_bf16 v[46:49], v[152:155], v[176:179], v[46:49]
	v_mfma_f32_16x16x32_bf16 v[42:45], v[160:163], v[176:179], v[42:45]
	v_mfma_f32_16x16x32_bf16 v[30:33], v[152:155], v[204:207], v[30:33]
	v_mfma_f32_16x16x32_bf16 v[26:29], v[160:163], v[204:207], v[26:29]
	v_mfma_f32_16x16x32_bf16 v[14:17], v[152:155], v[212:215], v[14:17]
	v_mfma_f32_16x16x32_bf16 v[10:13], v[160:163], v[212:215], v[10:13]
	s_barrier
	s_add_u32 s18, s18, s2
	s_addc_u32 s19, s19, 0
	s_add_i32 s66, s67, s21
	s_add_u32 s76, s18, s6
	s_addc_u32 s77, s19, s7
	s_mov_b32 m0, s66
	s_nop 0
	global_load_lds_dwordx4 v132, s[18:19]
	s_add_i32 m0, s66, 0x2000
	s_nop 0
	global_load_lds_dwordx4 v136, s[18:19]
	s_waitcnt vmcnt(6)
	s_barrier
	v_mfma_f32_16x16x32_bf16 v[54:57], v[216:219], v[164:167], 0
	v_mfma_f32_16x16x32_bf16 v[50:53], v[224:227], v[164:167], 0
	v_mfma_f32_16x16x32_bf16 v[38:41], v[216:219], v[172:175], 0
	v_mfma_f32_16x16x32_bf16 v[34:37], v[224:227], v[172:175], 0
	v_mfma_f32_16x16x32_bf16 v[22:25], v[216:219], v[180:183], 0
	v_mfma_f32_16x16x32_bf16 v[18:21], v[224:227], v[180:183], 0
	v_mfma_f32_16x16x32_bf16 v[6:9], v[216:219], v[208:211], 0
	v_mfma_f32_16x16x32_bf16 v[2:5], v[224:227], v[208:211], 0
	v_mfma_f32_16x16x32_bf16 v[54:57], v[220:223], v[168:171], v[54:57]
	v_mfma_f32_16x16x32_bf16 v[50:53], v[228:231], v[168:171], v[50:53]
	v_mfma_f32_16x16x32_bf16 v[38:41], v[220:223], v[176:179], v[38:41]
	v_mfma_f32_16x16x32_bf16 v[34:37], v[228:231], v[176:179], v[34:37]
	v_mfma_f32_16x16x32_bf16 v[22:25], v[220:223], v[204:207], v[22:25]
	v_mfma_f32_16x16x32_bf16 v[18:21], v[228:231], v[204:207], v[18:21]
	v_mfma_f32_16x16x32_bf16 v[6:9], v[220:223], v[212:215], v[6:9]
	v_mfma_f32_16x16x32_bf16 v[2:5], v[228:231], v[212:215], v[2:5]
	s_barrier
	s_add_i32 s18, 0, 0x18000
	ds_read_b128 v[142:145], v248 offset:32768
	ds_read_b128 v[152:155], v248 offset:33792
	ds_read_b128 v[156:159], v248 offset:34816
	ds_read_b128 v[160:163], v248 offset:35840
	s_add_u32 s4, s4, s2
	s_addc_u32 s5, s5, 0
	s_mov_b32 m0, s24
	ds_read_b128 v[164:167], v150 offset:32768
	ds_read_b128 v[168:171], v150 offset:33792
	ds_read_b128 v[172:175], v150 offset:34816
	ds_read_b128 v[176:179], v150 offset:35840
	ds_read_b128 v[180:183], v150 offset:36864
	ds_read_b128 v[204:207], v150 offset:37888
	ds_read_b128 v[208:211], v150 offset:38912
	ds_read_b128 v[212:215], v150 offset:39936
	global_load_lds_dwordx4 v130, s[4:5]
	s_mov_b32 m0, s25
	s_nop 0
	global_load_lds_dwordx4 v134, s[4:5]
	s_waitcnt lgkmcnt(8)
	s_barrier
	s_waitcnt lgkmcnt(0)
	v_mfma_f32_16x16x32_bf16 v[126:129], v[142:145], v[164:167], v[126:129]
	v_mfma_f32_16x16x32_bf16 v[122:125], v[156:159], v[164:167], v[122:125]
	v_mfma_f32_16x16x32_bf16 v[110:113], v[142:145], v[172:175], v[110:113]
	v_mfma_f32_16x16x32_bf16 v[106:109], v[156:159], v[172:175], v[106:109]
	v_mfma_f32_16x16x32_bf16 v[94:97], v[142:145], v[180:183], v[94:97]
	v_mfma_f32_16x16x32_bf16 v[90:93], v[156:159], v[180:183], v[90:93]
	v_mfma_f32_16x16x32_bf16 v[78:81], v[142:145], v[208:211], v[78:81]
	v_mfma_f32_16x16x32_bf16 v[74:77], v[156:159], v[208:211], v[74:77]
	v_mfma_f32_16x16x32_bf16 v[126:129], v[152:155], v[168:171], v[126:129]
	v_mfma_f32_16x16x32_bf16 v[122:125], v[160:163], v[168:171], v[122:125]
	v_mfma_f32_16x16x32_bf16 v[110:113], v[152:155], v[176:179], v[110:113]
	v_mfma_f32_16x16x32_bf16 v[106:109], v[160:163], v[176:179], v[106:109]
	v_mfma_f32_16x16x32_bf16 v[94:97], v[152:155], v[204:207], v[94:97]
	v_mfma_f32_16x16x32_bf16 v[90:93], v[160:163], v[204:207], v[90:93]
	v_mfma_f32_16x16x32_bf16 v[78:81], v[152:155], v[212:215], v[78:81]
	v_mfma_f32_16x16x32_bf16 v[74:77], v[160:163], v[212:215], v[74:77]
	s_barrier
	s_add_i32 s4, 0, 0x1c000
	s_add_i32 s5, s18, s21
	s_mov_b32 m0, s5
	ds_read_b128 v[216:219], v248 offset:49152
	ds_read_b128 v[220:223], v248 offset:50176
	ds_read_b128 v[224:227], v248 offset:51200
	ds_read_b128 v[228:231], v248 offset:52224
	global_load_lds_dwordx4 v132, s[70:71]
	s_add_i32 m0, s5, 0x2000
	s_nop 0
	global_load_lds_dwordx4 v136, s[70:71]
	s_barrier
	s_waitcnt lgkmcnt(0)
	v_mfma_f32_16x16x32_bf16 v[118:121], v[216:219], v[164:167], v[118:121]
	v_mfma_f32_16x16x32_bf16 v[114:117], v[224:227], v[164:167], v[114:117]
	v_mfma_f32_16x16x32_bf16 v[102:105], v[216:219], v[172:175], v[102:105]
	v_mfma_f32_16x16x32_bf16 v[98:101], v[224:227], v[172:175], v[98:101]
	v_mfma_f32_16x16x32_bf16 v[86:89], v[216:219], v[180:183], v[86:89]
	v_mfma_f32_16x16x32_bf16 v[82:85], v[224:227], v[180:183], v[82:85]
	v_mfma_f32_16x16x32_bf16 v[70:73], v[216:219], v[208:211], v[70:73]
	v_mfma_f32_16x16x32_bf16 v[66:69], v[224:227], v[208:211], v[66:69]
	v_mfma_f32_16x16x32_bf16 v[118:121], v[220:223], v[168:171], v[118:121]
	v_mfma_f32_16x16x32_bf16 v[114:117], v[228:231], v[168:171], v[114:117]
	v_mfma_f32_16x16x32_bf16 v[102:105], v[220:223], v[176:179], v[102:105]
	v_mfma_f32_16x16x32_bf16 v[98:101], v[228:231], v[176:179], v[98:101]
	v_mfma_f32_16x16x32_bf16 v[86:89], v[220:223], v[204:207], v[86:89]
	v_mfma_f32_16x16x32_bf16 v[82:85], v[228:231], v[204:207], v[82:85]
	v_mfma_f32_16x16x32_bf16 v[70:73], v[220:223], v[212:215], v[70:73]
	v_mfma_f32_16x16x32_bf16 v[66:69], v[228:231], v[212:215], v[66:69]
	s_barrier
	s_mov_b32 m0, s30
	ds_read_b128 v[164:167], v150 offset:49152
	ds_read_b128 v[168:171], v150 offset:50176
	ds_read_b128 v[172:175], v150 offset:51200
	ds_read_b128 v[176:179], v150 offset:52224
	ds_read_b128 v[180:183], v150 offset:53248
	ds_read_b128 v[204:207], v150 offset:54272
	ds_read_b128 v[208:211], v150 offset:55296
	ds_read_b128 v[212:215], v150 offset:56320
	global_load_lds_dwordx4 v130, s[72:73]
	s_mov_b32 m0, s31
	s_nop 0
	global_load_lds_dwordx4 v134, s[72:73]
	s_barrier
	s_waitcnt lgkmcnt(0)
	v_mfma_f32_16x16x32_bf16 v[62:65], v[142:145], v[164:167], v[62:65]
	v_mfma_f32_16x16x32_bf16 v[58:61], v[156:159], v[164:167], v[58:61]
	v_mfma_f32_16x16x32_bf16 v[46:49], v[142:145], v[172:175], v[46:49]
	v_mfma_f32_16x16x32_bf16 v[42:45], v[156:159], v[172:175], v[42:45]
	v_mfma_f32_16x16x32_bf16 v[30:33], v[142:145], v[180:183], v[30:33]
	v_mfma_f32_16x16x32_bf16 v[26:29], v[156:159], v[180:183], v[26:29]
	v_mfma_f32_16x16x32_bf16 v[14:17], v[142:145], v[208:211], v[14:17]
	v_mfma_f32_16x16x32_bf16 v[10:13], v[156:159], v[208:211], v[10:13]
	v_mfma_f32_16x16x32_bf16 v[62:65], v[152:155], v[168:171], v[62:65]
	v_mfma_f32_16x16x32_bf16 v[58:61], v[160:163], v[168:171], v[58:61]
	v_mfma_f32_16x16x32_bf16 v[46:49], v[152:155], v[176:179], v[46:49]
	v_mfma_f32_16x16x32_bf16 v[42:45], v[160:163], v[176:179], v[42:45]
	v_mfma_f32_16x16x32_bf16 v[30:33], v[152:155], v[204:207], v[30:33]
	v_mfma_f32_16x16x32_bf16 v[26:29], v[160:163], v[204:207], v[26:29]
	v_mfma_f32_16x16x32_bf16 v[14:17], v[152:155], v[212:215], v[14:17]
	v_mfma_f32_16x16x32_bf16 v[10:13], v[160:163], v[212:215], v[10:13]
	s_barrier
	s_add_i32 s4, s4, s21
	s_mov_b32 m0, s4
	s_nop 0
	global_load_lds_dwordx4 v132, s[76:77]
	s_add_i32 m0, s4, 0x2000
	s_nop 0
	global_load_lds_dwordx4 v136, s[76:77]
	s_add_u32 s0, s0, 0x100
	s_addc_u32 s1, s1, 0
	s_add_u32 s48, s48, 0x100
	s_addc_u32 s49, s49, 0
	s_cmp_ge_u32 s65, s27
	s_mov_b32 s4, s65
	s_waitcnt vmcnt(6)
	s_barrier
	v_mfma_f32_16x16x32_bf16 v[54:57], v[216:219], v[164:167], v[54:57]
	v_mfma_f32_16x16x32_bf16 v[50:53], v[224:227], v[164:167], v[50:53]
	v_mfma_f32_16x16x32_bf16 v[38:41], v[216:219], v[172:175], v[38:41]
	v_mfma_f32_16x16x32_bf16 v[34:37], v[224:227], v[172:175], v[34:37]
	v_mfma_f32_16x16x32_bf16 v[22:25], v[216:219], v[180:183], v[22:25]
	v_mfma_f32_16x16x32_bf16 v[18:21], v[224:227], v[180:183], v[18:21]
	v_mfma_f32_16x16x32_bf16 v[6:9], v[216:219], v[208:211], v[6:9]
	v_mfma_f32_16x16x32_bf16 v[2:5], v[224:227], v[208:211], v[2:5]
	v_mfma_f32_16x16x32_bf16 v[54:57], v[220:223], v[168:171], v[54:57]
	v_mfma_f32_16x16x32_bf16 v[50:53], v[228:231], v[168:171], v[50:53]
	v_mfma_f32_16x16x32_bf16 v[38:41], v[220:223], v[176:179], v[38:41]
	v_mfma_f32_16x16x32_bf16 v[34:37], v[228:231], v[176:179], v[34:37]
	v_mfma_f32_16x16x32_bf16 v[22:25], v[220:223], v[204:207], v[22:25]
	v_mfma_f32_16x16x32_bf16 v[18:21], v[228:231], v[204:207], v[18:21]
	v_mfma_f32_16x16x32_bf16 v[6:9], v[220:223], v[212:215], v[6:9]
	v_mfma_f32_16x16x32_bf16 v[2:5], v[228:231], v[212:215], v[2:5]
	s_barrier
	s_cbranch_scc1 .Lkexit_698
.LBB0_698:
	s_add_i32 s65, s4, 2
	s_add_u32 s18, s0, 0x80
	s_addc_u32 s5, s1, 0
	s_add_i32 s66, 0, 0x10000
	ds_read_b128 v[142:145], v248
	ds_read_b128 v[152:155], v248 offset:1024
	ds_read_b128 v[156:159], v248 offset:2048
	ds_read_b128 v[160:163], v248 offset:3072
	s_cmp_eq_u32 s34, s4
	s_cselect_b32 s4, s10, s18
	s_cselect_b32 s5, s11, s5
	s_cselect_b32 s19, s13, s49
	s_cselect_b32 s18, s12, s48
	v_lshl_add_u64 v[146:147], s[0:1], 0, v[138:139]
	s_add_i32 m0, s22, 0xc000
	ds_read_b128 v[164:167], v150
	ds_read_b128 v[168:171], v150 offset:1024
	ds_read_b128 v[172:175], v150 offset:2048
	ds_read_b128 v[176:179], v150 offset:3072
	ds_read_b128 v[180:183], v150 offset:4096
	ds_read_b128 v[204:207], v150 offset:5120
	ds_read_b128 v[208:211], v150 offset:6144
	ds_read_b128 v[212:215], v150 offset:7168
	global_load_lds_dwordx4 v[146:147], off
	v_lshl_add_u64 v[146:147], s[0:1], 0, v[140:141]
	s_add_i32 m0, s22, 0xe000
	s_nop 0
	global_load_lds_dwordx4 v[146:147], off
	s_waitcnt lgkmcnt(8)
	s_barrier
	s_waitcnt lgkmcnt(0)
	v_mfma_f32_16x16x32_bf16 v[126:129], v[142:145], v[164:167], v[126:129]
	v_mfma_f32_16x16x32_bf16 v[122:125], v[156:159], v[164:167], v[122:125]
	v_mfma_f32_16x16x32_bf16 v[110:113], v[142:145], v[172:175], v[110:113]
	v_mfma_f32_16x16x32_bf16 v[106:109], v[156:159], v[172:175], v[106:109]
	v_mfma_f32_16x16x32_bf16 v[94:97], v[142:145], v[180:183], v[94:97]
	v_mfma_f32_16x16x32_bf16 v[90:93], v[156:159], v[180:183], v[90:93]
	v_mfma_f32_16x16x32_bf16 v[78:81], v[142:145], v[208:211], v[78:81]
	v_mfma_f32_16x16x32_bf16 v[74:77], v[156:159], v[208:211], v[74:77]
	v_mfma_f32_16x16x32_bf16 v[126:129], v[152:155], v[168:171], v[126:129]
	v_mfma_f32_16x16x32_bf16 v[122:125], v[160:163], v[168:171], v[122:125]
	v_mfma_f32_16x16x32_bf16 v[110:113], v[152:155], v[176:179], v[110:113]
	v_mfma_f32_16x16x32_bf16 v[106:109], v[160:163], v[176:179], v[106:109]
	v_mfma_f32_16x16x32_bf16 v[94:97], v[152:155], v[204:207], v[94:97]
	v_mfma_f32_16x16x32_bf16 v[90:93], v[160:163], v[204:207], v[90:93]
	v_mfma_f32_16x16x32_bf16 v[78:81], v[152:155], v[212:215], v[78:81]
	v_mfma_f32_16x16x32_bf16 v[74:77], v[160:163], v[212:215], v[74:77]
	s_barrier
	s_add_i32 s67, 0, 0x14000
	s_add_i32 s66, s66, s21
	ds_read_b128 v[216:219], v248 offset:16384
	ds_read_b128 v[220:223], v248 offset:17408
	ds_read_b128 v[224:227], v248 offset:18432
	ds_read_b128 v[228:231], v248 offset:19456
	s_add_u32 s70, s18, s6
	s_addc_u32 s71, s19, s7
	s_mov_b32 m0, s66
	s_nop 0
	global_load_lds_dwordx4 v132, s[18:19]
	s_add_i32 m0, s66, 0x2000
	s_nop 0
	global_load_lds_dwordx4 v136, s[18:19]
	s_barrier
	s_waitcnt lgkmcnt(0)
	v_mfma_f32_16x16x32_bf16 v[118:121], v[216:219], v[164:167], v[118:121]
	v_mfma_f32_16x16x32_bf16 v[114:117], v[224:227], v[164:167], v[114:117]
	v_mfma_f32_16x16x32_bf16 v[102:105], v[216:219], v[172:175], v[102:105]
	v_mfma_f32_16x16x32_bf16 v[98:101], v[224:227], v[172:175], v[98:101]
	v_mfma_f32_16x16x32_bf16 v[86:89], v[216:219], v[180:183], v[86:89]
	v_mfma_f32_16x16x32_bf16 v[82:85], v[224:227], v[180:183], v[82:85]
	v_mfma_f32_16x16x32_bf16 v[70:73], v[216:219], v[208:211], v[70:73]
	v_mfma_f32_16x16x32_bf16 v[66:69], v[224:227], v[208:211], v[66:69]
	v_mfma_f32_16x16x32_bf16 v[118:121], v[220:223], v[168:171], v[118:121]
	v_mfma_f32_16x16x32_bf16 v[114:117], v[228:231], v[168:171], v[114:117]
	v_mfma_f32_16x16x32_bf16 v[102:105], v[220:223], v[176:179], v[102:105]
	v_mfma_f32_16x16x32_bf16 v[98:101], v[228:231], v[176:179], v[98:101]
	v_mfma_f32_16x16x32_bf16 v[86:89], v[220:223], v[204:207], v[86:89]
	v_mfma_f32_16x16x32_bf16 v[82:85], v[228:231], v[204:207], v[82:85]
	v_mfma_f32_16x16x32_bf16 v[70:73], v[220:223], v[212:215], v[70:73]
	v_mfma_f32_16x16x32_bf16 v[66:69], v[228:231], v[212:215], v[66:69]
	s_barrier
	s_mov_b32 m0, s22
	s_add_u32 s72, s4, s6
	s_addc_u32 s73, s5, s7
	ds_read_b128 v[164:167], v150 offset:16384
	ds_read_b128 v[168:171], v150 offset:17408
	ds_read_b128 v[172:175], v150 offset:18432
	ds_read_b128 v[176:179], v150 offset:19456
	ds_read_b128 v[180:183], v150 offset:20480
	ds_read_b128 v[204:207], v150 offset:21504
	ds_read_b128 v[208:211], v150 offset:22528
	ds_read_b128 v[212:215], v150 offset:23552
	global_load_lds_dwordx4 v130, s[4:5]
	s_mov_b32 m0, s23
	s_nop 0
	global_load_lds_dwordx4 v134, s[4:5]
	s_barrier
	s_waitcnt lgkmcnt(0)
	v_mfma_f32_16x16x32_bf16 v[62:65], v[142:145], v[164:167], v[62:65]
	v_mfma_f32_16x16x32_bf16 v[58:61], v[156:159], v[164:167], v[58:61]
	v_mfma_f32_16x16x32_bf16 v[46:49], v[142:145], v[172:175], v[46:49]
	v_mfma_f32_16x16x32_bf16 v[42:45], v[156:159], v[172:175], v[42:45]
	v_mfma_f32_16x16x32_bf16 v[30:33], v[142:145], v[180:183], v[30:33]
	v_mfma_f32_16x16x32_bf16 v[26:29], v[156:159], v[180:183], v[26:29]
	v_mfma_f32_16x16x32_bf16 v[14:17], v[142:145], v[208:211], v[14:17]
	v_mfma_f32_16x16x32_bf16 v[10:13], v[156:159], v[208:211], v[10:13]
	v_mfma_f32_16x16x32_bf16 v[62:65], v[152:155], v[168:171], v[62:65]
	v_mfma_f32_16x16x32_bf16 v[58:61], v[160:163], v[168:171], v[58:61]
	v_mfma_f32_16x16x32_bf16 v[46:49], v[152:155], v[176:179], v[46:49]
	v_mfma_f32_16x16x32_bf16 v[42:45], v[160:163], v[176:179], v[42:45]
	v_mfma_f32_16x16x32_bf16 v[30:33], v[152:155], v[204:207], v[30:33]
	v_mfma_f32_16x16x32_bf16 v[26:29], v[160:163], v[204:207], v[26:29]
	v_mfma_f32_16x16x32_bf16 v[14:17], v[152:155], v[212:215], v[14:17]
	v_mfma_f32_16x16x32_bf16 v[10:13], v[160:163], v[212:215], v[10:13]
	s_barrier
	s_add_u32 s18, s18, s2
	s_addc_u32 s19, s19, 0
	s_add_i32 s66, s67, s21
	s_add_u32 s76, s18, s6
	s_addc_u32 s77, s19, s7
	s_mov_b32 m0, s66
	s_nop 0
	global_load_lds_dwordx4 v132, s[18:19]
	s_add_i32 m0, s66, 0x2000
	s_nop 0
	global_load_lds_dwordx4 v136, s[18:19]
	s_waitcnt vmcnt(6)
	s_barrier
	v_mfma_f32_16x16x32_bf16 v[54:57], v[216:219], v[164:167], v[54:57]
	v_mfma_f32_16x16x32_bf16 v[50:53], v[224:227], v[164:167], v[50:53]
	v_mfma_f32_16x16x32_bf16 v[38:41], v[216:219], v[172:175], v[38:41]
	v_mfma_f32_16x16x32_bf16 v[34:37], v[224:227], v[172:175], v[34:37]
	v_mfma_f32_16x16x32_bf16 v[22:25], v[216:219], v[180:183], v[22:25]
	v_mfma_f32_16x16x32_bf16 v[18:21], v[224:227], v[180:183], v[18:21]
	v_mfma_f32_16x16x32_bf16 v[6:9], v[216:219], v[208:211], v[6:9]
	v_mfma_f32_16x16x32_bf16 v[2:5], v[224:227], v[208:211], v[2:5]
	v_mfma_f32_16x16x32_bf16 v[54:57], v[220:223], v[168:171], v[54:57]
	v_mfma_f32_16x16x32_bf16 v[50:53], v[228:231], v[168:171], v[50:53]
	v_mfma_f32_16x16x32_bf16 v[38:41], v[220:223], v[176:179], v[38:41]
	v_mfma_f32_16x16x32_bf16 v[34:37], v[228:231], v[176:179], v[34:37]
	v_mfma_f32_16x16x32_bf16 v[22:25], v[220:223], v[204:207], v[22:25]
	v_mfma_f32_16x16x32_bf16 v[18:21], v[228:231], v[204:207], v[18:21]
	v_mfma_f32_16x16x32_bf16 v[6:9], v[220:223], v[212:215], v[6:9]
	v_mfma_f32_16x16x32_bf16 v[2:5], v[228:231], v[212:215], v[2:5]
	s_barrier
	s_add_i32 s18, 0, 0x18000
	ds_read_b128 v[142:145], v248 offset:32768
	ds_read_b128 v[152:155], v248 offset:33792
	ds_read_b128 v[156:159], v248 offset:34816
	ds_read_b128 v[160:163], v248 offset:35840
	s_add_u32 s4, s4, s2
	s_addc_u32 s5, s5, 0
	s_mov_b32 m0, s24
	ds_read_b128 v[164:167], v150 offset:32768
	ds_read_b128 v[168:171], v150 offset:33792
	ds_read_b128 v[172:175], v150 offset:34816
	ds_read_b128 v[176:179], v150 offset:35840
	ds_read_b128 v[180:183], v150 offset:36864
	ds_read_b128 v[204:207], v150 offset:37888
	ds_read_b128 v[208:211], v150 offset:38912
	ds_read_b128 v[212:215], v150 offset:39936
	global_load_lds_dwordx4 v130, s[4:5]
	s_mov_b32 m0, s25
	s_nop 0
	global_load_lds_dwordx4 v134, s[4:5]
	s_waitcnt lgkmcnt(8)
	s_barrier
	s_waitcnt lgkmcnt(0)
	v_mfma_f32_16x16x32_bf16 v[126:129], v[142:145], v[164:167], v[126:129]
	v_mfma_f32_16x16x32_bf16 v[122:125], v[156:159], v[164:167], v[122:125]
	v_mfma_f32_16x16x32_bf16 v[110:113], v[142:145], v[172:175], v[110:113]
	v_mfma_f32_16x16x32_bf16 v[106:109], v[156:159], v[172:175], v[106:109]
	v_mfma_f32_16x16x32_bf16 v[94:97], v[142:145], v[180:183], v[94:97]
	v_mfma_f32_16x16x32_bf16 v[90:93], v[156:159], v[180:183], v[90:93]
	v_mfma_f32_16x16x32_bf16 v[78:81], v[142:145], v[208:211], v[78:81]
	v_mfma_f32_16x16x32_bf16 v[74:77], v[156:159], v[208:211], v[74:77]
	v_mfma_f32_16x16x32_bf16 v[126:129], v[152:155], v[168:171], v[126:129]
	v_mfma_f32_16x16x32_bf16 v[122:125], v[160:163], v[168:171], v[122:125]
	v_mfma_f32_16x16x32_bf16 v[110:113], v[152:155], v[176:179], v[110:113]
	v_mfma_f32_16x16x32_bf16 v[106:109], v[160:163], v[176:179], v[106:109]
	v_mfma_f32_16x16x32_bf16 v[94:97], v[152:155], v[204:207], v[94:97]
	v_mfma_f32_16x16x32_bf16 v[90:93], v[160:163], v[204:207], v[90:93]
	v_mfma_f32_16x16x32_bf16 v[78:81], v[152:155], v[212:215], v[78:81]
	v_mfma_f32_16x16x32_bf16 v[74:77], v[160:163], v[212:215], v[74:77]
	s_barrier
	s_add_i32 s4, 0, 0x1c000
	s_add_i32 s5, s18, s21
	s_mov_b32 m0, s5
	ds_read_b128 v[216:219], v248 offset:49152
	ds_read_b128 v[220:223], v248 offset:50176
	ds_read_b128 v[224:227], v248 offset:51200
	ds_read_b128 v[228:231], v248 offset:52224
	global_load_lds_dwordx4 v132, s[70:71]
	s_add_i32 m0, s5, 0x2000
	s_nop 0
	global_load_lds_dwordx4 v136, s[70:71]
	s_barrier
	s_waitcnt lgkmcnt(0)
	v_mfma_f32_16x16x32_bf16 v[118:121], v[216:219], v[164:167], v[118:121]
	v_mfma_f32_16x16x32_bf16 v[114:117], v[224:227], v[164:167], v[114:117]
	v_mfma_f32_16x16x32_bf16 v[102:105], v[216:219], v[172:175], v[102:105]
	v_mfma_f32_16x16x32_bf16 v[98:101], v[224:227], v[172:175], v[98:101]
	v_mfma_f32_16x16x32_bf16 v[86:89], v[216:219], v[180:183], v[86:89]
	v_mfma_f32_16x16x32_bf16 v[82:85], v[224:227], v[180:183], v[82:85]
	v_mfma_f32_16x16x32_bf16 v[70:73], v[216:219], v[208:211], v[70:73]
	v_mfma_f32_16x16x32_bf16 v[66:69], v[224:227], v[208:211], v[66:69]
	v_mfma_f32_16x16x32_bf16 v[118:121], v[220:223], v[168:171], v[118:121]
	v_mfma_f32_16x16x32_bf16 v[114:117], v[228:231], v[168:171], v[114:117]
	v_mfma_f32_16x16x32_bf16 v[102:105], v[220:223], v[176:179], v[102:105]
	v_mfma_f32_16x16x32_bf16 v[98:101], v[228:231], v[176:179], v[98:101]
	v_mfma_f32_16x16x32_bf16 v[86:89], v[220:223], v[204:207], v[86:89]
	v_mfma_f32_16x16x32_bf16 v[82:85], v[228:231], v[204:207], v[82:85]
	v_mfma_f32_16x16x32_bf16 v[70:73], v[220:223], v[212:215], v[70:73]
	v_mfma_f32_16x16x32_bf16 v[66:69], v[228:231], v[212:215], v[66:69]
	s_barrier
	s_mov_b32 m0, s30
	ds_read_b128 v[164:167], v150 offset:49152
	ds_read_b128 v[168:171], v150 offset:50176
	ds_read_b128 v[172:175], v150 offset:51200
	ds_read_b128 v[176:179], v150 offset:52224
	ds_read_b128 v[180:183], v150 offset:53248
	ds_read_b128 v[204:207], v150 offset:54272
	ds_read_b128 v[208:211], v150 offset:55296
	ds_read_b128 v[212:215], v150 offset:56320
	global_load_lds_dwordx4 v130, s[72:73]
	s_mov_b32 m0, s31
	s_nop 0
	global_load_lds_dwordx4 v134, s[72:73]
	s_barrier
	s_waitcnt lgkmcnt(0)
	v_mfma_f32_16x16x32_bf16 v[62:65], v[142:145], v[164:167], v[62:65]
	v_mfma_f32_16x16x32_bf16 v[58:61], v[156:159], v[164:167], v[58:61]
	v_mfma_f32_16x16x32_bf16 v[46:49], v[142:145], v[172:175], v[46:49]
	v_mfma_f32_16x16x32_bf16 v[42:45], v[156:159], v[172:175], v[42:45]
	v_mfma_f32_16x16x32_bf16 v[30:33], v[142:145], v[180:183], v[30:33]
	v_mfma_f32_16x16x32_bf16 v[26:29], v[156:159], v[180:183], v[26:29]
	v_mfma_f32_16x16x32_bf16 v[14:17], v[142:145], v[208:211], v[14:17]
	v_mfma_f32_16x16x32_bf16 v[10:13], v[156:159], v[208:211], v[10:13]
	v_mfma_f32_16x16x32_bf16 v[62:65], v[152:155], v[168:171], v[62:65]
	v_mfma_f32_16x16x32_bf16 v[58:61], v[160:163], v[168:171], v[58:61]
	v_mfma_f32_16x16x32_bf16 v[46:49], v[152:155], v[176:179], v[46:49]
	v_mfma_f32_16x16x32_bf16 v[42:45], v[160:163], v[176:179], v[42:45]
	v_mfma_f32_16x16x32_bf16 v[30:33], v[152:155], v[204:207], v[30:33]
	v_mfma_f32_16x16x32_bf16 v[26:29], v[160:163], v[204:207], v[26:29]
	v_mfma_f32_16x16x32_bf16 v[14:17], v[152:155], v[212:215], v[14:17]
	v_mfma_f32_16x16x32_bf16 v[10:13], v[160:163], v[212:215], v[10:13]
	s_barrier
	s_add_i32 s4, s4, s21
	s_mov_b32 m0, s4
	s_nop 0
	global_load_lds_dwordx4 v132, s[76:77]
	s_add_i32 m0, s4, 0x2000
	s_nop 0
	global_load_lds_dwordx4 v136, s[76:77]
	s_add_u32 s0, s0, 0x100
	s_addc_u32 s1, s1, 0
	s_add_u32 s48, s48, 0x100
	s_addc_u32 s49, s49, 0
	s_cmp_ge_u32 s65, s27
	s_mov_b32 s4, s65
	s_waitcnt vmcnt(6)
	s_barrier
	v_mfma_f32_16x16x32_bf16 v[54:57], v[216:219], v[164:167], v[54:57]
	v_mfma_f32_16x16x32_bf16 v[50:53], v[224:227], v[164:167], v[50:53]
	v_mfma_f32_16x16x32_bf16 v[38:41], v[216:219], v[172:175], v[38:41]
	v_mfma_f32_16x16x32_bf16 v[34:37], v[224:227], v[172:175], v[34:37]
	v_mfma_f32_16x16x32_bf16 v[22:25], v[216:219], v[180:183], v[22:25]
	v_mfma_f32_16x16x32_bf16 v[18:21], v[224:227], v[180:183], v[18:21]
	v_mfma_f32_16x16x32_bf16 v[6:9], v[216:219], v[208:211], v[6:9]
	v_mfma_f32_16x16x32_bf16 v[2:5], v[224:227], v[208:211], v[2:5]
	v_mfma_f32_16x16x32_bf16 v[54:57], v[220:223], v[168:171], v[54:57]
	v_mfma_f32_16x16x32_bf16 v[50:53], v[228:231], v[168:171], v[50:53]
	v_mfma_f32_16x16x32_bf16 v[38:41], v[220:223], v[176:179], v[38:41]
	v_mfma_f32_16x16x32_bf16 v[34:37], v[228:231], v[176:179], v[34:37]
	v_mfma_f32_16x16x32_bf16 v[22:25], v[220:223], v[204:207], v[22:25]
	v_mfma_f32_16x16x32_bf16 v[18:21], v[228:231], v[204:207], v[18:21]
	v_mfma_f32_16x16x32_bf16 v[6:9], v[220:223], v[212:215], v[6:9]
	v_mfma_f32_16x16x32_bf16 v[2:5], v[228:231], v[212:215], v[2:5]
	s_barrier
	s_cbranch_scc0 .LBB0_698

.LBB0_729:
	v_bfe_u32 v1, v19, 4, 2
	s_waitcnt vmcnt(0)
	v_and_b32_e32 v164, 15, v19
	v_lshlrev_b32_e32 v21, 4, v1
	v_lshlrev_b32_e32 v19, 2, v19
	s_and_b32 s10, s10, 3
	v_lshl_or_b32 v21, v164, 6, v21
	s_lshl_b32 s11, s9, 13
	v_and_b32_e32 v19, 32, v19
	s_lshr_b32 s35, s64, 6
	s_lshl_b32 s40, s9, 6
	v_bitop3_b32 v22, v21, s11, v19 bitop3:0xde
	s_lshl_b32 s11, s10, 12
	s_lshl_b32 s8, s8, 2
	v_readlane_b32 s12, v241, 53
	v_readlane_b32 s13, v241, 54
	s_add_u32 s18, s12, s8
	s_addc_u32 s19, s13, 0
	s_add_i32 m0, s29, 0x18000
	v_lshl_add_u64 v[2:3], v[2:3], 0, s[6:7]
	s_waitcnt vmcnt(4)
	s_barrier
	global_load_lds_dwordx4 v[2:3], off
	v_lshl_add_u64 v[2:3], v[4:5], 0, s[6:7]
	s_add_i32 m0, s29, 0x1a000
	s_add_i32 s41, s29, 0x8000
	global_load_lds_dwordx4 v[2:3], off
	v_lshl_add_u64 v[2:3], v[6:7], 0, s[6:7]
	s_mov_b32 m0, s41
	s_add_i32 s42, s29, 0xa000
	global_load_lds_dwordx4 v[2:3], off
	v_lshl_add_u64 v[2:3], v[8:9], 0, s[6:7]
	s_mov_b32 m0, s42
	s_lshl_b32 s48, s57, 3
	global_load_lds_dwordx4 v[2:3], off
	s_add_i32 m0, s29, 0x1c000
	v_lshl_add_u64 v[2:3], v[10:11], 0, s[6:7]
	global_load_lds_dwordx4 v[2:3], off
	v_lshl_add_u64 v[2:3], v[12:13], 0, s[6:7]
	s_add_i32 m0, s29, 0x1e000
	s_lshl_b32 s8, s9, 11
	global_load_lds_dwordx4 v[2:3], off
	v_cvt_f32_u32_e32 v2, s48
	s_lshl_b32 s9, s10, 9
	s_add_i32 s8, s8, 0
	s_lshr_b32 s45, s38, 3
	v_rcp_iflag_f32_e32 v2, v2
	s_add_i32 s49, s8, s9
	v_bitop3_b32 v165, v21, s11, v19 bitop3:0xde
	s_add_i32 s43, s35, -2
	v_mul_f32_e32 v2, 0x4f7ffffe, v2
	v_cvt_u32_f32_e32 v2, v2
	s_lshl_b32 s44, s10, 6
	s_and_b32 s46, s38, 7
	s_add_i32 s47, s45, 1
	s_add_i32 s49, s49, 0x20000
	s_lshl_b32 s8, s10, 7
	v_readlane_b32 s10, v243, 29
	v_readlane_b32 s11, v243, 30
	s_add_u32 s20, s10, s8
	v_readfirstlane_b32 s9, v2
	v_add_u32_e32 v2, v16, v14
	s_addc_u32 s21, s11, 0
	s_sub_i32 s8, 0, s48
	v_add_lshl_u32 v2, v2, v15, 1
	v_mov_b32_e32 v3, v0
	s_waitcnt vmcnt(6)
	s_mul_i32 s8, s8, s9
	v_lshl_add_u64 v[138:139], s[2:3], 0, v[2:3]
	v_add_u32_e32 v2, v20, v17
	s_mul_hi_u32 s8, s9, s8
	v_add_lshl_u32 v2, v2, v18, 1
	s_mov_b32 s39, s93
	s_mov_b32 s67, 0
	s_add_i32 s68, s9, s8
	v_lshl_add_u64 v[140:141], s[2:3], 0, v[2:3]
	s_mov_b32 s25, -1
	v_add_u32_e32 v166, 0, v22
	s_barrier
	v_add_u32_e32 v248, 0x10000, v165
	s_branch .LBB0_731

.LBB0_741:
	s_add_u32 s0, s0, 0x80
	s_addc_u32 s1, s1, 0
	s_add_u32 s65, s4, 0x100
	s_addc_u32 s66, s5, 0
	s_mov_b32 s4, 0
	s_add_i32 s70, s4, 2
	s_add_u32 s10, s0, 0x80
	s_addc_u32 s5, s1, 0
	s_add_i32 s71, 0, 0x10000
	ds_read_b128 v[142:145], v248
	ds_read_b128 v[146:149], v248 offset:1024
	ds_read_b128 v[150:153], v248 offset:2048
	ds_read_b128 v[154:157], v248 offset:3072
	s_cmp_eq_u32 s43, s4
	s_cselect_b32 s4, s22, s10
	s_cselect_b32 s5, s23, s5
	s_cselect_b32 s11, s13, s66
	s_cselect_b32 s10, s12, s65
	v_lshl_add_u64 v[162:163], s[0:1], 0, v[138:139]
	s_add_i32 m0, s29, 0xc000
	ds_read_b128 v[158:161], v166
	ds_read_b128 v[168:171], v166 offset:1024
	ds_read_b128 v[172:175], v166 offset:2048
	ds_read_b128 v[176:179], v166 offset:3072
	ds_read_b128 v[180:183], v166 offset:4096
	ds_read_b128 v[204:207], v166 offset:5120
	ds_read_b128 v[208:211], v166 offset:6144
	ds_read_b128 v[212:215], v166 offset:7168
	global_load_lds_dwordx4 v[162:163], off
	v_lshl_add_u64 v[162:163], s[0:1], 0, v[140:141]
	s_add_i32 m0, s29, 0xe000
	s_nop 0
	global_load_lds_dwordx4 v[162:163], off
	s_waitcnt lgkmcnt(8)
	s_barrier
	s_waitcnt lgkmcnt(0)
	v_mfma_f32_16x16x32_bf16 v[126:129], v[142:145], v[158:161], 0
	v_mfma_f32_16x16x32_bf16 v[122:125], v[150:153], v[158:161], 0
	v_mfma_f32_16x16x32_bf16 v[110:113], v[142:145], v[172:175], 0
	v_mfma_f32_16x16x32_bf16 v[106:109], v[150:153], v[172:175], 0
	v_mfma_f32_16x16x32_bf16 v[94:97], v[142:145], v[180:183], 0
	v_mfma_f32_16x16x32_bf16 v[90:93], v[150:153], v[180:183], 0
	v_mfma_f32_16x16x32_bf16 v[78:81], v[142:145], v[208:211], 0
	v_mfma_f32_16x16x32_bf16 v[74:77], v[150:153], v[208:211], 0
	v_mfma_f32_16x16x32_bf16 v[126:129], v[146:149], v[168:171], v[126:129]
	v_mfma_f32_16x16x32_bf16 v[122:125], v[154:157], v[168:171], v[122:125]
	v_mfma_f32_16x16x32_bf16 v[110:113], v[146:149], v[176:179], v[110:113]
	v_mfma_f32_16x16x32_bf16 v[106:109], v[154:157], v[176:179], v[106:109]
	v_mfma_f32_16x16x32_bf16 v[94:97], v[146:149], v[204:207], v[94:97]
	v_mfma_f32_16x16x32_bf16 v[90:93], v[154:157], v[204:207], v[90:93]
	v_mfma_f32_16x16x32_bf16 v[78:81], v[146:149], v[212:215], v[78:81]
	v_mfma_f32_16x16x32_bf16 v[74:77], v[154:157], v[212:215], v[74:77]
	s_barrier
	s_add_i32 s72, 0, 0x14000
	s_add_i32 s71, s71, s28
	ds_read_b128 v[216:219], v248 offset:16384
	ds_read_b128 v[220:223], v248 offset:17408
	ds_read_b128 v[224:227], v248 offset:18432
	ds_read_b128 v[228:231], v248 offset:19456
	s_add_u32 s76, s10, s6
	s_addc_u32 s77, s11, s7
	s_mov_b32 m0, s71
	s_nop 0
	global_load_lds_dwordx4 v132, s[10:11]
	s_add_i32 m0, s71, 0x2000
	s_nop 0
	global_load_lds_dwordx4 v136, s[10:11]
	s_barrier
	s_waitcnt lgkmcnt(0)
	v_mfma_f32_16x16x32_bf16 v[118:121], v[216:219], v[158:161], 0
	v_mfma_f32_16x16x32_bf16 v[114:117], v[224:227], v[158:161], 0
	v_mfma_f32_16x16x32_bf16 v[102:105], v[216:219], v[172:175], 0
	v_mfma_f32_16x16x32_bf16 v[98:101], v[224:227], v[172:175], 0
	v_mfma_f32_16x16x32_bf16 v[86:89], v[216:219], v[180:183], 0
	v_mfma_f32_16x16x32_bf16 v[82:85], v[224:227], v[180:183], 0
	v_mfma_f32_16x16x32_bf16 v[70:73], v[216:219], v[208:211], 0
	v_mfma_f32_16x16x32_bf16 v[66:69], v[224:227], v[208:211], 0
	v_mfma_f32_16x16x32_bf16 v[118:121], v[220:223], v[168:171], v[118:121]
	v_mfma_f32_16x16x32_bf16 v[114:117], v[228:231], v[168:171], v[114:117]
	v_mfma_f32_16x16x32_bf16 v[102:105], v[220:223], v[176:179], v[102:105]
	v_mfma_f32_16x16x32_bf16 v[98:101], v[228:231], v[176:179], v[98:101]
	v_mfma_f32_16x16x32_bf16 v[86:89], v[220:223], v[204:207], v[86:89]
	v_mfma_f32_16x16x32_bf16 v[82:85], v[228:231], v[204:207], v[82:85]
	v_mfma_f32_16x16x32_bf16 v[70:73], v[220:223], v[212:215], v[70:73]
	v_mfma_f32_16x16x32_bf16 v[66:69], v[228:231], v[212:215], v[66:69]
	s_barrier
	s_mov_b32 m0, s29
	s_add_u32 s78, s4, s6
	s_addc_u32 s79, s5, s7
	ds_read_b128 v[158:161], v166 offset:16384
	ds_read_b128 v[168:171], v166 offset:17408
	ds_read_b128 v[172:175], v166 offset:18432
	ds_read_b128 v[176:179], v166 offset:19456
	ds_read_b128 v[180:183], v166 offset:20480
	ds_read_b128 v[204:207], v166 offset:21504
	ds_read_b128 v[208:211], v166 offset:22528
	ds_read_b128 v[212:215], v166 offset:23552
	global_load_lds_dwordx4 v130, s[4:5]
	s_mov_b32 m0, s30
	s_nop 0
	global_load_lds_dwordx4 v134, s[4:5]
	s_barrier
	s_waitcnt lgkmcnt(0)
	v_mfma_f32_16x16x32_bf16 v[62:65], v[142:145], v[158:161], 0
	v_mfma_f32_16x16x32_bf16 v[58:61], v[150:153], v[158:161], 0
	v_mfma_f32_16x16x32_bf16 v[46:49], v[142:145], v[172:175], 0
	v_mfma_f32_16x16x32_bf16 v[42:45], v[150:153], v[172:175], 0
	v_mfma_f32_16x16x32_bf16 v[30:33], v[142:145], v[180:183], 0
	v_mfma_f32_16x16x32_bf16 v[26:29], v[150:153], v[180:183], 0
	v_mfma_f32_16x16x32_bf16 v[14:17], v[142:145], v[208:211], 0
	v_mfma_f32_16x16x32_bf16 v[10:13], v[150:153], v[208:211], 0
	v_mfma_f32_16x16x32_bf16 v[62:65], v[146:149], v[168:171], v[62:65]
	v_mfma_f32_16x16x32_bf16 v[58:61], v[154:157], v[168:171], v[58:61]
	v_mfma_f32_16x16x32_bf16 v[46:49], v[146:149], v[176:179], v[46:49]
	v_mfma_f32_16x16x32_bf16 v[42:45], v[154:157], v[176:179], v[42:45]
	v_mfma_f32_16x16x32_bf16 v[30:33], v[146:149], v[204:207], v[30:33]
	v_mfma_f32_16x16x32_bf16 v[26:29], v[154:157], v[204:207], v[26:29]
	v_mfma_f32_16x16x32_bf16 v[14:17], v[146:149], v[212:215], v[14:17]
	v_mfma_f32_16x16x32_bf16 v[10:13], v[154:157], v[212:215], v[10:13]
	s_barrier
	s_add_u32 s10, s10, s2
	s_addc_u32 s11, s11, 0
	s_add_i32 s71, s72, s28
	s_add_u32 s80, s10, s6
	s_addc_u32 s81, s11, s7
	s_mov_b32 m0, s71
	s_nop 0
	global_load_lds_dwordx4 v132, s[10:11]
	s_add_i32 m0, s71, 0x2000
	s_nop 0
	global_load_lds_dwordx4 v136, s[10:11]
	s_waitcnt vmcnt(6)
	s_barrier
	v_mfma_f32_16x16x32_bf16 v[54:57], v[216:219], v[158:161], 0
	v_mfma_f32_16x16x32_bf16 v[50:53], v[224:227], v[158:161], 0
	v_mfma_f32_16x16x32_bf16 v[38:41], v[216:219], v[172:175], 0
	v_mfma_f32_16x16x32_bf16 v[34:37], v[224:227], v[172:175], 0
	v_mfma_f32_16x16x32_bf16 v[22:25], v[216:219], v[180:183], 0
	v_mfma_f32_16x16x32_bf16 v[18:21], v[224:227], v[180:183], 0
	v_mfma_f32_16x16x32_bf16 v[6:9], v[216:219], v[208:211], 0
	v_mfma_f32_16x16x32_bf16 v[2:5], v[224:227], v[208:211], 0
	v_mfma_f32_16x16x32_bf16 v[54:57], v[220:223], v[168:171], v[54:57]
	v_mfma_f32_16x16x32_bf16 v[50:53], v[228:231], v[168:171], v[50:53]
	v_mfma_f32_16x16x32_bf16 v[38:41], v[220:223], v[176:179], v[38:41]
	v_mfma_f32_16x16x32_bf16 v[34:37], v[228:231], v[176:179], v[34:37]
	v_mfma_f32_16x16x32_bf16 v[22:25], v[220:223], v[204:207], v[22:25]
	v_mfma_f32_16x16x32_bf16 v[18:21], v[228:231], v[204:207], v[18:21]
	v_mfma_f32_16x16x32_bf16 v[6:9], v[220:223], v[212:215], v[6:9]
	v_mfma_f32_16x16x32_bf16 v[2:5], v[228:231], v[212:215], v[2:5]
	s_barrier
	s_add_i32 s10, 0, 0x18000
	ds_read_b128 v[142:145], v248 offset:32768
	ds_read_b128 v[146:149], v248 offset:33792
	ds_read_b128 v[150:153], v248 offset:34816
	ds_read_b128 v[154:157], v248 offset:35840
	s_add_u32 s4, s4, s2
	s_addc_u32 s5, s5, 0
	s_mov_b32 m0, s31
	ds_read_b128 v[158:161], v166 offset:32768
	ds_read_b128 v[168:171], v166 offset:33792
	ds_read_b128 v[172:175], v166 offset:34816
	ds_read_b128 v[176:179], v166 offset:35840
	ds_read_b128 v[180:183], v166 offset:36864
	ds_read_b128 v[204:207], v166 offset:37888
	ds_read_b128 v[208:211], v166 offset:38912
	ds_read_b128 v[212:215], v166 offset:39936
	global_load_lds_dwordx4 v130, s[4:5]
	s_mov_b32 m0, s34
	s_nop 0
	global_load_lds_dwordx4 v134, s[4:5]
	s_waitcnt lgkmcnt(8)
	s_barrier
	s_waitcnt lgkmcnt(0)
	v_mfma_f32_16x16x32_bf16 v[126:129], v[142:145], v[158:161], v[126:129]
	v_mfma_f32_16x16x32_bf16 v[122:125], v[150:153], v[158:161], v[122:125]
	v_mfma_f32_16x16x32_bf16 v[110:113], v[142:145], v[172:175], v[110:113]
	v_mfma_f32_16x16x32_bf16 v[106:109], v[150:153], v[172:175], v[106:109]
	v_mfma_f32_16x16x32_bf16 v[94:97], v[142:145], v[180:183], v[94:97]
	v_mfma_f32_16x16x32_bf16 v[90:93], v[150:153], v[180:183], v[90:93]
	v_mfma_f32_16x16x32_bf16 v[78:81], v[142:145], v[208:211], v[78:81]
	v_mfma_f32_16x16x32_bf16 v[74:77], v[150:153], v[208:211], v[74:77]
	v_mfma_f32_16x16x32_bf16 v[126:129], v[146:149], v[168:171], v[126:129]
	v_mfma_f32_16x16x32_bf16 v[122:125], v[154:157], v[168:171], v[122:125]
	v_mfma_f32_16x16x32_bf16 v[110:113], v[146:149], v[176:179], v[110:113]
	v_mfma_f32_16x16x32_bf16 v[106:109], v[154:157], v[176:179], v[106:109]
	v_mfma_f32_16x16x32_bf16 v[94:97], v[146:149], v[204:207], v[94:97]
	v_mfma_f32_16x16x32_bf16 v[90:93], v[154:157], v[204:207], v[90:93]
	v_mfma_f32_16x16x32_bf16 v[78:81], v[146:149], v[212:215], v[78:81]
	v_mfma_f32_16x16x32_bf16 v[74:77], v[154:157], v[212:215], v[74:77]
	s_barrier
	s_add_i32 s4, 0, 0x1c000
	s_add_i32 s5, s10, s28
	s_mov_b32 m0, s5
	ds_read_b128 v[216:219], v248 offset:49152
	ds_read_b128 v[220:223], v248 offset:50176
	ds_read_b128 v[224:227], v248 offset:51200
	ds_read_b128 v[228:231], v248 offset:52224
	global_load_lds_dwordx4 v132, s[76:77]
	s_add_i32 m0, s5, 0x2000
	s_nop 0
	global_load_lds_dwordx4 v136, s[76:77]
	s_barrier
	s_waitcnt lgkmcnt(0)
	v_mfma_f32_16x16x32_bf16 v[118:121], v[216:219], v[158:161], v[118:121]
	v_mfma_f32_16x16x32_bf16 v[114:117], v[224:227], v[158:161], v[114:117]
	v_mfma_f32_16x16x32_bf16 v[102:105], v[216:219], v[172:175], v[102:105]
	v_mfma_f32_16x16x32_bf16 v[98:101], v[224:227], v[172:175], v[98:101]
	v_mfma_f32_16x16x32_bf16 v[86:89], v[216:219], v[180:183], v[86:89]
	v_mfma_f32_16x16x32_bf16 v[82:85], v[224:227], v[180:183], v[82:85]
	v_mfma_f32_16x16x32_bf16 v[70:73], v[216:219], v[208:211], v[70:73]
	v_mfma_f32_16x16x32_bf16 v[66:69], v[224:227], v[208:211], v[66:69]
	v_mfma_f32_16x16x32_bf16 v[118:121], v[220:223], v[168:171], v[118:121]
	v_mfma_f32_16x16x32_bf16 v[114:117], v[228:231], v[168:171], v[114:117]
	v_mfma_f32_16x16x32_bf16 v[102:105], v[220:223], v[176:179], v[102:105]
	v_mfma_f32_16x16x32_bf16 v[98:101], v[228:231], v[176:179], v[98:101]
	v_mfma_f32_16x16x32_bf16 v[86:89], v[220:223], v[204:207], v[86:89]
	v_mfma_f32_16x16x32_bf16 v[82:85], v[228:231], v[204:207], v[82:85]
	v_mfma_f32_16x16x32_bf16 v[70:73], v[220:223], v[212:215], v[70:73]
	v_mfma_f32_16x16x32_bf16 v[66:69], v[228:231], v[212:215], v[66:69]
	s_barrier
	s_mov_b32 m0, s41
	ds_read_b128 v[158:161], v166 offset:49152
	ds_read_b128 v[168:171], v166 offset:50176
	ds_read_b128 v[172:175], v166 offset:51200
	ds_read_b128 v[176:179], v166 offset:52224
	ds_read_b128 v[180:183], v166 offset:53248
	ds_read_b128 v[204:207], v166 offset:54272
	ds_read_b128 v[208:211], v166 offset:55296
	ds_read_b128 v[212:215], v166 offset:56320
	global_load_lds_dwordx4 v130, s[78:79]
	s_mov_b32 m0, s42
	s_nop 0
	global_load_lds_dwordx4 v134, s[78:79]
	s_barrier
	s_waitcnt lgkmcnt(0)
	v_mfma_f32_16x16x32_bf16 v[62:65], v[142:145], v[158:161], v[62:65]
	v_mfma_f32_16x16x32_bf16 v[58:61], v[150:153], v[158:161], v[58:61]
	v_mfma_f32_16x16x32_bf16 v[46:49], v[142:145], v[172:175], v[46:49]
	v_mfma_f32_16x16x32_bf16 v[42:45], v[150:153], v[172:175], v[42:45]
	v_mfma_f32_16x16x32_bf16 v[30:33], v[142:145], v[180:183], v[30:33]
	v_mfma_f32_16x16x32_bf16 v[26:29], v[150:153], v[180:183], v[26:29]
	v_mfma_f32_16x16x32_bf16 v[14:17], v[142:145], v[208:211], v[14:17]
	v_mfma_f32_16x16x32_bf16 v[10:13], v[150:153], v[208:211], v[10:13]
	v_mfma_f32_16x16x32_bf16 v[62:65], v[146:149], v[168:171], v[62:65]
	v_mfma_f32_16x16x32_bf16 v[58:61], v[154:157], v[168:171], v[58:61]
	v_mfma_f32_16x16x32_bf16 v[46:49], v[146:149], v[176:179], v[46:49]
	v_mfma_f32_16x16x32_bf16 v[42:45], v[154:157], v[176:179], v[42:45]
	v_mfma_f32_16x16x32_bf16 v[30:33], v[146:149], v[204:207], v[30:33]
	v_mfma_f32_16x16x32_bf16 v[26:29], v[154:157], v[204:207], v[26:29]
	v_mfma_f32_16x16x32_bf16 v[14:17], v[146:149], v[212:215], v[14:17]
	v_mfma_f32_16x16x32_bf16 v[10:13], v[154:157], v[212:215], v[10:13]
	s_barrier
	s_add_i32 s4, s4, s28
	s_mov_b32 m0, s4
	s_nop 0
	global_load_lds_dwordx4 v132, s[80:81]
	s_add_i32 m0, s4, 0x2000
	s_nop 0
	global_load_lds_dwordx4 v136, s[80:81]
	s_add_u32 s0, s0, 0x100
	s_addc_u32 s1, s1, 0
	s_add_u32 s65, s65, 0x100
	s_addc_u32 s66, s66, 0
	s_cmp_ge_u32 s70, s35
	s_mov_b32 s4, s70
	s_waitcnt vmcnt(6)
	s_barrier
	v_mfma_f32_16x16x32_bf16 v[54:57], v[216:219], v[158:161], v[54:57]
	v_mfma_f32_16x16x32_bf16 v[50:53], v[224:227], v[158:161], v[50:53]
	v_mfma_f32_16x16x32_bf16 v[38:41], v[216:219], v[172:175], v[38:41]
	v_mfma_f32_16x16x32_bf16 v[34:37], v[224:227], v[172:175], v[34:37]
	v_mfma_f32_16x16x32_bf16 v[22:25], v[216:219], v[180:183], v[22:25]
	v_mfma_f32_16x16x32_bf16 v[18:21], v[224:227], v[180:183], v[18:21]
	v_mfma_f32_16x16x32_bf16 v[6:9], v[216:219], v[208:211], v[6:9]
	v_mfma_f32_16x16x32_bf16 v[2:5], v[224:227], v[208:211], v[2:5]
	v_mfma_f32_16x16x32_bf16 v[54:57], v[220:223], v[168:171], v[54:57]
	v_mfma_f32_16x16x32_bf16 v[50:53], v[228:231], v[168:171], v[50:53]
	v_mfma_f32_16x16x32_bf16 v[38:41], v[220:223], v[176:179], v[38:41]
	v_mfma_f32_16x16x32_bf16 v[34:37], v[228:231], v[176:179], v[34:37]
	v_mfma_f32_16x16x32_bf16 v[22:25], v[220:223], v[204:207], v[22:25]
	v_mfma_f32_16x16x32_bf16 v[18:21], v[228:231], v[204:207], v[18:21]
	v_mfma_f32_16x16x32_bf16 v[6:9], v[220:223], v[212:215], v[6:9]
	v_mfma_f32_16x16x32_bf16 v[2:5], v[228:231], v[212:215], v[2:5]
	s_barrier
	s_cbranch_scc1 .Lkexit_742
.LBB0_742:
	s_add_i32 s70, s4, 2
	s_add_u32 s10, s0, 0x80
	s_addc_u32 s5, s1, 0
	s_add_i32 s71, 0, 0x10000
	ds_read_b128 v[142:145], v248
	ds_read_b128 v[146:149], v248 offset:1024
	ds_read_b128 v[150:153], v248 offset:2048
	ds_read_b128 v[154:157], v248 offset:3072
	s_cmp_eq_u32 s43, s4
	s_cselect_b32 s4, s22, s10
	s_cselect_b32 s5, s23, s5
	s_cselect_b32 s11, s13, s66
	s_cselect_b32 s10, s12, s65
	v_lshl_add_u64 v[162:163], s[0:1], 0, v[138:139]
	s_add_i32 m0, s29, 0xc000
	ds_read_b128 v[158:161], v166
	ds_read_b128 v[168:171], v166 offset:1024
	ds_read_b128 v[172:175], v166 offset:2048
	ds_read_b128 v[176:179], v166 offset:3072
	ds_read_b128 v[180:183], v166 offset:4096
	ds_read_b128 v[204:207], v166 offset:5120
	ds_read_b128 v[208:211], v166 offset:6144
	ds_read_b128 v[212:215], v166 offset:7168
	global_load_lds_dwordx4 v[162:163], off
	v_lshl_add_u64 v[162:163], s[0:1], 0, v[140:141]
	s_add_i32 m0, s29, 0xe000
	s_nop 0
	global_load_lds_dwordx4 v[162:163], off
	s_waitcnt lgkmcnt(8)
	s_barrier
	s_waitcnt lgkmcnt(0)
	v_mfma_f32_16x16x32_bf16 v[126:129], v[142:145], v[158:161], v[126:129]
	v_mfma_f32_16x16x32_bf16 v[122:125], v[150:153], v[158:161], v[122:125]
	v_mfma_f32_16x16x32_bf16 v[110:113], v[142:145], v[172:175], v[110:113]
	v_mfma_f32_16x16x32_bf16 v[106:109], v[150:153], v[172:175], v[106:109]
	v_mfma_f32_16x16x32_bf16 v[94:97], v[142:145], v[180:183], v[94:97]
	v_mfma_f32_16x16x32_bf16 v[90:93], v[150:153], v[180:183], v[90:93]
	v_mfma_f32_16x16x32_bf16 v[78:81], v[142:145], v[208:211], v[78:81]
	v_mfma_f32_16x16x32_bf16 v[74:77], v[150:153], v[208:211], v[74:77]
	v_mfma_f32_16x16x32_bf16 v[126:129], v[146:149], v[168:171], v[126:129]
	v_mfma_f32_16x16x32_bf16 v[122:125], v[154:157], v[168:171], v[122:125]
	v_mfma_f32_16x16x32_bf16 v[110:113], v[146:149], v[176:179], v[110:113]
	v_mfma_f32_16x16x32_bf16 v[106:109], v[154:157], v[176:179], v[106:109]
	v_mfma_f32_16x16x32_bf16 v[94:97], v[146:149], v[204:207], v[94:97]
	v_mfma_f32_16x16x32_bf16 v[90:93], v[154:157], v[204:207], v[90:93]
	v_mfma_f32_16x16x32_bf16 v[78:81], v[146:149], v[212:215], v[78:81]
	v_mfma_f32_16x16x32_bf16 v[74:77], v[154:157], v[212:215], v[74:77]
	s_barrier
	s_add_i32 s72, 0, 0x14000
	s_add_i32 s71, s71, s28
	ds_read_b128 v[216:219], v248 offset:16384
	ds_read_b128 v[220:223], v248 offset:17408
	ds_read_b128 v[224:227], v248 offset:18432
	ds_read_b128 v[228:231], v248 offset:19456
	s_add_u32 s76, s10, s6
	s_addc_u32 s77, s11, s7
	s_mov_b32 m0, s71
	s_nop 0
	global_load_lds_dwordx4 v132, s[10:11]
	s_add_i32 m0, s71, 0x2000
	s_nop 0
	global_load_lds_dwordx4 v136, s[10:11]
	s_barrier
	s_waitcnt lgkmcnt(0)
	v_mfma_f32_16x16x32_bf16 v[118:121], v[216:219], v[158:161], v[118:121]
	v_mfma_f32_16x16x32_bf16 v[114:117], v[224:227], v[158:161], v[114:117]
	v_mfma_f32_16x16x32_bf16 v[102:105], v[216:219], v[172:175], v[102:105]
	v_mfma_f32_16x16x32_bf16 v[98:101], v[224:227], v[172:175], v[98:101]
	v_mfma_f32_16x16x32_bf16 v[86:89], v[216:219], v[180:183], v[86:89]
	v_mfma_f32_16x16x32_bf16 v[82:85], v[224:227], v[180:183], v[82:85]
	v_mfma_f32_16x16x32_bf16 v[70:73], v[216:219], v[208:211], v[70:73]
	v_mfma_f32_16x16x32_bf16 v[66:69], v[224:227], v[208:211], v[66:69]
	v_mfma_f32_16x16x32_bf16 v[118:121], v[220:223], v[168:171], v[118:121]
	v_mfma_f32_16x16x32_bf16 v[114:117], v[228:231], v[168:171], v[114:117]
	v_mfma_f32_16x16x32_bf16 v[102:105], v[220:223], v[176:179], v[102:105]
	v_mfma_f32_16x16x32_bf16 v[98:101], v[228:231], v[176:179], v[98:101]
	v_mfma_f32_16x16x32_bf16 v[86:89], v[220:223], v[204:207], v[86:89]
	v_mfma_f32_16x16x32_bf16 v[82:85], v[228:231], v[204:207], v[82:85]
	v_mfma_f32_16x16x32_bf16 v[70:73], v[220:223], v[212:215], v[70:73]
	v_mfma_f32_16x16x32_bf16 v[66:69], v[228:231], v[212:215], v[66:69]
	s_barrier
	s_mov_b32 m0, s29
	s_add_u32 s78, s4, s6
	s_addc_u32 s79, s5, s7
	ds_read_b128 v[158:161], v166 offset:16384
	ds_read_b128 v[168:171], v166 offset:17408
	ds_read_b128 v[172:175], v166 offset:18432
	ds_read_b128 v[176:179], v166 offset:19456
	ds_read_b128 v[180:183], v166 offset:20480
	ds_read_b128 v[204:207], v166 offset:21504
	ds_read_b128 v[208:211], v166 offset:22528
	ds_read_b128 v[212:215], v166 offset:23552
	global_load_lds_dwordx4 v130, s[4:5]
	s_mov_b32 m0, s30
	s_nop 0
	global_load_lds_dwordx4 v134, s[4:5]
	s_barrier
	s_waitcnt lgkmcnt(0)
	v_mfma_f32_16x16x32_bf16 v[62:65], v[142:145], v[158:161], v[62:65]
	v_mfma_f32_16x16x32_bf16 v[58:61], v[150:153], v[158:161], v[58:61]
	v_mfma_f32_16x16x32_bf16 v[46:49], v[142:145], v[172:175], v[46:49]
	v_mfma_f32_16x16x32_bf16 v[42:45], v[150:153], v[172:175], v[42:45]
	v_mfma_f32_16x16x32_bf16 v[30:33], v[142:145], v[180:183], v[30:33]
	v_mfma_f32_16x16x32_bf16 v[26:29], v[150:153], v[180:183], v[26:29]
	v_mfma_f32_16x16x32_bf16 v[14:17], v[142:145], v[208:211], v[14:17]
	v_mfma_f32_16x16x32_bf16 v[10:13], v[150:153], v[208:211], v[10:13]
	v_mfma_f32_16x16x32_bf16 v[62:65], v[146:149], v[168:171], v[62:65]
	v_mfma_f32_16x16x32_bf16 v[58:61], v[154:157], v[168:171], v[58:61]
	v_mfma_f32_16x16x32_bf16 v[46:49], v[146:149], v[176:179], v[46:49]
	v_mfma_f32_16x16x32_bf16 v[42:45], v[154:157], v[176:179], v[42:45]
	v_mfma_f32_16x16x32_bf16 v[30:33], v[146:149], v[204:207], v[30:33]
	v_mfma_f32_16x16x32_bf16 v[26:29], v[154:157], v[204:207], v[26:29]
	v_mfma_f32_16x16x32_bf16 v[14:17], v[146:149], v[212:215], v[14:17]
	v_mfma_f32_16x16x32_bf16 v[10:13], v[154:157], v[212:215], v[10:13]
	s_barrier
	s_add_u32 s10, s10, s2
	s_addc_u32 s11, s11, 0
	s_add_i32 s71, s72, s28
	s_add_u32 s80, s10, s6
	s_addc_u32 s81, s11, s7
	s_mov_b32 m0, s71
	s_nop 0
	global_load_lds_dwordx4 v132, s[10:11]
	s_add_i32 m0, s71, 0x2000
	s_nop 0
	global_load_lds_dwordx4 v136, s[10:11]
	s_waitcnt vmcnt(6)
	s_barrier
	v_mfma_f32_16x16x32_bf16 v[54:57], v[216:219], v[158:161], v[54:57]
	v_mfma_f32_16x16x32_bf16 v[50:53], v[224:227], v[158:161], v[50:53]
	v_mfma_f32_16x16x32_bf16 v[38:41], v[216:219], v[172:175], v[38:41]
	v_mfma_f32_16x16x32_bf16 v[34:37], v[224:227], v[172:175], v[34:37]
	v_mfma_f32_16x16x32_bf16 v[22:25], v[216:219], v[180:183], v[22:25]
	v_mfma_f32_16x16x32_bf16 v[18:21], v[224:227], v[180:183], v[18:21]
	v_mfma_f32_16x16x32_bf16 v[6:9], v[216:219], v[208:211], v[6:9]
	v_mfma_f32_16x16x32_bf16 v[2:5], v[224:227], v[208:211], v[2:5]
	v_mfma_f32_16x16x32_bf16 v[54:57], v[220:223], v[168:171], v[54:57]
	v_mfma_f32_16x16x32_bf16 v[50:53], v[228:231], v[168:171], v[50:53]
	v_mfma_f32_16x16x32_bf16 v[38:41], v[220:223], v[176:179], v[38:41]
	v_mfma_f32_16x16x32_bf16 v[34:37], v[228:231], v[176:179], v[34:37]
	v_mfma_f32_16x16x32_bf16 v[22:25], v[220:223], v[204:207], v[22:25]
	v_mfma_f32_16x16x32_bf16 v[18:21], v[228:231], v[204:207], v[18:21]
	v_mfma_f32_16x16x32_bf16 v[6:9], v[220:223], v[212:215], v[6:9]
	v_mfma_f32_16x16x32_bf16 v[2:5], v[228:231], v[212:215], v[2:5]
	s_barrier
	s_add_i32 s10, 0, 0x18000
	ds_read_b128 v[142:145], v248 offset:32768
	ds_read_b128 v[146:149], v248 offset:33792
	ds_read_b128 v[150:153], v248 offset:34816
	ds_read_b128 v[154:157], v248 offset:35840
	s_add_u32 s4, s4, s2
	s_addc_u32 s5, s5, 0
	s_mov_b32 m0, s31
	ds_read_b128 v[158:161], v166 offset:32768
	ds_read_b128 v[168:171], v166 offset:33792
	ds_read_b128 v[172:175], v166 offset:34816
	ds_read_b128 v[176:179], v166 offset:35840
	ds_read_b128 v[180:183], v166 offset:36864
	ds_read_b128 v[204:207], v166 offset:37888
	ds_read_b128 v[208:211], v166 offset:38912
	ds_read_b128 v[212:215], v166 offset:39936
	global_load_lds_dwordx4 v130, s[4:5]
	s_mov_b32 m0, s34
	s_nop 0
	global_load_lds_dwordx4 v134, s[4:5]
	s_waitcnt lgkmcnt(8)
	s_barrier
	s_waitcnt lgkmcnt(0)
	v_mfma_f32_16x16x32_bf16 v[126:129], v[142:145], v[158:161], v[126:129]
	v_mfma_f32_16x16x32_bf16 v[122:125], v[150:153], v[158:161], v[122:125]
	v_mfma_f32_16x16x32_bf16 v[110:113], v[142:145], v[172:175], v[110:113]
	v_mfma_f32_16x16x32_bf16 v[106:109], v[150:153], v[172:175], v[106:109]
	v_mfma_f32_16x16x32_bf16 v[94:97], v[142:145], v[180:183], v[94:97]
	v_mfma_f32_16x16x32_bf16 v[90:93], v[150:153], v[180:183], v[90:93]
	v_mfma_f32_16x16x32_bf16 v[78:81], v[142:145], v[208:211], v[78:81]
	v_mfma_f32_16x16x32_bf16 v[74:77], v[150:153], v[208:211], v[74:77]
	v_mfma_f32_16x16x32_bf16 v[126:129], v[146:149], v[168:171], v[126:129]
	v_mfma_f32_16x16x32_bf16 v[122:125], v[154:157], v[168:171], v[122:125]
	v_mfma_f32_16x16x32_bf16 v[110:113], v[146:149], v[176:179], v[110:113]
	v_mfma_f32_16x16x32_bf16 v[106:109], v[154:157], v[176:179], v[106:109]
	v_mfma_f32_16x16x32_bf16 v[94:97], v[146:149], v[204:207], v[94:97]
	v_mfma_f32_16x16x32_bf16 v[90:93], v[154:157], v[204:207], v[90:93]
	v_mfma_f32_16x16x32_bf16 v[78:81], v[146:149], v[212:215], v[78:81]
	v_mfma_f32_16x16x32_bf16 v[74:77], v[154:157], v[212:215], v[74:77]
	s_barrier
	s_add_i32 s4, 0, 0x1c000
	s_add_i32 s5, s10, s28
	s_mov_b32 m0, s5
	ds_read_b128 v[216:219], v248 offset:49152
	ds_read_b128 v[220:223], v248 offset:50176
	ds_read_b128 v[224:227], v248 offset:51200
	ds_read_b128 v[228:231], v248 offset:52224
	global_load_lds_dwordx4 v132, s[76:77]
	s_add_i32 m0, s5, 0x2000
	s_nop 0
	global_load_lds_dwordx4 v136, s[76:77]
	s_barrier
	s_waitcnt lgkmcnt(0)
	v_mfma_f32_16x16x32_bf16 v[118:121], v[216:219], v[158:161], v[118:121]
	v_mfma_f32_16x16x32_bf16 v[114:117], v[224:227], v[158:161], v[114:117]
	v_mfma_f32_16x16x32_bf16 v[102:105], v[216:219], v[172:175], v[102:105]
	v_mfma_f32_16x16x32_bf16 v[98:101], v[224:227], v[172:175], v[98:101]
	v_mfma_f32_16x16x32_bf16 v[86:89], v[216:219], v[180:183], v[86:89]
	v_mfma_f32_16x16x32_bf16 v[82:85], v[224:227], v[180:183], v[82:85]
	v_mfma_f32_16x16x32_bf16 v[70:73], v[216:219], v[208:211], v[70:73]
	v_mfma_f32_16x16x32_bf16 v[66:69], v[224:227], v[208:211], v[66:69]
	v_mfma_f32_16x16x32_bf16 v[118:121], v[220:223], v[168:171], v[118:121]
	v_mfma_f32_16x16x32_bf16 v[114:117], v[228:231], v[168:171], v[114:117]
	v_mfma_f32_16x16x32_bf16 v[102:105], v[220:223], v[176:179], v[102:105]
	v_mfma_f32_16x16x32_bf16 v[98:101], v[228:231], v[176:179], v[98:101]
	v_mfma_f32_16x16x32_bf16 v[86:89], v[220:223], v[204:207], v[86:89]
	v_mfma_f32_16x16x32_bf16 v[82:85], v[228:231], v[204:207], v[82:85]
	v_mfma_f32_16x16x32_bf16 v[70:73], v[220:223], v[212:215], v[70:73]
	v_mfma_f32_16x16x32_bf16 v[66:69], v[228:231], v[212:215], v[66:69]
	s_barrier
	s_mov_b32 m0, s41
	ds_read_b128 v[158:161], v166 offset:49152
	ds_read_b128 v[168:171], v166 offset:50176
	ds_read_b128 v[172:175], v166 offset:51200
	ds_read_b128 v[176:179], v166 offset:52224
	ds_read_b128 v[180:183], v166 offset:53248
	ds_read_b128 v[204:207], v166 offset:54272
	ds_read_b128 v[208:211], v166 offset:55296
	ds_read_b128 v[212:215], v166 offset:56320
	global_load_lds_dwordx4 v130, s[78:79]
	s_mov_b32 m0, s42
	s_nop 0
	global_load_lds_dwordx4 v134, s[78:79]
	s_barrier
	s_waitcnt lgkmcnt(0)
	v_mfma_f32_16x16x32_bf16 v[62:65], v[142:145], v[158:161], v[62:65]
	v_mfma_f32_16x16x32_bf16 v[58:61], v[150:153], v[158:161], v[58:61]
	v_mfma_f32_16x16x32_bf16 v[46:49], v[142:145], v[172:175], v[46:49]
	v_mfma_f32_16x16x32_bf16 v[42:45], v[150:153], v[172:175], v[42:45]
	v_mfma_f32_16x16x32_bf16 v[30:33], v[142:145], v[180:183], v[30:33]
	v_mfma_f32_16x16x32_bf16 v[26:29], v[150:153], v[180:183], v[26:29]
	v_mfma_f32_16x16x32_bf16 v[14:17], v[142:145], v[208:211], v[14:17]
	v_mfma_f32_16x16x32_bf16 v[10:13], v[150:153], v[208:211], v[10:13]
	v_mfma_f32_16x16x32_bf16 v[62:65], v[146:149], v[168:171], v[62:65]
	v_mfma_f32_16x16x32_bf16 v[58:61], v[154:157], v[168:171], v[58:61]
	v_mfma_f32_16x16x32_bf16 v[46:49], v[146:149], v[176:179], v[46:49]
	v_mfma_f32_16x16x32_bf16 v[42:45], v[154:157], v[176:179], v[42:45]
	v_mfma_f32_16x16x32_bf16 v[30:33], v[146:149], v[204:207], v[30:33]
	v_mfma_f32_16x16x32_bf16 v[26:29], v[154:157], v[204:207], v[26:29]
	v_mfma_f32_16x16x32_bf16 v[14:17], v[146:149], v[212:215], v[14:17]
	v_mfma_f32_16x16x32_bf16 v[10:13], v[154:157], v[212:215], v[10:13]
	s_barrier
	s_add_i32 s4, s4, s28
	s_mov_b32 m0, s4
	s_nop 0
	global_load_lds_dwordx4 v132, s[80:81]
	s_add_i32 m0, s4, 0x2000
	s_nop 0
	global_load_lds_dwordx4 v136, s[80:81]
	s_add_u32 s0, s0, 0x100
	s_addc_u32 s1, s1, 0
	s_add_u32 s65, s65, 0x100
	s_addc_u32 s66, s66, 0
	s_cmp_ge_u32 s70, s35
	s_mov_b32 s4, s70
	s_waitcnt vmcnt(6)
	s_barrier
	v_mfma_f32_16x16x32_bf16 v[54:57], v[216:219], v[158:161], v[54:57]
	v_mfma_f32_16x16x32_bf16 v[50:53], v[224:227], v[158:161], v[50:53]
	v_mfma_f32_16x16x32_bf16 v[38:41], v[216:219], v[172:175], v[38:41]
	v_mfma_f32_16x16x32_bf16 v[34:37], v[224:227], v[172:175], v[34:37]
	v_mfma_f32_16x16x32_bf16 v[22:25], v[216:219], v[180:183], v[22:25]
	v_mfma_f32_16x16x32_bf16 v[18:21], v[224:227], v[180:183], v[18:21]
	v_mfma_f32_16x16x32_bf16 v[6:9], v[216:219], v[208:211], v[6:9]
	v_mfma_f32_16x16x32_bf16 v[2:5], v[224:227], v[208:211], v[2:5]
	v_mfma_f32_16x16x32_bf16 v[54:57], v[220:223], v[168:171], v[54:57]
	v_mfma_f32_16x16x32_bf16 v[50:53], v[228:231], v[168:171], v[50:53]
	v_mfma_f32_16x16x32_bf16 v[38:41], v[220:223], v[176:179], v[38:41]
	v_mfma_f32_16x16x32_bf16 v[34:37], v[228:231], v[176:179], v[34:37]
	v_mfma_f32_16x16x32_bf16 v[22:25], v[220:223], v[204:207], v[22:25]
	v_mfma_f32_16x16x32_bf16 v[18:21], v[228:231], v[204:207], v[18:21]
	v_mfma_f32_16x16x32_bf16 v[6:9], v[220:223], v[212:215], v[6:9]
	v_mfma_f32_16x16x32_bf16 v[2:5], v[228:231], v[212:215], v[2:5]
	s_barrier
	s_cbranch_scc0 .LBB0_742

.Lstag_795_done:
	v_add_u32_e32 v248, 0x10000, v171
	s_branch .LBB0_795

.LBB0_805:
	s_add_u32 s0, s0, 0x80
	s_addc_u32 s1, s1, 0
	s_add_u32 s12, s4, 0x100
	s_addc_u32 s13, s5, 0
	s_mov_b32 s4, 0
	s_waitcnt vmcnt(0)
	s_add_i32 s27, s4, 2
	s_add_u32 s10, s0, 0x80
	s_addc_u32 s5, s1, 0
	s_add_i32 s28, 0, 0x10000
	ds_read_b128 v[142:145], v248
	ds_read_b128 v[146:149], v248 offset:1024
	ds_read_b128 v[150:153], v248 offset:2048
	ds_read_b128 v[154:157], v248 offset:3072
	s_cmp_eq_u32 s48, s4
	s_cselect_b32 s4, s22, s10
	s_cselect_b32 s5, s23, s5
	s_cselect_b32 s11, s25, s13
	s_cselect_b32 s10, s24, s12
	v_lshl_add_u64 v[212:213], s[0:1], 0, v[138:139]
	s_add_i32 m0, s35, 0xc000
	ds_read_b128 v[158:161], v172
	ds_read_b128 v[162:165], v172 offset:1024
	ds_read_b128 v[166:169], v172 offset:2048
	ds_read_b128 v[174:177], v172 offset:3072
	ds_read_b128 v[178:181], v172 offset:4096
	ds_read_b128 v[182:185], v172 offset:5120
	ds_read_b128 v[204:207], v172 offset:6144
	ds_read_b128 v[208:211], v172 offset:7168
	global_load_lds_dwordx4 v[212:213], off
	v_lshl_add_u64 v[212:213], s[0:1], 0, v[140:141]
	s_add_i32 m0, s35, 0xe000
	s_nop 0
	global_load_lds_dwordx4 v[212:213], off
	s_waitcnt lgkmcnt(8)
	s_barrier
	s_waitcnt lgkmcnt(0)
	v_mfma_f32_16x16x32_bf16 v[126:129], v[142:145], v[158:161], 0
	v_mfma_f32_16x16x32_bf16 v[122:125], v[150:153], v[158:161], 0
	v_mfma_f32_16x16x32_bf16 v[110:113], v[142:145], v[166:169], 0
	v_mfma_f32_16x16x32_bf16 v[106:109], v[150:153], v[166:169], 0
	v_mfma_f32_16x16x32_bf16 v[94:97], v[142:145], v[178:181], 0
	v_mfma_f32_16x16x32_bf16 v[90:93], v[150:153], v[178:181], 0
	v_mfma_f32_16x16x32_bf16 v[78:81], v[142:145], v[204:207], 0
	v_mfma_f32_16x16x32_bf16 v[74:77], v[150:153], v[204:207], 0
	v_mfma_f32_16x16x32_bf16 v[126:129], v[146:149], v[162:165], v[126:129]
	v_mfma_f32_16x16x32_bf16 v[122:125], v[154:157], v[162:165], v[122:125]
	v_mfma_f32_16x16x32_bf16 v[110:113], v[146:149], v[174:177], v[110:113]
	v_mfma_f32_16x16x32_bf16 v[106:109], v[154:157], v[174:177], v[106:109]
	v_mfma_f32_16x16x32_bf16 v[94:97], v[146:149], v[182:185], v[94:97]
	v_mfma_f32_16x16x32_bf16 v[90:93], v[154:157], v[182:185], v[90:93]
	v_mfma_f32_16x16x32_bf16 v[78:81], v[146:149], v[208:211], v[78:81]
	v_mfma_f32_16x16x32_bf16 v[74:77], v[154:157], v[208:211], v[74:77]
	s_barrier
	s_add_i32 s29, 0, 0x14000
	s_add_i32 s28, s28, s34
	s_add_u32 s78, s10, s6
	s_addc_u32 s79, s11, s7
	s_mov_b32 m0, s28
	ds_read_b128 v[212:215], v248 offset:16384
	ds_read_b128 v[216:219], v248 offset:17408
	ds_read_b128 v[220:223], v248 offset:18432
	ds_read_b128 v[224:227], v248 offset:19456
	global_load_lds_dwordx4 v132, s[10:11]
	s_add_i32 m0, s28, 0x2000
	s_nop 0
	global_load_lds_dwordx4 v136, s[10:11]
	s_barrier
	s_waitcnt lgkmcnt(0)
	v_mfma_f32_16x16x32_bf16 v[118:121], v[212:215], v[158:161], 0
	v_mfma_f32_16x16x32_bf16 v[114:117], v[220:223], v[158:161], 0
	v_mfma_f32_16x16x32_bf16 v[102:105], v[212:215], v[166:169], 0
	v_mfma_f32_16x16x32_bf16 v[98:101], v[220:223], v[166:169], 0
	v_mfma_f32_16x16x32_bf16 v[86:89], v[212:215], v[178:181], 0
	v_mfma_f32_16x16x32_bf16 v[82:85], v[220:223], v[178:181], 0
	v_mfma_f32_16x16x32_bf16 v[70:73], v[212:215], v[204:207], 0
	v_mfma_f32_16x16x32_bf16 v[66:69], v[220:223], v[204:207], 0
	v_mfma_f32_16x16x32_bf16 v[118:121], v[216:219], v[162:165], v[118:121]
	v_mfma_f32_16x16x32_bf16 v[114:117], v[224:227], v[162:165], v[114:117]
	v_mfma_f32_16x16x32_bf16 v[102:105], v[216:219], v[174:177], v[102:105]
	v_mfma_f32_16x16x32_bf16 v[98:101], v[224:227], v[174:177], v[98:101]
	v_mfma_f32_16x16x32_bf16 v[86:89], v[216:219], v[182:185], v[86:89]
	v_mfma_f32_16x16x32_bf16 v[82:85], v[224:227], v[182:185], v[82:85]
	v_mfma_f32_16x16x32_bf16 v[70:73], v[216:219], v[208:211], v[70:73]
	v_mfma_f32_16x16x32_bf16 v[66:69], v[224:227], v[208:211], v[66:69]
	s_barrier
	s_mov_b32 m0, s35
	s_add_u32 s80, s4, s6
	s_addc_u32 s81, s5, s7
	ds_read_b128 v[158:161], v172 offset:16384
	ds_read_b128 v[162:165], v172 offset:17408
	ds_read_b128 v[166:169], v172 offset:18432
	ds_read_b128 v[174:177], v172 offset:19456
	ds_read_b128 v[178:181], v172 offset:20480
	ds_read_b128 v[182:185], v172 offset:21504
	ds_read_b128 v[204:207], v172 offset:22528
	ds_read_b128 v[208:211], v172 offset:23552
	global_load_lds_dwordx4 v130, s[4:5]
	s_mov_b32 m0, s40
	s_nop 0
	global_load_lds_dwordx4 v134, s[4:5]
	s_barrier
	s_waitcnt lgkmcnt(0)
	v_mfma_f32_16x16x32_bf16 v[62:65], v[142:145], v[158:161], 0
	v_mfma_f32_16x16x32_bf16 v[58:61], v[150:153], v[158:161], 0
	v_mfma_f32_16x16x32_bf16 v[46:49], v[142:145], v[166:169], 0
	v_mfma_f32_16x16x32_bf16 v[42:45], v[150:153], v[166:169], 0
	v_mfma_f32_16x16x32_bf16 v[30:33], v[142:145], v[178:181], 0
	v_mfma_f32_16x16x32_bf16 v[26:29], v[150:153], v[178:181], 0
	v_mfma_f32_16x16x32_bf16 v[14:17], v[142:145], v[204:207], 0
	v_mfma_f32_16x16x32_bf16 v[10:13], v[150:153], v[204:207], 0
	v_mfma_f32_16x16x32_bf16 v[62:65], v[146:149], v[162:165], v[62:65]
	v_mfma_f32_16x16x32_bf16 v[58:61], v[154:157], v[162:165], v[58:61]
	v_mfma_f32_16x16x32_bf16 v[46:49], v[146:149], v[174:177], v[46:49]
	v_mfma_f32_16x16x32_bf16 v[42:45], v[154:157], v[174:177], v[42:45]
	v_mfma_f32_16x16x32_bf16 v[30:33], v[146:149], v[182:185], v[30:33]
	v_mfma_f32_16x16x32_bf16 v[26:29], v[154:157], v[182:185], v[26:29]
	v_mfma_f32_16x16x32_bf16 v[14:17], v[146:149], v[208:211], v[14:17]
	v_mfma_f32_16x16x32_bf16 v[10:13], v[154:157], v[208:211], v[10:13]
	s_barrier
	s_add_u32 s10, s10, s92
	s_addc_u32 s11, s11, 0
	s_add_i32 s28, s29, s34
	s_add_u32 s58, s10, s6
	s_addc_u32 s59, s11, s7
	s_mov_b32 m0, s28
	s_nop 0
	global_load_lds_dwordx4 v132, s[10:11]
	s_add_i32 m0, s28, 0x2000
	s_nop 0
	global_load_lds_dwordx4 v136, s[10:11]
	s_waitcnt vmcnt(6)
	s_barrier
	v_mfma_f32_16x16x32_bf16 v[54:57], v[212:215], v[158:161], 0
	v_mfma_f32_16x16x32_bf16 v[50:53], v[220:223], v[158:161], 0
	v_mfma_f32_16x16x32_bf16 v[38:41], v[212:215], v[166:169], 0
	v_mfma_f32_16x16x32_bf16 v[34:37], v[220:223], v[166:169], 0
	v_mfma_f32_16x16x32_bf16 v[22:25], v[212:215], v[178:181], 0
	v_mfma_f32_16x16x32_bf16 v[18:21], v[220:223], v[178:181], 0
	v_mfma_f32_16x16x32_bf16 v[6:9], v[212:215], v[204:207], 0
	v_mfma_f32_16x16x32_bf16 v[2:5], v[220:223], v[204:207], 0
	v_mfma_f32_16x16x32_bf16 v[54:57], v[216:219], v[162:165], v[54:57]
	v_mfma_f32_16x16x32_bf16 v[50:53], v[224:227], v[162:165], v[50:53]
	v_mfma_f32_16x16x32_bf16 v[38:41], v[216:219], v[174:177], v[38:41]
	v_mfma_f32_16x16x32_bf16 v[34:37], v[224:227], v[174:177], v[34:37]
	v_mfma_f32_16x16x32_bf16 v[22:25], v[216:219], v[182:185], v[22:25]
	v_mfma_f32_16x16x32_bf16 v[18:21], v[224:227], v[182:185], v[18:21]
	v_mfma_f32_16x16x32_bf16 v[6:9], v[216:219], v[208:211], v[6:9]
	v_mfma_f32_16x16x32_bf16 v[2:5], v[224:227], v[208:211], v[2:5]
	s_barrier
	s_add_i32 s10, 0, 0x18000
	ds_read_b128 v[142:145], v248 offset:32768
	ds_read_b128 v[146:149], v248 offset:33792
	ds_read_b128 v[150:153], v248 offset:34816
	ds_read_b128 v[154:157], v248 offset:35840
	s_add_u32 s4, s4, s92
	s_addc_u32 s5, s5, 0
	s_mov_b32 m0, s41
	ds_read_b128 v[158:161], v172 offset:32768
	ds_read_b128 v[162:165], v172 offset:33792
	ds_read_b128 v[166:169], v172 offset:34816
	ds_read_b128 v[174:177], v172 offset:35840
	ds_read_b128 v[178:181], v172 offset:36864
	ds_read_b128 v[182:185], v172 offset:37888
	ds_read_b128 v[204:207], v172 offset:38912
	ds_read_b128 v[208:211], v172 offset:39936
	global_load_lds_dwordx4 v130, s[4:5]
	s_mov_b32 m0, s42
	s_nop 0
	global_load_lds_dwordx4 v134, s[4:5]
	s_waitcnt lgkmcnt(8)
	s_barrier
	s_waitcnt lgkmcnt(0)
	v_mfma_f32_16x16x32_bf16 v[126:129], v[142:145], v[158:161], v[126:129]
	v_mfma_f32_16x16x32_bf16 v[122:125], v[150:153], v[158:161], v[122:125]
	v_mfma_f32_16x16x32_bf16 v[110:113], v[142:145], v[166:169], v[110:113]
	v_mfma_f32_16x16x32_bf16 v[106:109], v[150:153], v[166:169], v[106:109]
	v_mfma_f32_16x16x32_bf16 v[94:97], v[142:145], v[178:181], v[94:97]
	v_mfma_f32_16x16x32_bf16 v[90:93], v[150:153], v[178:181], v[90:93]
	v_mfma_f32_16x16x32_bf16 v[78:81], v[142:145], v[204:207], v[78:81]
	v_mfma_f32_16x16x32_bf16 v[74:77], v[150:153], v[204:207], v[74:77]
	v_mfma_f32_16x16x32_bf16 v[126:129], v[146:149], v[162:165], v[126:129]
	v_mfma_f32_16x16x32_bf16 v[122:125], v[154:157], v[162:165], v[122:125]
	v_mfma_f32_16x16x32_bf16 v[110:113], v[146:149], v[174:177], v[110:113]
	v_mfma_f32_16x16x32_bf16 v[106:109], v[154:157], v[174:177], v[106:109]
	v_mfma_f32_16x16x32_bf16 v[94:97], v[146:149], v[182:185], v[94:97]
	v_mfma_f32_16x16x32_bf16 v[90:93], v[154:157], v[182:185], v[90:93]
	v_mfma_f32_16x16x32_bf16 v[78:81], v[146:149], v[208:211], v[78:81]
	v_mfma_f32_16x16x32_bf16 v[74:77], v[154:157], v[208:211], v[74:77]
	s_barrier
	s_add_i32 s4, 0, 0x1c000
	s_add_i32 s5, s10, s34
	s_mov_b32 m0, s5
	ds_read_b128 v[212:215], v248 offset:49152
	ds_read_b128 v[216:219], v248 offset:50176
	ds_read_b128 v[220:223], v248 offset:51200
	ds_read_b128 v[224:227], v248 offset:52224
	global_load_lds_dwordx4 v132, s[78:79]
	s_add_i32 m0, s5, 0x2000
	s_nop 0
	global_load_lds_dwordx4 v136, s[78:79]
	s_barrier
	s_waitcnt lgkmcnt(0)
	v_mfma_f32_16x16x32_bf16 v[118:121], v[212:215], v[158:161], v[118:121]
	v_mfma_f32_16x16x32_bf16 v[114:117], v[220:223], v[158:161], v[114:117]
	v_mfma_f32_16x16x32_bf16 v[102:105], v[212:215], v[166:169], v[102:105]
	v_mfma_f32_16x16x32_bf16 v[98:101], v[220:223], v[166:169], v[98:101]
	v_mfma_f32_16x16x32_bf16 v[86:89], v[212:215], v[178:181], v[86:89]
	v_mfma_f32_16x16x32_bf16 v[82:85], v[220:223], v[178:181], v[82:85]
	v_mfma_f32_16x16x32_bf16 v[70:73], v[212:215], v[204:207], v[70:73]
	v_mfma_f32_16x16x32_bf16 v[66:69], v[220:223], v[204:207], v[66:69]
	v_mfma_f32_16x16x32_bf16 v[118:121], v[216:219], v[162:165], v[118:121]
	v_mfma_f32_16x16x32_bf16 v[114:117], v[224:227], v[162:165], v[114:117]
	v_mfma_f32_16x16x32_bf16 v[102:105], v[216:219], v[174:177], v[102:105]
	v_mfma_f32_16x16x32_bf16 v[98:101], v[224:227], v[174:177], v[98:101]
	v_mfma_f32_16x16x32_bf16 v[86:89], v[216:219], v[182:185], v[86:89]
	v_mfma_f32_16x16x32_bf16 v[82:85], v[224:227], v[182:185], v[82:85]
	v_mfma_f32_16x16x32_bf16 v[70:73], v[216:219], v[208:211], v[70:73]
	v_mfma_f32_16x16x32_bf16 v[66:69], v[224:227], v[208:211], v[66:69]
	s_barrier
	s_mov_b32 m0, s46
	ds_read_b128 v[158:161], v172 offset:49152
	ds_read_b128 v[162:165], v172 offset:50176
	ds_read_b128 v[166:169], v172 offset:51200
	ds_read_b128 v[174:177], v172 offset:52224
	ds_read_b128 v[178:181], v172 offset:53248
	ds_read_b128 v[182:185], v172 offset:54272
	ds_read_b128 v[204:207], v172 offset:55296
	ds_read_b128 v[208:211], v172 offset:56320
	global_load_lds_dwordx4 v130, s[80:81]
	s_mov_b32 m0, s47
	s_nop 0
	global_load_lds_dwordx4 v134, s[80:81]
	s_barrier
	s_waitcnt lgkmcnt(0)
	v_mfma_f32_16x16x32_bf16 v[62:65], v[142:145], v[158:161], v[62:65]
	v_mfma_f32_16x16x32_bf16 v[58:61], v[150:153], v[158:161], v[58:61]
	v_mfma_f32_16x16x32_bf16 v[46:49], v[142:145], v[166:169], v[46:49]
	v_mfma_f32_16x16x32_bf16 v[42:45], v[150:153], v[166:169], v[42:45]
	v_mfma_f32_16x16x32_bf16 v[30:33], v[142:145], v[178:181], v[30:33]
	v_mfma_f32_16x16x32_bf16 v[26:29], v[150:153], v[178:181], v[26:29]
	v_mfma_f32_16x16x32_bf16 v[14:17], v[142:145], v[204:207], v[14:17]
	v_mfma_f32_16x16x32_bf16 v[10:13], v[150:153], v[204:207], v[10:13]
	v_mfma_f32_16x16x32_bf16 v[62:65], v[146:149], v[162:165], v[62:65]
	v_mfma_f32_16x16x32_bf16 v[58:61], v[154:157], v[162:165], v[58:61]
	v_mfma_f32_16x16x32_bf16 v[46:49], v[146:149], v[174:177], v[46:49]
	v_mfma_f32_16x16x32_bf16 v[42:45], v[154:157], v[174:177], v[42:45]
	v_mfma_f32_16x16x32_bf16 v[30:33], v[146:149], v[182:185], v[30:33]
	v_mfma_f32_16x16x32_bf16 v[26:29], v[154:157], v[182:185], v[26:29]
	v_mfma_f32_16x16x32_bf16 v[14:17], v[146:149], v[208:211], v[14:17]
	v_mfma_f32_16x16x32_bf16 v[10:13], v[154:157], v[208:211], v[10:13]
	s_barrier
	s_add_i32 s4, s4, s34
	s_mov_b32 m0, s4
	s_nop 0
	global_load_lds_dwordx4 v132, s[58:59]
	s_add_i32 m0, s4, 0x2000
	s_nop 0
	global_load_lds_dwordx4 v136, s[58:59]
	s_add_u32 s0, s0, 0x100
	s_addc_u32 s1, s1, 0
	s_add_u32 s12, s12, 0x100
	s_addc_u32 s13, s13, 0
	s_cmp_ge_u32 s27, s43
	s_mov_b32 s4, s27
	s_waitcnt vmcnt(6)
	s_barrier
	v_mfma_f32_16x16x32_bf16 v[54:57], v[212:215], v[158:161], v[54:57]
	v_mfma_f32_16x16x32_bf16 v[50:53], v[220:223], v[158:161], v[50:53]
	v_mfma_f32_16x16x32_bf16 v[38:41], v[212:215], v[166:169], v[38:41]
	v_mfma_f32_16x16x32_bf16 v[34:37], v[220:223], v[166:169], v[34:37]
	v_mfma_f32_16x16x32_bf16 v[22:25], v[212:215], v[178:181], v[22:25]
	v_mfma_f32_16x16x32_bf16 v[18:21], v[220:223], v[178:181], v[18:21]
	v_mfma_f32_16x16x32_bf16 v[6:9], v[212:215], v[204:207], v[6:9]
	v_mfma_f32_16x16x32_bf16 v[2:5], v[220:223], v[204:207], v[2:5]
	v_mfma_f32_16x16x32_bf16 v[54:57], v[216:219], v[162:165], v[54:57]
	v_mfma_f32_16x16x32_bf16 v[50:53], v[224:227], v[162:165], v[50:53]
	v_mfma_f32_16x16x32_bf16 v[38:41], v[216:219], v[174:177], v[38:41]
	v_mfma_f32_16x16x32_bf16 v[34:37], v[224:227], v[174:177], v[34:37]
	v_mfma_f32_16x16x32_bf16 v[22:25], v[216:219], v[182:185], v[22:25]
	v_mfma_f32_16x16x32_bf16 v[18:21], v[224:227], v[182:185], v[18:21]
	v_mfma_f32_16x16x32_bf16 v[6:9], v[216:219], v[208:211], v[6:9]
	v_mfma_f32_16x16x32_bf16 v[2:5], v[224:227], v[208:211], v[2:5]
	s_barrier
	s_cbranch_scc1 .Lkexit_806
.LBB0_806:
	s_add_i32 s27, s4, 2
	s_add_u32 s10, s0, 0x80
	s_addc_u32 s5, s1, 0
	s_add_i32 s28, 0, 0x10000
	ds_read_b128 v[142:145], v248
	ds_read_b128 v[146:149], v248 offset:1024
	ds_read_b128 v[150:153], v248 offset:2048
	ds_read_b128 v[154:157], v248 offset:3072
	s_cmp_eq_u32 s48, s4
	s_cselect_b32 s4, s22, s10
	s_cselect_b32 s5, s23, s5
	s_cselect_b32 s11, s25, s13
	s_cselect_b32 s10, s24, s12
	v_lshl_add_u64 v[212:213], s[0:1], 0, v[138:139]
	s_add_i32 m0, s35, 0xc000
	ds_read_b128 v[158:161], v172
	ds_read_b128 v[162:165], v172 offset:1024
	ds_read_b128 v[166:169], v172 offset:2048
	ds_read_b128 v[174:177], v172 offset:3072
	ds_read_b128 v[178:181], v172 offset:4096
	ds_read_b128 v[182:185], v172 offset:5120
	ds_read_b128 v[204:207], v172 offset:6144
	ds_read_b128 v[208:211], v172 offset:7168
	global_load_lds_dwordx4 v[212:213], off
	v_lshl_add_u64 v[212:213], s[0:1], 0, v[140:141]
	s_add_i32 m0, s35, 0xe000
	s_nop 0
	global_load_lds_dwordx4 v[212:213], off
	s_waitcnt lgkmcnt(8)
	s_barrier
	s_waitcnt lgkmcnt(0)
	v_mfma_f32_16x16x32_bf16 v[126:129], v[142:145], v[158:161], v[126:129]
	v_mfma_f32_16x16x32_bf16 v[122:125], v[150:153], v[158:161], v[122:125]
	v_mfma_f32_16x16x32_bf16 v[110:113], v[142:145], v[166:169], v[110:113]
	v_mfma_f32_16x16x32_bf16 v[106:109], v[150:153], v[166:169], v[106:109]
	v_mfma_f32_16x16x32_bf16 v[94:97], v[142:145], v[178:181], v[94:97]
	v_mfma_f32_16x16x32_bf16 v[90:93], v[150:153], v[178:181], v[90:93]
	v_mfma_f32_16x16x32_bf16 v[78:81], v[142:145], v[204:207], v[78:81]
	v_mfma_f32_16x16x32_bf16 v[74:77], v[150:153], v[204:207], v[74:77]
	v_mfma_f32_16x16x32_bf16 v[126:129], v[146:149], v[162:165], v[126:129]
	v_mfma_f32_16x16x32_bf16 v[122:125], v[154:157], v[162:165], v[122:125]
	v_mfma_f32_16x16x32_bf16 v[110:113], v[146:149], v[174:177], v[110:113]
	v_mfma_f32_16x16x32_bf16 v[106:109], v[154:157], v[174:177], v[106:109]
	v_mfma_f32_16x16x32_bf16 v[94:97], v[146:149], v[182:185], v[94:97]
	v_mfma_f32_16x16x32_bf16 v[90:93], v[154:157], v[182:185], v[90:93]
	v_mfma_f32_16x16x32_bf16 v[78:81], v[146:149], v[208:211], v[78:81]
	v_mfma_f32_16x16x32_bf16 v[74:77], v[154:157], v[208:211], v[74:77]
	s_barrier
	s_add_i32 s29, 0, 0x14000
	s_add_i32 s28, s28, s34
	s_add_u32 s78, s10, s6
	s_addc_u32 s79, s11, s7
	s_mov_b32 m0, s28
	ds_read_b128 v[212:215], v248 offset:16384
	ds_read_b128 v[216:219], v248 offset:17408
	ds_read_b128 v[220:223], v248 offset:18432
	ds_read_b128 v[224:227], v248 offset:19456
	global_load_lds_dwordx4 v132, s[10:11]
	s_add_i32 m0, s28, 0x2000
	s_nop 0
	global_load_lds_dwordx4 v136, s[10:11]
	s_barrier
	s_waitcnt lgkmcnt(0)
	v_mfma_f32_16x16x32_bf16 v[118:121], v[212:215], v[158:161], v[118:121]
	v_mfma_f32_16x16x32_bf16 v[114:117], v[220:223], v[158:161], v[114:117]
	v_mfma_f32_16x16x32_bf16 v[102:105], v[212:215], v[166:169], v[102:105]
	v_mfma_f32_16x16x32_bf16 v[98:101], v[220:223], v[166:169], v[98:101]
	v_mfma_f32_16x16x32_bf16 v[86:89], v[212:215], v[178:181], v[86:89]
	v_mfma_f32_16x16x32_bf16 v[82:85], v[220:223], v[178:181], v[82:85]
	v_mfma_f32_16x16x32_bf16 v[70:73], v[212:215], v[204:207], v[70:73]
	v_mfma_f32_16x16x32_bf16 v[66:69], v[220:223], v[204:207], v[66:69]
	v_mfma_f32_16x16x32_bf16 v[118:121], v[216:219], v[162:165], v[118:121]
	v_mfma_f32_16x16x32_bf16 v[114:117], v[224:227], v[162:165], v[114:117]
	v_mfma_f32_16x16x32_bf16 v[102:105], v[216:219], v[174:177], v[102:105]
	v_mfma_f32_16x16x32_bf16 v[98:101], v[224:227], v[174:177], v[98:101]
	v_mfma_f32_16x16x32_bf16 v[86:89], v[216:219], v[182:185], v[86:89]
	v_mfma_f32_16x16x32_bf16 v[82:85], v[224:227], v[182:185], v[82:85]
	v_mfma_f32_16x16x32_bf16 v[70:73], v[216:219], v[208:211], v[70:73]
	v_mfma_f32_16x16x32_bf16 v[66:69], v[224:227], v[208:211], v[66:69]
	s_barrier
	s_mov_b32 m0, s35
	s_add_u32 s80, s4, s6
	s_addc_u32 s81, s5, s7
	ds_read_b128 v[158:161], v172 offset:16384
	ds_read_b128 v[162:165], v172 offset:17408
	ds_read_b128 v[166:169], v172 offset:18432
	ds_read_b128 v[174:177], v172 offset:19456
	ds_read_b128 v[178:181], v172 offset:20480
	ds_read_b128 v[182:185], v172 offset:21504
	ds_read_b128 v[204:207], v172 offset:22528
	ds_read_b128 v[208:211], v172 offset:23552
	global_load_lds_dwordx4 v130, s[4:5]
	s_mov_b32 m0, s40
	s_nop 0
	global_load_lds_dwordx4 v134, s[4:5]
	s_barrier
	s_waitcnt lgkmcnt(0)
	v_mfma_f32_16x16x32_bf16 v[62:65], v[142:145], v[158:161], v[62:65]
	v_mfma_f32_16x16x32_bf16 v[58:61], v[150:153], v[158:161], v[58:61]
	v_mfma_f32_16x16x32_bf16 v[46:49], v[142:145], v[166:169], v[46:49]
	v_mfma_f32_16x16x32_bf16 v[42:45], v[150:153], v[166:169], v[42:45]
	v_mfma_f32_16x16x32_bf16 v[30:33], v[142:145], v[178:181], v[30:33]
	v_mfma_f32_16x16x32_bf16 v[26:29], v[150:153], v[178:181], v[26:29]
	v_mfma_f32_16x16x32_bf16 v[14:17], v[142:145], v[204:207], v[14:17]
	v_mfma_f32_16x16x32_bf16 v[10:13], v[150:153], v[204:207], v[10:13]
	v_mfma_f32_16x16x32_bf16 v[62:65], v[146:149], v[162:165], v[62:65]
	v_mfma_f32_16x16x32_bf16 v[58:61], v[154:157], v[162:165], v[58:61]
	v_mfma_f32_16x16x32_bf16 v[46:49], v[146:149], v[174:177], v[46:49]
	v_mfma_f32_16x16x32_bf16 v[42:45], v[154:157], v[174:177], v[42:45]
	v_mfma_f32_16x16x32_bf16 v[30:33], v[146:149], v[182:185], v[30:33]
	v_mfma_f32_16x16x32_bf16 v[26:29], v[154:157], v[182:185], v[26:29]
	v_mfma_f32_16x16x32_bf16 v[14:17], v[146:149], v[208:211], v[14:17]
	v_mfma_f32_16x16x32_bf16 v[10:13], v[154:157], v[208:211], v[10:13]
	s_barrier
	s_add_u32 s10, s10, s92
	s_addc_u32 s11, s11, 0
	s_add_i32 s28, s29, s34
	s_add_u32 s58, s10, s6
	s_addc_u32 s59, s11, s7
	s_mov_b32 m0, s28
	s_nop 0
	global_load_lds_dwordx4 v132, s[10:11]
	s_add_i32 m0, s28, 0x2000
	s_nop 0
	global_load_lds_dwordx4 v136, s[10:11]
	s_waitcnt vmcnt(6)
	s_barrier
	v_mfma_f32_16x16x32_bf16 v[54:57], v[212:215], v[158:161], v[54:57]
	v_mfma_f32_16x16x32_bf16 v[50:53], v[220:223], v[158:161], v[50:53]
	v_mfma_f32_16x16x32_bf16 v[38:41], v[212:215], v[166:169], v[38:41]
	v_mfma_f32_16x16x32_bf16 v[34:37], v[220:223], v[166:169], v[34:37]
	v_mfma_f32_16x16x32_bf16 v[22:25], v[212:215], v[178:181], v[22:25]
	v_mfma_f32_16x16x32_bf16 v[18:21], v[220:223], v[178:181], v[18:21]
	v_mfma_f32_16x16x32_bf16 v[6:9], v[212:215], v[204:207], v[6:9]
	v_mfma_f32_16x16x32_bf16 v[2:5], v[220:223], v[204:207], v[2:5]
	v_mfma_f32_16x16x32_bf16 v[54:57], v[216:219], v[162:165], v[54:57]
	v_mfma_f32_16x16x32_bf16 v[50:53], v[224:227], v[162:165], v[50:53]
	v_mfma_f32_16x16x32_bf16 v[38:41], v[216:219], v[174:177], v[38:41]
	v_mfma_f32_16x16x32_bf16 v[34:37], v[224:227], v[174:177], v[34:37]
	v_mfma_f32_16x16x32_bf16 v[22:25], v[216:219], v[182:185], v[22:25]
	v_mfma_f32_16x16x32_bf16 v[18:21], v[224:227], v[182:185], v[18:21]
	v_mfma_f32_16x16x32_bf16 v[6:9], v[216:219], v[208:211], v[6:9]
	v_mfma_f32_16x16x32_bf16 v[2:5], v[224:227], v[208:211], v[2:5]
	s_barrier
	s_add_i32 s10, 0, 0x18000
	ds_read_b128 v[142:145], v248 offset:32768
	ds_read_b128 v[146:149], v248 offset:33792
	ds_read_b128 v[150:153], v248 offset:34816
	ds_read_b128 v[154:157], v248 offset:35840
	s_add_u32 s4, s4, s92
	s_addc_u32 s5, s5, 0
	s_mov_b32 m0, s41
	ds_read_b128 v[158:161], v172 offset:32768
	ds_read_b128 v[162:165], v172 offset:33792
	ds_read_b128 v[166:169], v172 offset:34816
	ds_read_b128 v[174:177], v172 offset:35840
	ds_read_b128 v[178:181], v172 offset:36864
	ds_read_b128 v[182:185], v172 offset:37888
	ds_read_b128 v[204:207], v172 offset:38912
	ds_read_b128 v[208:211], v172 offset:39936
	global_load_lds_dwordx4 v130, s[4:5]
	s_mov_b32 m0, s42
	s_nop 0
	global_load_lds_dwordx4 v134, s[4:5]
	s_waitcnt lgkmcnt(8)
	s_barrier
	s_waitcnt lgkmcnt(0)
	v_mfma_f32_16x16x32_bf16 v[126:129], v[142:145], v[158:161], v[126:129]
	v_mfma_f32_16x16x32_bf16 v[122:125], v[150:153], v[158:161], v[122:125]
	v_mfma_f32_16x16x32_bf16 v[110:113], v[142:145], v[166:169], v[110:113]
	v_mfma_f32_16x16x32_bf16 v[106:109], v[150:153], v[166:169], v[106:109]
	v_mfma_f32_16x16x32_bf16 v[94:97], v[142:145], v[178:181], v[94:97]
	v_mfma_f32_16x16x32_bf16 v[90:93], v[150:153], v[178:181], v[90:93]
	v_mfma_f32_16x16x32_bf16 v[78:81], v[142:145], v[204:207], v[78:81]
	v_mfma_f32_16x16x32_bf16 v[74:77], v[150:153], v[204:207], v[74:77]
	v_mfma_f32_16x16x32_bf16 v[126:129], v[146:149], v[162:165], v[126:129]
	v_mfma_f32_16x16x32_bf16 v[122:125], v[154:157], v[162:165], v[122:125]
	v_mfma_f32_16x16x32_bf16 v[110:113], v[146:149], v[174:177], v[110:113]
	v_mfma_f32_16x16x32_bf16 v[106:109], v[154:157], v[174:177], v[106:109]
	v_mfma_f32_16x16x32_bf16 v[94:97], v[146:149], v[182:185], v[94:97]
	v_mfma_f32_16x16x32_bf16 v[90:93], v[154:157], v[182:185], v[90:93]
	v_mfma_f32_16x16x32_bf16 v[78:81], v[146:149], v[208:211], v[78:81]
	v_mfma_f32_16x16x32_bf16 v[74:77], v[154:157], v[208:211], v[74:77]
	s_barrier
	s_add_i32 s4, 0, 0x1c000
	s_add_i32 s5, s10, s34
	s_mov_b32 m0, s5
	ds_read_b128 v[212:215], v248 offset:49152
	ds_read_b128 v[216:219], v248 offset:50176
	ds_read_b128 v[220:223], v248 offset:51200
	ds_read_b128 v[224:227], v248 offset:52224
	global_load_lds_dwordx4 v132, s[78:79]
	s_add_i32 m0, s5, 0x2000
	s_nop 0
	global_load_lds_dwordx4 v136, s[78:79]
	s_barrier
	s_waitcnt lgkmcnt(0)
	v_mfma_f32_16x16x32_bf16 v[118:121], v[212:215], v[158:161], v[118:121]
	v_mfma_f32_16x16x32_bf16 v[114:117], v[220:223], v[158:161], v[114:117]
	v_mfma_f32_16x16x32_bf16 v[102:105], v[212:215], v[166:169], v[102:105]
	v_mfma_f32_16x16x32_bf16 v[98:101], v[220:223], v[166:169], v[98:101]
	v_mfma_f32_16x16x32_bf16 v[86:89], v[212:215], v[178:181], v[86:89]
	v_mfma_f32_16x16x32_bf16 v[82:85], v[220:223], v[178:181], v[82:85]
	v_mfma_f32_16x16x32_bf16 v[70:73], v[212:215], v[204:207], v[70:73]
	v_mfma_f32_16x16x32_bf16 v[66:69], v[220:223], v[204:207], v[66:69]
	v_mfma_f32_16x16x32_bf16 v[118:121], v[216:219], v[162:165], v[118:121]
	v_mfma_f32_16x16x32_bf16 v[114:117], v[224:227], v[162:165], v[114:117]
	v_mfma_f32_16x16x32_bf16 v[102:105], v[216:219], v[174:177], v[102:105]
	v_mfma_f32_16x16x32_bf16 v[98:101], v[224:227], v[174:177], v[98:101]
	v_mfma_f32_16x16x32_bf16 v[86:89], v[216:219], v[182:185], v[86:89]
	v_mfma_f32_16x16x32_bf16 v[82:85], v[224:227], v[182:185], v[82:85]
	v_mfma_f32_16x16x32_bf16 v[70:73], v[216:219], v[208:211], v[70:73]
	v_mfma_f32_16x16x32_bf16 v[66:69], v[224:227], v[208:211], v[66:69]
	s_barrier
	s_mov_b32 m0, s46
	ds_read_b128 v[158:161], v172 offset:49152
	ds_read_b128 v[162:165], v172 offset:50176
	ds_read_b128 v[166:169], v172 offset:51200
	ds_read_b128 v[174:177], v172 offset:52224
	ds_read_b128 v[178:181], v172 offset:53248
	ds_read_b128 v[182:185], v172 offset:54272
	ds_read_b128 v[204:207], v172 offset:55296
	ds_read_b128 v[208:211], v172 offset:56320
	global_load_lds_dwordx4 v130, s[80:81]
	s_mov_b32 m0, s47
	s_nop 0
	global_load_lds_dwordx4 v134, s[80:81]
	s_barrier
	s_waitcnt lgkmcnt(0)
	v_mfma_f32_16x16x32_bf16 v[62:65], v[142:145], v[158:161], v[62:65]
	v_mfma_f32_16x16x32_bf16 v[58:61], v[150:153], v[158:161], v[58:61]
	v_mfma_f32_16x16x32_bf16 v[46:49], v[142:145], v[166:169], v[46:49]
	v_mfma_f32_16x16x32_bf16 v[42:45], v[150:153], v[166:169], v[42:45]
	v_mfma_f32_16x16x32_bf16 v[30:33], v[142:145], v[178:181], v[30:33]
	v_mfma_f32_16x16x32_bf16 v[26:29], v[150:153], v[178:181], v[26:29]
	v_mfma_f32_16x16x32_bf16 v[14:17], v[142:145], v[204:207], v[14:17]
	v_mfma_f32_16x16x32_bf16 v[10:13], v[150:153], v[204:207], v[10:13]
	v_mfma_f32_16x16x32_bf16 v[62:65], v[146:149], v[162:165], v[62:65]
	v_mfma_f32_16x16x32_bf16 v[58:61], v[154:157], v[162:165], v[58:61]
	v_mfma_f32_16x16x32_bf16 v[46:49], v[146:149], v[174:177], v[46:49]
	v_mfma_f32_16x16x32_bf16 v[42:45], v[154:157], v[174:177], v[42:45]
	v_mfma_f32_16x16x32_bf16 v[30:33], v[146:149], v[182:185], v[30:33]
	v_mfma_f32_16x16x32_bf16 v[26:29], v[154:157], v[182:185], v[26:29]
	v_mfma_f32_16x16x32_bf16 v[14:17], v[146:149], v[208:211], v[14:17]
	v_mfma_f32_16x16x32_bf16 v[10:13], v[154:157], v[208:211], v[10:13]
	s_barrier
	s_add_i32 s4, s4, s34
	s_mov_b32 m0, s4
	s_nop 0
	global_load_lds_dwordx4 v132, s[58:59]
	s_add_i32 m0, s4, 0x2000
	s_nop 0
	global_load_lds_dwordx4 v136, s[58:59]
	s_add_u32 s0, s0, 0x100
	s_addc_u32 s1, s1, 0
	s_add_u32 s12, s12, 0x100
	s_addc_u32 s13, s13, 0
	s_cmp_ge_u32 s27, s43
	s_mov_b32 s4, s27
	s_waitcnt vmcnt(6)
	s_barrier
	v_mfma_f32_16x16x32_bf16 v[54:57], v[212:215], v[158:161], v[54:57]
	v_mfma_f32_16x16x32_bf16 v[50:53], v[220:223], v[158:161], v[50:53]
	v_mfma_f32_16x16x32_bf16 v[38:41], v[212:215], v[166:169], v[38:41]
	v_mfma_f32_16x16x32_bf16 v[34:37], v[220:223], v[166:169], v[34:37]
	v_mfma_f32_16x16x32_bf16 v[22:25], v[212:215], v[178:181], v[22:25]
	v_mfma_f32_16x16x32_bf16 v[18:21], v[220:223], v[178:181], v[18:21]
	v_mfma_f32_16x16x32_bf16 v[6:9], v[212:215], v[204:207], v[6:9]
	v_mfma_f32_16x16x32_bf16 v[2:5], v[220:223], v[204:207], v[2:5]
	v_mfma_f32_16x16x32_bf16 v[54:57], v[216:219], v[162:165], v[54:57]
	v_mfma_f32_16x16x32_bf16 v[50:53], v[224:227], v[162:165], v[50:53]
	v_mfma_f32_16x16x32_bf16 v[38:41], v[216:219], v[174:177], v[38:41]
	v_mfma_f32_16x16x32_bf16 v[34:37], v[224:227], v[174:177], v[34:37]
	v_mfma_f32_16x16x32_bf16 v[22:25], v[216:219], v[182:185], v[22:25]
	v_mfma_f32_16x16x32_bf16 v[18:21], v[224:227], v[182:185], v[18:21]
	v_mfma_f32_16x16x32_bf16 v[6:9], v[216:219], v[208:211], v[6:9]
	v_mfma_f32_16x16x32_bf16 v[2:5], v[224:227], v[208:211], v[2:5]
	s_barrier
	s_cbranch_scc0 .LBB0_806

	.amdhsa_kernel _Z8yoco_fwd6Params
		.amdhsa_group_segment_fixed_size 0
		.amdhsa_private_segment_fixed_size 0
		.amdhsa_kernarg_size 1336
		.amdhsa_user_sgpr_count 2
		.amdhsa_user_sgpr_dispatch_ptr 0
		.amdhsa_user_sgpr_queue_ptr 0
		.amdhsa_user_sgpr_kernarg_segment_ptr 1
		.amdhsa_user_sgpr_dispatch_id 0
		.amdhsa_user_sgpr_kernarg_preload_length 0
		.amdhsa_user_sgpr_kernarg_preload_offset 0
		.amdhsa_user_sgpr_private_segment_size 0
		.amdhsa_uses_dynamic_stack 0
		.amdhsa_enable_private_segment 0
		.amdhsa_system_sgpr_workgroup_id_x 1
		.amdhsa_system_sgpr_workgroup_id_y 0
		.amdhsa_system_sgpr_workgroup_id_z 0
		.amdhsa_system_sgpr_workgroup_info 0
		.amdhsa_system_vgpr_workitem_id 2
		.amdhsa_next_free_vgpr 256
		.amdhsa_next_free_sgpr 100
		.amdhsa_accum_offset 256
		.amdhsa_reserve_vcc 1
		.amdhsa_float_round_mode_32 0
		.amdhsa_float_round_mode_16_64 0
		.amdhsa_float_denorm_mode_32 3
		.amdhsa_float_denorm_mode_16_64 3
		.amdhsa_dx10_clamp 1
		.amdhsa_ieee_mode 1
		.amdhsa_fp16_overflow 0
		.amdhsa_tg_split 0
		.amdhsa_exception_fp_ieee_invalid_op 0
		.amdhsa_exception_fp_denorm_src 0
		.amdhsa_exception_fp_ieee_div_zero 0
		.amdhsa_exception_fp_ieee_overflow 0
		.amdhsa_exception_fp_ieee_underflow 0
		.amdhsa_exception_fp_ieee_inexact 0
		.amdhsa_exception_int_div_zero 0
	.end_amdhsa_kernel

amdhsa.kernels:
  - .agpr_count:     0
    .args:
      - .offset:         0
        .size:           1080
        .value_kind:     by_value
      - .offset:         1080
        .size:           4
        .value_kind:     hidden_block_count_x
      - .offset:         1084
        .size:           4
        .value_kind:     hidden_block_count_y
      - .offset:         1088
        .size:           4
        .value_kind:     hidden_block_count_z
      - .offset:         1092
        .size:           2
        .value_kind:     hidden_group_size_x
      - .offset:         1094
        .size:           2
        .value_kind:     hidden_group_size_y
      - .offset:         1096
        .size:           2
        .value_kind:     hidden_group_size_z
      - .offset:         1098
        .size:           2
        .value_kind:     hidden_remainder_x
      - .offset:         1100
        .size:           2
        .value_kind:     hidden_remainder_y
      - .offset:         1102
        .size:           2
        .value_kind:     hidden_remainder_z
      - .offset:         1120
        .size:           8
        .value_kind:     hidden_global_offset_x
      - .offset:         1128
        .size:           8
        .value_kind:     hidden_global_offset_y
      - .offset:         1136
        .size:           8
        .value_kind:     hidden_global_offset_z
      - .offset:         1144
        .size:           2
        .value_kind:     hidden_grid_dims
      - .offset:         1168
        .size:           8
        .value_kind:     hidden_multigrid_sync_arg
      - .offset:         1200
        .size:           4
        .value_kind:     hidden_dynamic_lds_size
    .group_segment_fixed_size: 0
    .kernarg_segment_align: 8
    .kernarg_segment_size: 1336
    .language:       OpenCL C
    .language_version:
      - 2
      - 0
    .max_flat_workgroup_size: 512
    .name:           _Z8yoco_fwd6Params
    .private_segment_fixed_size: 0
    .sgpr_count:     106
    .sgpr_spill_count: 229
    .symbol:         _Z8yoco_fwd6Params.kd
    .uniform_work_group_size: 1
    .uses_dynamic_stack: false
    .vgpr_count:     256
    .vgpr_spill_count: 0
    .wavefront_size: 64
